# strategy 9 (sec 7.11): K-loop counter/pointer/exit-test block moved in front of the loop-back barrier in all five GEMM loops (on v56)
# baseline (speedup 1.0000x reference)
.LBB0_164:
	s_add_u32 s50, s16, 0x100
	s_addc_u32 s51, s17, 0
	s_mov_b32 s86, -2
	s_add_u32 s16, s14, 0x100
	s_addc_u32 s17, s15, 0
	s_add_i32 s22, 0, 0x10000
	s_cmp_eq_u32 s86, 8
	s_cselect_b32 s39, s11, s17
	s_cselect_b32 s38, s10, s16
	v_add_u32_e32 v142, s22, v145
	s_cselect_b32 s19, s13, s51
	s_cselect_b32 s18, s12, s50
	s_add_i32 s23, 0, 0x14000
	ds_read_b128 v[138:141], v142
	ds_read_b128 v[148:151], v142 offset:1024
	ds_read_b128 v[152:155], v142 offset:2048
	ds_read_b128 v[156:159], v142 offset:3072
	v_add_u32_e32 v142, s23, v145
	ds_read_b128 v[170:173], v142
	ds_read_b128 v[174:177], v142 offset:1024
	ds_read_b128 v[178:181], v142 offset:2048
	ds_read_b128 v[182:185], v142 offset:3072
	v_lshl_add_u64 v[142:143], s[14:15], 0, v[134:135]
	s_add_i32 m0, s41, 0xc000
	ds_read_b128 v[186:189], v147
	ds_read_b128 v[190:193], v147 offset:1024
	ds_read_b128 v[194:197], v147 offset:2048
	ds_read_b128 v[198:201], v147 offset:3072
	ds_read_b128 v[202:205], v147 offset:4096
	ds_read_b128 v[206:209], v147 offset:5120
	ds_read_b128 v[210:213], v147 offset:6144
	ds_read_b128 v[222:225], v147 offset:7168
	global_load_lds_dwordx4 v[142:143], off
	v_lshl_add_u64 v[142:143], s[14:15], 0, v[136:137]
	s_add_i32 m0, s41, 0xe000
	s_nop 0
	global_load_lds_dwordx4 v[142:143], off
	s_waitcnt vmcnt(8)
	s_waitcnt lgkmcnt(0)
	s_barrier
	s_setprio 1
	s_waitcnt lgkmcnt(0)
	v_mfma_f32_16x16x32_bf16 v[124:127], v[138:141], v[186:189], 0
	v_mfma_f32_16x16x32_bf16 v[120:123], v[152:155], v[186:189], 0
	v_mfma_f32_16x16x32_bf16 v[108:111], v[138:141], v[194:197], 0
	v_mfma_f32_16x16x32_bf16 v[104:107], v[152:155], v[194:197], 0
	v_mfma_f32_16x16x32_bf16 v[92:95], v[138:141], v[202:205], 0
	v_mfma_f32_16x16x32_bf16 v[88:91], v[152:155], v[202:205], 0
	v_mfma_f32_16x16x32_bf16 v[76:79], v[138:141], v[210:213], 0
	v_mfma_f32_16x16x32_bf16 v[72:75], v[152:155], v[210:213], 0
	v_mfma_f32_16x16x32_bf16 v[124:127], v[148:151], v[190:193], v[124:127]
	v_mfma_f32_16x16x32_bf16 v[120:123], v[156:159], v[190:193], v[120:123]
	v_mfma_f32_16x16x32_bf16 v[108:111], v[148:151], v[198:201], v[108:111]
	v_mfma_f32_16x16x32_bf16 v[104:107], v[156:159], v[198:201], v[104:107]
	v_mfma_f32_16x16x32_bf16 v[92:95], v[148:151], v[206:209], v[92:95]
	v_mfma_f32_16x16x32_bf16 v[88:91], v[156:159], v[206:209], v[88:91]
	v_mfma_f32_16x16x32_bf16 v[76:79], v[148:151], v[222:225], v[76:79]
	v_mfma_f32_16x16x32_bf16 v[72:75], v[156:159], v[222:225], v[72:75]
	v_mfma_f32_16x16x32_bf16 v[116:119], v[170:173], v[186:189], 0
	v_mfma_f32_16x16x32_bf16 v[112:115], v[178:181], v[186:189], 0
	v_mfma_f32_16x16x32_bf16 v[100:103], v[170:173], v[194:197], 0
	v_mfma_f32_16x16x32_bf16 v[96:99], v[178:181], v[194:197], 0
	v_mfma_f32_16x16x32_bf16 v[84:87], v[170:173], v[202:205], 0
	v_mfma_f32_16x16x32_bf16 v[80:83], v[178:181], v[202:205], 0
	v_mfma_f32_16x16x32_bf16 v[68:71], v[170:173], v[210:213], 0
	v_mfma_f32_16x16x32_bf16 v[64:67], v[178:181], v[210:213], 0
	v_mfma_f32_16x16x32_bf16 v[116:119], v[174:177], v[190:193], v[116:119]
	v_mfma_f32_16x16x32_bf16 v[112:115], v[182:185], v[190:193], v[112:115]
	v_mfma_f32_16x16x32_bf16 v[100:103], v[174:177], v[198:201], v[100:103]
	v_mfma_f32_16x16x32_bf16 v[96:99], v[182:185], v[198:201], v[96:99]
	v_mfma_f32_16x16x32_bf16 v[84:87], v[174:177], v[206:209], v[84:87]
	v_mfma_f32_16x16x32_bf16 v[80:83], v[182:185], v[206:209], v[80:83]
	v_mfma_f32_16x16x32_bf16 v[68:71], v[174:177], v[222:225], v[68:71]
	v_mfma_f32_16x16x32_bf16 v[64:67], v[182:185], v[222:225], v[64:67]
	s_setprio 0
	s_barrier
	s_add_i32 s14, s22, s27
	v_lshl_add_u64 v[142:143], s[18:19], 0, v[160:161]
	s_mov_b32 m0, s14
	ds_read_b128 v[186:189], v147 offset:16384
	ds_read_b128 v[190:193], v147 offset:17408
	ds_read_b128 v[194:197], v147 offset:18432
	ds_read_b128 v[198:201], v147 offset:19456
	ds_read_b128 v[202:205], v147 offset:20480
	ds_read_b128 v[206:209], v147 offset:21504
	ds_read_b128 v[210:213], v147 offset:22528
	ds_read_b128 v[222:225], v147 offset:23552
	global_load_lds_dwordx4 v[142:143], off
	s_add_i32 m0, s14, 0x2000
	s_add_u32 s14, s18, 0x30000
	v_lshl_add_u64 v[162:163], s[18:19], 0, v[128:129]
	s_addc_u32 s15, s19, 0
	s_add_i32 s22, s23, s27
	global_load_lds_dwordx4 v[162:163], off
	v_lshl_add_u64 v[164:165], s[14:15], 0, v[160:161]
	s_mov_b32 m0, s22
	v_lshl_add_u64 v[214:215], s[38:39], 0, v[130:131]
	global_load_lds_dwordx4 v[164:165], off
	v_lshl_add_u64 v[164:165], s[14:15], 0, v[128:129]
	s_add_i32 m0, s22, 0x2000
	s_nop 0
	global_load_lds_dwordx4 v[164:165], off
	v_lshl_add_u64 v[164:165], s[38:39], 0, v[132:133]
	s_mov_b32 m0, s41
	s_nop 0
	global_load_lds_dwordx4 v[164:165], off
	s_mov_b32 m0, s42
	s_nop 0
	global_load_lds_dwordx4 v[214:215], off
	s_waitcnt vmcnt(8)
	s_waitcnt lgkmcnt(0)
	s_barrier
	s_setprio 1
	s_waitcnt lgkmcnt(0)
	v_mfma_f32_16x16x32_bf16 v[60:63], v[138:141], v[186:189], 0
	v_mfma_f32_16x16x32_bf16 v[56:59], v[152:155], v[186:189], 0
	v_mfma_f32_16x16x32_bf16 v[44:47], v[138:141], v[194:197], 0
	v_mfma_f32_16x16x32_bf16 v[40:43], v[152:155], v[194:197], 0
	v_mfma_f32_16x16x32_bf16 v[28:31], v[138:141], v[202:205], 0
	v_mfma_f32_16x16x32_bf16 v[24:27], v[152:155], v[202:205], 0
	v_mfma_f32_16x16x32_bf16 v[12:15], v[138:141], v[210:213], 0
	v_mfma_f32_16x16x32_bf16 v[8:11], v[152:155], v[210:213], 0
	v_mfma_f32_16x16x32_bf16 v[60:63], v[148:151], v[190:193], v[60:63]
	v_mfma_f32_16x16x32_bf16 v[56:59], v[156:159], v[190:193], v[56:59]
	v_mfma_f32_16x16x32_bf16 v[44:47], v[148:151], v[198:201], v[44:47]
	v_mfma_f32_16x16x32_bf16 v[40:43], v[156:159], v[198:201], v[40:43]
	v_mfma_f32_16x16x32_bf16 v[28:31], v[148:151], v[206:209], v[28:31]
	v_mfma_f32_16x16x32_bf16 v[24:27], v[156:159], v[206:209], v[24:27]
	v_mfma_f32_16x16x32_bf16 v[12:15], v[148:151], v[222:225], v[12:15]
	v_mfma_f32_16x16x32_bf16 v[8:11], v[156:159], v[222:225], v[8:11]
	v_mfma_f32_16x16x32_bf16 v[52:55], v[170:173], v[186:189], 0
	v_mfma_f32_16x16x32_bf16 v[48:51], v[178:181], v[186:189], 0
	v_mfma_f32_16x16x32_bf16 v[36:39], v[170:173], v[194:197], 0
	v_mfma_f32_16x16x32_bf16 v[32:35], v[178:181], v[194:197], 0
	v_mfma_f32_16x16x32_bf16 v[20:23], v[170:173], v[202:205], 0
	v_mfma_f32_16x16x32_bf16 v[16:19], v[178:181], v[202:205], 0
	v_mfma_f32_16x16x32_bf16 v[4:7], v[170:173], v[210:213], 0
	v_mfma_f32_16x16x32_bf16 v[0:3], v[178:181], v[210:213], 0
	v_mfma_f32_16x16x32_bf16 v[52:55], v[174:177], v[190:193], v[52:55]
	v_mfma_f32_16x16x32_bf16 v[48:51], v[182:185], v[190:193], v[48:51]
	v_mfma_f32_16x16x32_bf16 v[36:39], v[174:177], v[198:201], v[36:39]
	v_mfma_f32_16x16x32_bf16 v[32:35], v[182:185], v[198:201], v[32:35]
	v_mfma_f32_16x16x32_bf16 v[20:23], v[174:177], v[206:209], v[20:23]
	v_mfma_f32_16x16x32_bf16 v[16:19], v[182:185], v[206:209], v[16:19]
	v_mfma_f32_16x16x32_bf16 v[4:7], v[174:177], v[222:225], v[4:7]
	v_mfma_f32_16x16x32_bf16 v[0:3], v[182:185], v[222:225], v[0:3]
	s_setprio 0
	s_barrier
	s_add_i32 s22, 0, 0x18000
	s_add_i32 s23, 0, 0x1c000
	v_add_u32_e32 v156, s22, v145
	v_add_u32_e32 v167, s23, v145
	ds_read_b128 v[138:141], v156
	ds_read_b128 v[148:151], v156 offset:1024
	ds_read_b128 v[152:155], v156 offset:2048
	ds_read_b128 v[156:159], v156 offset:3072
	ds_read_b128 v[170:173], v167
	ds_read_b128 v[174:177], v167 offset:1024
	ds_read_b128 v[178:181], v167 offset:2048
	ds_read_b128 v[182:185], v167 offset:3072
	s_add_u32 s14, s38, 0x30000
	s_addc_u32 s15, s39, 0
	s_mov_b32 m0, s43
	v_lshl_add_u64 v[226:227], s[14:15], 0, v[132:133]
	ds_read_b128 v[186:189], v147 offset:32768
	ds_read_b128 v[190:193], v147 offset:33792
	ds_read_b128 v[194:197], v147 offset:34816
	ds_read_b128 v[198:201], v147 offset:35840
	ds_read_b128 v[202:205], v147 offset:36864
	ds_read_b128 v[206:209], v147 offset:37888
	ds_read_b128 v[210:213], v147 offset:38912
	ds_read_b128 v[222:225], v147 offset:39936
	global_load_lds_dwordx4 v[226:227], off
	v_lshl_add_u64 v[226:227], s[14:15], 0, v[130:131]
	s_mov_b32 m0, s80
	s_nop 0
	global_load_lds_dwordx4 v[226:227], off
	s_waitcnt vmcnt(8)
	s_waitcnt lgkmcnt(0)
	s_barrier
	s_setprio 1
	s_waitcnt lgkmcnt(0)
	v_mfma_f32_16x16x32_bf16 v[124:127], v[138:141], v[186:189], v[124:127]
	v_mfma_f32_16x16x32_bf16 v[120:123], v[152:155], v[186:189], v[120:123]
	v_mfma_f32_16x16x32_bf16 v[108:111], v[138:141], v[194:197], v[108:111]
	v_mfma_f32_16x16x32_bf16 v[104:107], v[152:155], v[194:197], v[104:107]
	v_mfma_f32_16x16x32_bf16 v[92:95], v[138:141], v[202:205], v[92:95]
	v_mfma_f32_16x16x32_bf16 v[88:91], v[152:155], v[202:205], v[88:91]
	v_mfma_f32_16x16x32_bf16 v[76:79], v[138:141], v[210:213], v[76:79]
	v_mfma_f32_16x16x32_bf16 v[72:75], v[152:155], v[210:213], v[72:75]
	v_mfma_f32_16x16x32_bf16 v[124:127], v[148:151], v[190:193], v[124:127]
	v_mfma_f32_16x16x32_bf16 v[120:123], v[156:159], v[190:193], v[120:123]
	v_mfma_f32_16x16x32_bf16 v[108:111], v[148:151], v[198:201], v[108:111]
	v_mfma_f32_16x16x32_bf16 v[104:107], v[156:159], v[198:201], v[104:107]
	v_mfma_f32_16x16x32_bf16 v[92:95], v[148:151], v[206:209], v[92:95]
	v_mfma_f32_16x16x32_bf16 v[88:91], v[156:159], v[206:209], v[88:91]
	v_mfma_f32_16x16x32_bf16 v[76:79], v[148:151], v[222:225], v[76:79]
	v_mfma_f32_16x16x32_bf16 v[72:75], v[156:159], v[222:225], v[72:75]
	v_mfma_f32_16x16x32_bf16 v[116:119], v[170:173], v[186:189], v[116:119]
	v_mfma_f32_16x16x32_bf16 v[112:115], v[178:181], v[186:189], v[112:115]
	v_mfma_f32_16x16x32_bf16 v[100:103], v[170:173], v[194:197], v[100:103]
	v_mfma_f32_16x16x32_bf16 v[96:99], v[178:181], v[194:197], v[96:99]
	v_mfma_f32_16x16x32_bf16 v[84:87], v[170:173], v[202:205], v[84:87]
	v_mfma_f32_16x16x32_bf16 v[80:83], v[178:181], v[202:205], v[80:83]
	v_mfma_f32_16x16x32_bf16 v[68:71], v[170:173], v[210:213], v[68:71]
	v_mfma_f32_16x16x32_bf16 v[64:67], v[178:181], v[210:213], v[64:67]
	v_mfma_f32_16x16x32_bf16 v[116:119], v[174:177], v[190:193], v[116:119]
	v_mfma_f32_16x16x32_bf16 v[112:115], v[182:185], v[190:193], v[112:115]
	v_mfma_f32_16x16x32_bf16 v[100:103], v[174:177], v[198:201], v[100:103]
	v_mfma_f32_16x16x32_bf16 v[96:99], v[182:185], v[198:201], v[96:99]
	v_mfma_f32_16x16x32_bf16 v[84:87], v[174:177], v[206:209], v[84:87]
	v_mfma_f32_16x16x32_bf16 v[80:83], v[182:185], v[206:209], v[80:83]
	v_mfma_f32_16x16x32_bf16 v[68:71], v[174:177], v[222:225], v[68:71]
	v_mfma_f32_16x16x32_bf16 v[64:67], v[182:185], v[222:225], v[64:67]
	s_setprio 0
	s_barrier
	s_add_i32 s14, s22, s27
	v_lshl_add_u64 v[142:143], v[142:143], 0, s[48:49]
	s_mov_b32 m0, s14
	ds_read_b128 v[186:189], v147 offset:49152
	ds_read_b128 v[190:193], v147 offset:50176
	ds_read_b128 v[194:197], v147 offset:51200
	ds_read_b128 v[198:201], v147 offset:52224
	ds_read_b128 v[202:205], v147 offset:53248
	ds_read_b128 v[206:209], v147 offset:54272
	ds_read_b128 v[210:213], v147 offset:55296
	ds_read_b128 v[222:225], v147 offset:56320
	global_load_lds_dwordx4 v[142:143], off
	s_add_i32 m0, s14, 0x2000
	s_add_u32 s14, s18, 0x30080
	v_lshl_add_u64 v[142:143], v[162:163], 0, s[48:49]
	s_addc_u32 s15, s19, 0
	s_add_i32 s18, s23, s27
	global_load_lds_dwordx4 v[142:143], off
	v_lshl_add_u64 v[142:143], s[14:15], 0, v[160:161]
	s_mov_b32 m0, s18
	s_nop 0
	global_load_lds_dwordx4 v[142:143], off
	v_lshl_add_u64 v[142:143], s[14:15], 0, v[128:129]
	s_add_i32 m0, s18, 0x2000
	s_nop 0
	global_load_lds_dwordx4 v[142:143], off
	v_lshl_add_u64 v[142:143], v[164:165], 0, s[48:49]
	s_mov_b32 m0, s81
	s_nop 0
	global_load_lds_dwordx4 v[142:143], off
	v_lshl_add_u64 v[142:143], v[214:215], 0, s[48:49]
	s_mov_b32 m0, s82
	s_nop 0
	global_load_lds_dwordx4 v[142:143], off
	s_waitcnt vmcnt(8)
	s_waitcnt lgkmcnt(0)
	s_barrier
	s_setprio 1
	s_waitcnt lgkmcnt(0)
	v_mfma_f32_16x16x32_bf16 v[60:63], v[138:141], v[186:189], v[60:63]
	v_mfma_f32_16x16x32_bf16 v[56:59], v[152:155], v[186:189], v[56:59]
	v_mfma_f32_16x16x32_bf16 v[44:47], v[138:141], v[194:197], v[44:47]
	v_mfma_f32_16x16x32_bf16 v[40:43], v[152:155], v[194:197], v[40:43]
	v_mfma_f32_16x16x32_bf16 v[28:31], v[138:141], v[202:205], v[28:31]
	v_mfma_f32_16x16x32_bf16 v[24:27], v[152:155], v[202:205], v[24:27]
	v_mfma_f32_16x16x32_bf16 v[12:15], v[138:141], v[210:213], v[12:15]
	v_mfma_f32_16x16x32_bf16 v[8:11], v[152:155], v[210:213], v[8:11]
	v_mfma_f32_16x16x32_bf16 v[60:63], v[148:151], v[190:193], v[60:63]
	v_mfma_f32_16x16x32_bf16 v[56:59], v[156:159], v[190:193], v[56:59]
	v_mfma_f32_16x16x32_bf16 v[44:47], v[148:151], v[198:201], v[44:47]
	v_mfma_f32_16x16x32_bf16 v[40:43], v[156:159], v[198:201], v[40:43]
	v_mfma_f32_16x16x32_bf16 v[28:31], v[148:151], v[206:209], v[28:31]
	v_mfma_f32_16x16x32_bf16 v[24:27], v[156:159], v[206:209], v[24:27]
	v_mfma_f32_16x16x32_bf16 v[12:15], v[148:151], v[222:225], v[12:15]
	v_mfma_f32_16x16x32_bf16 v[8:11], v[156:159], v[222:225], v[8:11]
	v_mfma_f32_16x16x32_bf16 v[52:55], v[170:173], v[186:189], v[52:55]
	v_mfma_f32_16x16x32_bf16 v[48:51], v[178:181], v[186:189], v[48:51]
	v_mfma_f32_16x16x32_bf16 v[36:39], v[170:173], v[194:197], v[36:39]
	v_mfma_f32_16x16x32_bf16 v[32:35], v[178:181], v[194:197], v[32:35]
	v_mfma_f32_16x16x32_bf16 v[20:23], v[170:173], v[202:205], v[20:23]
	v_mfma_f32_16x16x32_bf16 v[16:19], v[178:181], v[202:205], v[16:19]
	v_mfma_f32_16x16x32_bf16 v[4:7], v[170:173], v[210:213], v[4:7]
	v_mfma_f32_16x16x32_bf16 v[0:3], v[178:181], v[210:213], v[0:3]
	v_mfma_f32_16x16x32_bf16 v[52:55], v[174:177], v[190:193], v[52:55]
	v_mfma_f32_16x16x32_bf16 v[48:51], v[182:185], v[190:193], v[48:51]
	v_mfma_f32_16x16x32_bf16 v[36:39], v[174:177], v[198:201], v[36:39]
	v_mfma_f32_16x16x32_bf16 v[32:35], v[182:185], v[198:201], v[32:35]
	v_mfma_f32_16x16x32_bf16 v[20:23], v[174:177], v[206:209], v[20:23]
	v_mfma_f32_16x16x32_bf16 v[16:19], v[182:185], v[206:209], v[16:19]
	v_mfma_f32_16x16x32_bf16 v[4:7], v[174:177], v[222:225], v[4:7]
	v_mfma_f32_16x16x32_bf16 v[0:3], v[182:185], v[222:225], v[0:3]
	s_add_i32 s86, s86, 2
	s_add_u32 s50, s50, 0x100
	s_addc_u32 s51, s51, 0
	s_cmp_gt_u32 s86, 9
	s_mov_b64 s[14:15], s[16:17]
	s_setprio 0
	s_barrier
.LBB0_165:
	s_add_u32 s16, s14, 0x100
	s_addc_u32 s17, s15, 0
	s_add_i32 s22, 0, 0x10000
	s_cmp_eq_u32 s86, 8
	s_cselect_b32 s39, s11, s17
	s_cselect_b32 s38, s10, s16
	v_add_u32_e32 v142, s22, v145
	s_cselect_b32 s19, s13, s51
	s_cselect_b32 s18, s12, s50
	s_add_i32 s23, 0, 0x14000
	ds_read_b128 v[138:141], v142
	ds_read_b128 v[148:151], v142 offset:1024
	ds_read_b128 v[152:155], v142 offset:2048
	ds_read_b128 v[156:159], v142 offset:3072
	v_add_u32_e32 v142, s23, v145
	ds_read_b128 v[170:173], v142
	ds_read_b128 v[174:177], v142 offset:1024
	ds_read_b128 v[178:181], v142 offset:2048
	ds_read_b128 v[182:185], v142 offset:3072
	v_lshl_add_u64 v[142:143], s[14:15], 0, v[134:135]
	s_add_i32 m0, s41, 0xc000
	ds_read_b128 v[186:189], v147
	ds_read_b128 v[190:193], v147 offset:1024
	ds_read_b128 v[194:197], v147 offset:2048
	ds_read_b128 v[198:201], v147 offset:3072
	ds_read_b128 v[202:205], v147 offset:4096
	ds_read_b128 v[206:209], v147 offset:5120
	ds_read_b128 v[210:213], v147 offset:6144
	ds_read_b128 v[222:225], v147 offset:7168
	global_load_lds_dwordx4 v[142:143], off
	v_lshl_add_u64 v[142:143], s[14:15], 0, v[136:137]
	s_add_i32 m0, s41, 0xe000
	s_nop 0
	global_load_lds_dwordx4 v[142:143], off
	s_waitcnt vmcnt(8)
	s_waitcnt lgkmcnt(0)
	s_barrier
	s_setprio 1
	s_waitcnt lgkmcnt(0)
	v_mfma_f32_16x16x32_bf16 v[124:127], v[138:141], v[186:189], v[124:127]
	v_mfma_f32_16x16x32_bf16 v[120:123], v[152:155], v[186:189], v[120:123]
	v_mfma_f32_16x16x32_bf16 v[108:111], v[138:141], v[194:197], v[108:111]
	v_mfma_f32_16x16x32_bf16 v[104:107], v[152:155], v[194:197], v[104:107]
	v_mfma_f32_16x16x32_bf16 v[92:95], v[138:141], v[202:205], v[92:95]
	v_mfma_f32_16x16x32_bf16 v[88:91], v[152:155], v[202:205], v[88:91]
	v_mfma_f32_16x16x32_bf16 v[76:79], v[138:141], v[210:213], v[76:79]
	v_mfma_f32_16x16x32_bf16 v[72:75], v[152:155], v[210:213], v[72:75]
	v_mfma_f32_16x16x32_bf16 v[124:127], v[148:151], v[190:193], v[124:127]
	v_mfma_f32_16x16x32_bf16 v[120:123], v[156:159], v[190:193], v[120:123]
	v_mfma_f32_16x16x32_bf16 v[108:111], v[148:151], v[198:201], v[108:111]
	v_mfma_f32_16x16x32_bf16 v[104:107], v[156:159], v[198:201], v[104:107]
	v_mfma_f32_16x16x32_bf16 v[92:95], v[148:151], v[206:209], v[92:95]
	v_mfma_f32_16x16x32_bf16 v[88:91], v[156:159], v[206:209], v[88:91]
	v_mfma_f32_16x16x32_bf16 v[76:79], v[148:151], v[222:225], v[76:79]
	v_mfma_f32_16x16x32_bf16 v[72:75], v[156:159], v[222:225], v[72:75]
	v_mfma_f32_16x16x32_bf16 v[116:119], v[170:173], v[186:189], v[116:119]
	v_mfma_f32_16x16x32_bf16 v[112:115], v[178:181], v[186:189], v[112:115]
	v_mfma_f32_16x16x32_bf16 v[100:103], v[170:173], v[194:197], v[100:103]
	v_mfma_f32_16x16x32_bf16 v[96:99], v[178:181], v[194:197], v[96:99]
	v_mfma_f32_16x16x32_bf16 v[84:87], v[170:173], v[202:205], v[84:87]
	v_mfma_f32_16x16x32_bf16 v[80:83], v[178:181], v[202:205], v[80:83]
	v_mfma_f32_16x16x32_bf16 v[68:71], v[170:173], v[210:213], v[68:71]
	v_mfma_f32_16x16x32_bf16 v[64:67], v[178:181], v[210:213], v[64:67]
	v_mfma_f32_16x16x32_bf16 v[116:119], v[174:177], v[190:193], v[116:119]
	v_mfma_f32_16x16x32_bf16 v[112:115], v[182:185], v[190:193], v[112:115]
	v_mfma_f32_16x16x32_bf16 v[100:103], v[174:177], v[198:201], v[100:103]
	v_mfma_f32_16x16x32_bf16 v[96:99], v[182:185], v[198:201], v[96:99]
	v_mfma_f32_16x16x32_bf16 v[84:87], v[174:177], v[206:209], v[84:87]
	v_mfma_f32_16x16x32_bf16 v[80:83], v[182:185], v[206:209], v[80:83]
	v_mfma_f32_16x16x32_bf16 v[68:71], v[174:177], v[222:225], v[68:71]
	v_mfma_f32_16x16x32_bf16 v[64:67], v[182:185], v[222:225], v[64:67]
	s_setprio 0
	s_barrier
	s_add_i32 s14, s22, s27
	v_lshl_add_u64 v[142:143], s[18:19], 0, v[160:161]
	s_mov_b32 m0, s14
	ds_read_b128 v[186:189], v147 offset:16384
	ds_read_b128 v[190:193], v147 offset:17408
	ds_read_b128 v[194:197], v147 offset:18432
	ds_read_b128 v[198:201], v147 offset:19456
	ds_read_b128 v[202:205], v147 offset:20480
	ds_read_b128 v[206:209], v147 offset:21504
	ds_read_b128 v[210:213], v147 offset:22528
	ds_read_b128 v[222:225], v147 offset:23552
	global_load_lds_dwordx4 v[142:143], off
	s_add_i32 m0, s14, 0x2000
	s_add_u32 s14, s18, 0x30000
	v_lshl_add_u64 v[162:163], s[18:19], 0, v[128:129]
	s_addc_u32 s15, s19, 0
	s_add_i32 s22, s23, s27
	global_load_lds_dwordx4 v[162:163], off
	v_lshl_add_u64 v[164:165], s[14:15], 0, v[160:161]
	s_mov_b32 m0, s22
	v_lshl_add_u64 v[214:215], s[38:39], 0, v[130:131]
	global_load_lds_dwordx4 v[164:165], off
	v_lshl_add_u64 v[164:165], s[14:15], 0, v[128:129]
	s_add_i32 m0, s22, 0x2000
	s_nop 0
	global_load_lds_dwordx4 v[164:165], off
	v_lshl_add_u64 v[164:165], s[38:39], 0, v[132:133]
	s_mov_b32 m0, s41
	s_nop 0
	global_load_lds_dwordx4 v[164:165], off
	s_mov_b32 m0, s42
	s_nop 0
	global_load_lds_dwordx4 v[214:215], off
	s_waitcnt vmcnt(8)
	s_waitcnt lgkmcnt(0)
	s_barrier
	s_setprio 1
	s_waitcnt lgkmcnt(0)
	v_mfma_f32_16x16x32_bf16 v[60:63], v[138:141], v[186:189], v[60:63]
	v_mfma_f32_16x16x32_bf16 v[56:59], v[152:155], v[186:189], v[56:59]
	v_mfma_f32_16x16x32_bf16 v[44:47], v[138:141], v[194:197], v[44:47]
	v_mfma_f32_16x16x32_bf16 v[40:43], v[152:155], v[194:197], v[40:43]
	v_mfma_f32_16x16x32_bf16 v[28:31], v[138:141], v[202:205], v[28:31]
	v_mfma_f32_16x16x32_bf16 v[24:27], v[152:155], v[202:205], v[24:27]
	v_mfma_f32_16x16x32_bf16 v[12:15], v[138:141], v[210:213], v[12:15]
	v_mfma_f32_16x16x32_bf16 v[8:11], v[152:155], v[210:213], v[8:11]
	v_mfma_f32_16x16x32_bf16 v[60:63], v[148:151], v[190:193], v[60:63]
	v_mfma_f32_16x16x32_bf16 v[56:59], v[156:159], v[190:193], v[56:59]
	v_mfma_f32_16x16x32_bf16 v[44:47], v[148:151], v[198:201], v[44:47]
	v_mfma_f32_16x16x32_bf16 v[40:43], v[156:159], v[198:201], v[40:43]
	v_mfma_f32_16x16x32_bf16 v[28:31], v[148:151], v[206:209], v[28:31]
	v_mfma_f32_16x16x32_bf16 v[24:27], v[156:159], v[206:209], v[24:27]
	v_mfma_f32_16x16x32_bf16 v[12:15], v[148:151], v[222:225], v[12:15]
	v_mfma_f32_16x16x32_bf16 v[8:11], v[156:159], v[222:225], v[8:11]
	v_mfma_f32_16x16x32_bf16 v[52:55], v[170:173], v[186:189], v[52:55]
	v_mfma_f32_16x16x32_bf16 v[48:51], v[178:181], v[186:189], v[48:51]
	v_mfma_f32_16x16x32_bf16 v[36:39], v[170:173], v[194:197], v[36:39]
	v_mfma_f32_16x16x32_bf16 v[32:35], v[178:181], v[194:197], v[32:35]
	v_mfma_f32_16x16x32_bf16 v[20:23], v[170:173], v[202:205], v[20:23]
	v_mfma_f32_16x16x32_bf16 v[16:19], v[178:181], v[202:205], v[16:19]
	v_mfma_f32_16x16x32_bf16 v[4:7], v[170:173], v[210:213], v[4:7]
	v_mfma_f32_16x16x32_bf16 v[0:3], v[178:181], v[210:213], v[0:3]
	v_mfma_f32_16x16x32_bf16 v[52:55], v[174:177], v[190:193], v[52:55]
	v_mfma_f32_16x16x32_bf16 v[48:51], v[182:185], v[190:193], v[48:51]
	v_mfma_f32_16x16x32_bf16 v[36:39], v[174:177], v[198:201], v[36:39]
	v_mfma_f32_16x16x32_bf16 v[32:35], v[182:185], v[198:201], v[32:35]
	v_mfma_f32_16x16x32_bf16 v[20:23], v[174:177], v[206:209], v[20:23]
	v_mfma_f32_16x16x32_bf16 v[16:19], v[182:185], v[206:209], v[16:19]
	v_mfma_f32_16x16x32_bf16 v[4:7], v[174:177], v[222:225], v[4:7]
	v_mfma_f32_16x16x32_bf16 v[0:3], v[182:185], v[222:225], v[0:3]
	s_setprio 0
	s_barrier
	s_add_i32 s22, 0, 0x18000
	s_add_i32 s23, 0, 0x1c000
	v_add_u32_e32 v156, s22, v145
	v_add_u32_e32 v167, s23, v145
	ds_read_b128 v[138:141], v156
	ds_read_b128 v[148:151], v156 offset:1024
	ds_read_b128 v[152:155], v156 offset:2048
	ds_read_b128 v[156:159], v156 offset:3072
	ds_read_b128 v[170:173], v167
	ds_read_b128 v[174:177], v167 offset:1024
	ds_read_b128 v[178:181], v167 offset:2048
	ds_read_b128 v[182:185], v167 offset:3072
	s_add_u32 s14, s38, 0x30000
	s_addc_u32 s15, s39, 0
	s_mov_b32 m0, s43
	v_lshl_add_u64 v[226:227], s[14:15], 0, v[132:133]
	ds_read_b128 v[186:189], v147 offset:32768
	ds_read_b128 v[190:193], v147 offset:33792
	ds_read_b128 v[194:197], v147 offset:34816
	ds_read_b128 v[198:201], v147 offset:35840
	ds_read_b128 v[202:205], v147 offset:36864
	ds_read_b128 v[206:209], v147 offset:37888
	ds_read_b128 v[210:213], v147 offset:38912
	ds_read_b128 v[222:225], v147 offset:39936
	global_load_lds_dwordx4 v[226:227], off
	v_lshl_add_u64 v[226:227], s[14:15], 0, v[130:131]
	s_mov_b32 m0, s80
	s_nop 0
	global_load_lds_dwordx4 v[226:227], off
	s_waitcnt vmcnt(8)
	s_waitcnt lgkmcnt(0)
	s_barrier
	s_setprio 1
	s_waitcnt lgkmcnt(0)
	v_mfma_f32_16x16x32_bf16 v[124:127], v[138:141], v[186:189], v[124:127]
	v_mfma_f32_16x16x32_bf16 v[120:123], v[152:155], v[186:189], v[120:123]
	v_mfma_f32_16x16x32_bf16 v[108:111], v[138:141], v[194:197], v[108:111]
	v_mfma_f32_16x16x32_bf16 v[104:107], v[152:155], v[194:197], v[104:107]
	v_mfma_f32_16x16x32_bf16 v[92:95], v[138:141], v[202:205], v[92:95]
	v_mfma_f32_16x16x32_bf16 v[88:91], v[152:155], v[202:205], v[88:91]
	v_mfma_f32_16x16x32_bf16 v[76:79], v[138:141], v[210:213], v[76:79]
	v_mfma_f32_16x16x32_bf16 v[72:75], v[152:155], v[210:213], v[72:75]
	v_mfma_f32_16x16x32_bf16 v[124:127], v[148:151], v[190:193], v[124:127]
	v_mfma_f32_16x16x32_bf16 v[120:123], v[156:159], v[190:193], v[120:123]
	v_mfma_f32_16x16x32_bf16 v[108:111], v[148:151], v[198:201], v[108:111]
	v_mfma_f32_16x16x32_bf16 v[104:107], v[156:159], v[198:201], v[104:107]
	v_mfma_f32_16x16x32_bf16 v[92:95], v[148:151], v[206:209], v[92:95]
	v_mfma_f32_16x16x32_bf16 v[88:91], v[156:159], v[206:209], v[88:91]
	v_mfma_f32_16x16x32_bf16 v[76:79], v[148:151], v[222:225], v[76:79]
	v_mfma_f32_16x16x32_bf16 v[72:75], v[156:159], v[222:225], v[72:75]
	v_mfma_f32_16x16x32_bf16 v[116:119], v[170:173], v[186:189], v[116:119]
	v_mfma_f32_16x16x32_bf16 v[112:115], v[178:181], v[186:189], v[112:115]
	v_mfma_f32_16x16x32_bf16 v[100:103], v[170:173], v[194:197], v[100:103]
	v_mfma_f32_16x16x32_bf16 v[96:99], v[178:181], v[194:197], v[96:99]
	v_mfma_f32_16x16x32_bf16 v[84:87], v[170:173], v[202:205], v[84:87]
	v_mfma_f32_16x16x32_bf16 v[80:83], v[178:181], v[202:205], v[80:83]
	v_mfma_f32_16x16x32_bf16 v[68:71], v[170:173], v[210:213], v[68:71]
	v_mfma_f32_16x16x32_bf16 v[64:67], v[178:181], v[210:213], v[64:67]
	v_mfma_f32_16x16x32_bf16 v[116:119], v[174:177], v[190:193], v[116:119]
	v_mfma_f32_16x16x32_bf16 v[112:115], v[182:185], v[190:193], v[112:115]
	v_mfma_f32_16x16x32_bf16 v[100:103], v[174:177], v[198:201], v[100:103]
	v_mfma_f32_16x16x32_bf16 v[96:99], v[182:185], v[198:201], v[96:99]
	v_mfma_f32_16x16x32_bf16 v[84:87], v[174:177], v[206:209], v[84:87]
	v_mfma_f32_16x16x32_bf16 v[80:83], v[182:185], v[206:209], v[80:83]
	v_mfma_f32_16x16x32_bf16 v[68:71], v[174:177], v[222:225], v[68:71]
	v_mfma_f32_16x16x32_bf16 v[64:67], v[182:185], v[222:225], v[64:67]
	s_setprio 0
	s_barrier
	s_add_i32 s14, s22, s27
	v_lshl_add_u64 v[142:143], v[142:143], 0, s[48:49]
	s_mov_b32 m0, s14
	ds_read_b128 v[186:189], v147 offset:49152
	ds_read_b128 v[190:193], v147 offset:50176
	ds_read_b128 v[194:197], v147 offset:51200
	ds_read_b128 v[198:201], v147 offset:52224
	ds_read_b128 v[202:205], v147 offset:53248
	ds_read_b128 v[206:209], v147 offset:54272
	ds_read_b128 v[210:213], v147 offset:55296
	ds_read_b128 v[222:225], v147 offset:56320
	global_load_lds_dwordx4 v[142:143], off
	s_add_i32 m0, s14, 0x2000
	s_add_u32 s14, s18, 0x30080
	v_lshl_add_u64 v[142:143], v[162:163], 0, s[48:49]
	s_addc_u32 s15, s19, 0
	s_add_i32 s18, s23, s27
	global_load_lds_dwordx4 v[142:143], off
	v_lshl_add_u64 v[142:143], s[14:15], 0, v[160:161]
	s_mov_b32 m0, s18
	s_nop 0
	global_load_lds_dwordx4 v[142:143], off
	v_lshl_add_u64 v[142:143], s[14:15], 0, v[128:129]
	s_add_i32 m0, s18, 0x2000
	s_nop 0
	global_load_lds_dwordx4 v[142:143], off
	v_lshl_add_u64 v[142:143], v[164:165], 0, s[48:49]
	s_mov_b32 m0, s81
	s_nop 0
	global_load_lds_dwordx4 v[142:143], off
	v_lshl_add_u64 v[142:143], v[214:215], 0, s[48:49]
	s_mov_b32 m0, s82
	s_nop 0
	global_load_lds_dwordx4 v[142:143], off
	s_waitcnt vmcnt(8)
	s_waitcnt lgkmcnt(0)
	s_barrier
	s_setprio 1
	s_waitcnt lgkmcnt(0)
	v_mfma_f32_16x16x32_bf16 v[60:63], v[138:141], v[186:189], v[60:63]
	v_mfma_f32_16x16x32_bf16 v[56:59], v[152:155], v[186:189], v[56:59]
	v_mfma_f32_16x16x32_bf16 v[44:47], v[138:141], v[194:197], v[44:47]
	v_mfma_f32_16x16x32_bf16 v[40:43], v[152:155], v[194:197], v[40:43]
	v_mfma_f32_16x16x32_bf16 v[28:31], v[138:141], v[202:205], v[28:31]
	v_mfma_f32_16x16x32_bf16 v[24:27], v[152:155], v[202:205], v[24:27]
	v_mfma_f32_16x16x32_bf16 v[12:15], v[138:141], v[210:213], v[12:15]
	v_mfma_f32_16x16x32_bf16 v[8:11], v[152:155], v[210:213], v[8:11]
	v_mfma_f32_16x16x32_bf16 v[60:63], v[148:151], v[190:193], v[60:63]
	v_mfma_f32_16x16x32_bf16 v[56:59], v[156:159], v[190:193], v[56:59]
	v_mfma_f32_16x16x32_bf16 v[44:47], v[148:151], v[198:201], v[44:47]
	v_mfma_f32_16x16x32_bf16 v[40:43], v[156:159], v[198:201], v[40:43]
	v_mfma_f32_16x16x32_bf16 v[28:31], v[148:151], v[206:209], v[28:31]
	v_mfma_f32_16x16x32_bf16 v[24:27], v[156:159], v[206:209], v[24:27]
	v_mfma_f32_16x16x32_bf16 v[12:15], v[148:151], v[222:225], v[12:15]
	v_mfma_f32_16x16x32_bf16 v[8:11], v[156:159], v[222:225], v[8:11]
	v_mfma_f32_16x16x32_bf16 v[52:55], v[170:173], v[186:189], v[52:55]
	v_mfma_f32_16x16x32_bf16 v[48:51], v[178:181], v[186:189], v[48:51]
	v_mfma_f32_16x16x32_bf16 v[36:39], v[170:173], v[194:197], v[36:39]
	v_mfma_f32_16x16x32_bf16 v[32:35], v[178:181], v[194:197], v[32:35]
	v_mfma_f32_16x16x32_bf16 v[20:23], v[170:173], v[202:205], v[20:23]
	v_mfma_f32_16x16x32_bf16 v[16:19], v[178:181], v[202:205], v[16:19]
	v_mfma_f32_16x16x32_bf16 v[4:7], v[170:173], v[210:213], v[4:7]
	v_mfma_f32_16x16x32_bf16 v[0:3], v[178:181], v[210:213], v[0:3]
	v_mfma_f32_16x16x32_bf16 v[52:55], v[174:177], v[190:193], v[52:55]
	v_mfma_f32_16x16x32_bf16 v[48:51], v[182:185], v[190:193], v[48:51]
	v_mfma_f32_16x16x32_bf16 v[36:39], v[174:177], v[198:201], v[36:39]
	v_mfma_f32_16x16x32_bf16 v[32:35], v[182:185], v[198:201], v[32:35]
	v_mfma_f32_16x16x32_bf16 v[20:23], v[174:177], v[206:209], v[20:23]
	v_mfma_f32_16x16x32_bf16 v[16:19], v[182:185], v[206:209], v[16:19]
	v_mfma_f32_16x16x32_bf16 v[4:7], v[174:177], v[222:225], v[4:7]
	v_mfma_f32_16x16x32_bf16 v[0:3], v[182:185], v[222:225], v[0:3]
	s_add_i32 s86, s86, 2
	s_add_u32 s50, s50, 0x100
	s_addc_u32 s51, s51, 0
	s_cmp_gt_u32 s86, 9
	s_mov_b64 s[14:15], s[16:17]
	s_setprio 0
	s_barrier
	s_cbranch_scc0 .LBB0_165
	s_and_b64 vcc, exec, s[8:9]
	s_cbranch_vccz .LBB0_168
	s_barrier

.LBB0_252:
	s_ashr_i32 s19, s18, 31
	s_lshl_b64 s[6:7], s[18:19], 19
	s_add_u32 s84, s0, s6
	s_addc_u32 s85, s1, s7
	s_and_b64 s[6:7], s[38:39], exec
	s_cselect_b32 s4, s85, s43
	s_cselect_b32 s11, s84, s42
	s_ashr_i32 s17, s16, 31
	s_lshl_b64 s[6:7], s[16:17], 19
	s_add_u32 s6, s26, s6
	s_addc_u32 s7, s27, s7
	s_and_b64 s[24:25], s[38:39], exec
	s_cselect_b32 s17, s7, s83
	s_cselect_b32 s19, s6, s82
	s_add_u32 s42, s42, 0x40080
	s_addc_u32 s43, s43, 0
	s_add_u32 s24, s82, 0x100
	s_addc_u32 s25, s83, 0
	s_mov_b32 s41, -2
	s_waitcnt lgkmcnt(0)
	s_add_u32 s22, s42, 0xfffc0080
	s_addc_u32 s23, s43, -1
	s_add_i32 s28, 0, 0x10000
	s_cmp_eq_u32 s41, 12
	s_cselect_b32 vcc_hi, s4, s23
	s_cselect_b32 vcc_lo, s11, s22
	v_add_u32_e32 v160, s28, v167
	s_cselect_b32 s83, s17, s25
	s_cselect_b32 s82, s19, s24
	s_add_i32 s22, 0, 0x14000
	ds_read_b128 v[148:151], v160
	ds_read_b128 v[152:155], v160 offset:1024
	ds_read_b128 v[156:159], v160 offset:2048
	ds_read_b128 v[174:177], v160 offset:3072
	v_add_u32_e32 v160, s22, v167
	ds_read_b128 v[178:181], v160
	ds_read_b128 v[182:185], v160 offset:1024
	ds_read_b128 v[186:189], v160 offset:2048
	ds_read_b128 v[190:193], v160 offset:3072
	v_lshl_add_u64 v[162:163], s[42:43], 0, v[144:145]
	s_add_i32 m0, s81, 0xc000
	ds_read_b128 v[194:197], v173
	ds_read_b128 v[198:201], v173 offset:1024
	ds_read_b128 v[202:205], v173 offset:2048
	ds_read_b128 v[206:209], v173 offset:3072
	ds_read_b128 v[210:213], v173 offset:4096
	ds_read_b128 v[222:225], v173 offset:5120
	ds_read_b128 v[234:237], v173 offset:6144
	ds_read_b128 v[238:241], v173 offset:7168
	global_load_lds_dwordx4 v[162:163], off
	v_lshl_add_u64 v[162:163], s[42:43], 0, v[146:147]
	s_add_i32 m0, s81, 0xe000
	s_nop 0
	global_load_lds_dwordx4 v[162:163], off
	s_waitcnt vmcnt(8)
	s_waitcnt lgkmcnt(0)
	s_barrier
	s_setprio 1
	s_waitcnt lgkmcnt(0)
	v_mfma_f32_16x16x32_bf16 v[124:127], v[148:151], v[194:197], 0
	v_mfma_f32_16x16x32_bf16 v[120:123], v[156:159], v[194:197], 0
	v_mfma_f32_16x16x32_bf16 v[108:111], v[148:151], v[202:205], 0
	v_mfma_f32_16x16x32_bf16 v[104:107], v[156:159], v[202:205], 0
	v_mfma_f32_16x16x32_bf16 v[92:95], v[148:151], v[210:213], 0
	v_mfma_f32_16x16x32_bf16 v[88:91], v[156:159], v[210:213], 0
	v_mfma_f32_16x16x32_bf16 v[76:79], v[148:151], v[234:237], 0
	v_mfma_f32_16x16x32_bf16 v[72:75], v[156:159], v[234:237], 0
	v_mfma_f32_16x16x32_bf16 v[124:127], v[152:155], v[198:201], v[124:127]
	v_mfma_f32_16x16x32_bf16 v[120:123], v[174:177], v[198:201], v[120:123]
	v_mfma_f32_16x16x32_bf16 v[108:111], v[152:155], v[206:209], v[108:111]
	v_mfma_f32_16x16x32_bf16 v[104:107], v[174:177], v[206:209], v[104:107]
	v_mfma_f32_16x16x32_bf16 v[92:95], v[152:155], v[222:225], v[92:95]
	v_mfma_f32_16x16x32_bf16 v[88:91], v[174:177], v[222:225], v[88:91]
	v_mfma_f32_16x16x32_bf16 v[76:79], v[152:155], v[238:241], v[76:79]
	v_mfma_f32_16x16x32_bf16 v[72:75], v[174:177], v[238:241], v[72:75]
	v_mfma_f32_16x16x32_bf16 v[116:119], v[178:181], v[194:197], 0
	v_mfma_f32_16x16x32_bf16 v[112:115], v[186:189], v[194:197], 0
	v_mfma_f32_16x16x32_bf16 v[100:103], v[178:181], v[202:205], 0
	v_mfma_f32_16x16x32_bf16 v[96:99], v[186:189], v[202:205], 0
	v_mfma_f32_16x16x32_bf16 v[84:87], v[178:181], v[210:213], 0
	v_mfma_f32_16x16x32_bf16 v[80:83], v[186:189], v[210:213], 0
	v_mfma_f32_16x16x32_bf16 v[68:71], v[178:181], v[234:237], 0
	v_mfma_f32_16x16x32_bf16 v[64:67], v[186:189], v[234:237], 0
	v_mfma_f32_16x16x32_bf16 v[116:119], v[182:185], v[198:201], v[116:119]
	v_mfma_f32_16x16x32_bf16 v[112:115], v[190:193], v[198:201], v[112:115]
	v_mfma_f32_16x16x32_bf16 v[100:103], v[182:185], v[206:209], v[100:103]
	v_mfma_f32_16x16x32_bf16 v[96:99], v[190:193], v[206:209], v[96:99]
	v_mfma_f32_16x16x32_bf16 v[84:87], v[182:185], v[222:225], v[84:87]
	v_mfma_f32_16x16x32_bf16 v[80:83], v[190:193], v[222:225], v[80:83]
	v_mfma_f32_16x16x32_bf16 v[68:71], v[182:185], v[238:241], v[68:71]
	v_mfma_f32_16x16x32_bf16 v[64:67], v[190:193], v[238:241], v[64:67]
	s_setprio 0
	s_barrier
	s_add_i32 s23, s28, s80
	v_lshl_add_u64 v[162:163], s[82:83], 0, v[130:131]
	s_mov_b32 m0, s23
	ds_read_b128 v[194:197], v173 offset:16384
	ds_read_b128 v[198:201], v173 offset:17408
	ds_read_b128 v[202:205], v173 offset:18432
	ds_read_b128 v[206:209], v173 offset:19456
	ds_read_b128 v[210:213], v173 offset:20480
	ds_read_b128 v[222:225], v173 offset:21504
	ds_read_b128 v[234:237], v173 offset:22528
	ds_read_b128 v[238:241], v173 offset:23552
	global_load_lds_dwordx4 v[162:163], off
	s_add_i32 m0, s23, 0x2000
	s_add_u32 s50, s82, 0x40000
	v_lshl_add_u64 v[164:165], s[82:83], 0, v[134:135]
	s_addc_u32 s51, s83, 0
	s_add_i32 s22, s22, s80
	global_load_lds_dwordx4 v[164:165], off
	v_lshl_add_u64 v[170:171], s[50:51], 0, v[130:131]
	s_mov_b32 m0, s22
	v_lshl_add_u64 v[214:215], vcc, 0, v[132:133]
	global_load_lds_dwordx4 v[170:171], off
	v_lshl_add_u64 v[170:171], s[50:51], 0, v[134:135]
	s_add_i32 m0, s22, 0x2000
	s_nop 0
	global_load_lds_dwordx4 v[170:171], off
	v_lshl_add_u64 v[170:171], vcc, 0, v[128:129]
	s_mov_b32 m0, s81
	s_nop 0
	global_load_lds_dwordx4 v[170:171], off
	s_mov_b32 m0, s86
	s_nop 0
	global_load_lds_dwordx4 v[214:215], off
	s_waitcnt vmcnt(8)
	s_waitcnt lgkmcnt(0)
	s_barrier
	s_setprio 1
	s_waitcnt lgkmcnt(0)
	v_mfma_f32_16x16x32_bf16 v[60:63], v[148:151], v[194:197], 0
	v_mfma_f32_16x16x32_bf16 v[56:59], v[156:159], v[194:197], 0
	v_mfma_f32_16x16x32_bf16 v[44:47], v[148:151], v[202:205], 0
	v_mfma_f32_16x16x32_bf16 v[40:43], v[156:159], v[202:205], 0
	v_mfma_f32_16x16x32_bf16 v[28:31], v[148:151], v[210:213], 0
	v_mfma_f32_16x16x32_bf16 v[24:27], v[156:159], v[210:213], 0
	v_mfma_f32_16x16x32_bf16 v[12:15], v[148:151], v[234:237], 0
	v_mfma_f32_16x16x32_bf16 v[8:11], v[156:159], v[234:237], 0
	v_mfma_f32_16x16x32_bf16 v[60:63], v[152:155], v[198:201], v[60:63]
	v_mfma_f32_16x16x32_bf16 v[56:59], v[174:177], v[198:201], v[56:59]
	v_mfma_f32_16x16x32_bf16 v[44:47], v[152:155], v[206:209], v[44:47]
	v_mfma_f32_16x16x32_bf16 v[40:43], v[174:177], v[206:209], v[40:43]
	v_mfma_f32_16x16x32_bf16 v[28:31], v[152:155], v[222:225], v[28:31]
	v_mfma_f32_16x16x32_bf16 v[24:27], v[174:177], v[222:225], v[24:27]
	v_mfma_f32_16x16x32_bf16 v[12:15], v[152:155], v[238:241], v[12:15]
	v_mfma_f32_16x16x32_bf16 v[8:11], v[174:177], v[238:241], v[8:11]
	v_mfma_f32_16x16x32_bf16 v[52:55], v[178:181], v[194:197], 0
	v_mfma_f32_16x16x32_bf16 v[48:51], v[186:189], v[194:197], 0
	v_mfma_f32_16x16x32_bf16 v[36:39], v[178:181], v[202:205], 0
	v_mfma_f32_16x16x32_bf16 v[32:35], v[186:189], v[202:205], 0
	v_mfma_f32_16x16x32_bf16 v[20:23], v[178:181], v[210:213], 0
	v_mfma_f32_16x16x32_bf16 v[16:19], v[186:189], v[210:213], 0
	v_mfma_f32_16x16x32_bf16 v[4:7], v[178:181], v[234:237], 0
	v_mfma_f32_16x16x32_bf16 v[0:3], v[186:189], v[234:237], 0
	v_mfma_f32_16x16x32_bf16 v[52:55], v[182:185], v[198:201], v[52:55]
	v_mfma_f32_16x16x32_bf16 v[48:51], v[190:193], v[198:201], v[48:51]
	v_mfma_f32_16x16x32_bf16 v[36:39], v[182:185], v[206:209], v[36:39]
	v_mfma_f32_16x16x32_bf16 v[32:35], v[190:193], v[206:209], v[32:35]
	v_mfma_f32_16x16x32_bf16 v[20:23], v[182:185], v[222:225], v[20:23]
	v_mfma_f32_16x16x32_bf16 v[16:19], v[190:193], v[222:225], v[16:19]
	v_mfma_f32_16x16x32_bf16 v[4:7], v[182:185], v[238:241], v[4:7]
	v_mfma_f32_16x16x32_bf16 v[0:3], v[190:193], v[238:241], v[0:3]
	s_setprio 0
	s_barrier
	s_add_i32 s22, 0, 0x18000
	v_add_u32_e32 v160, s22, v167
	s_add_i32 s23, 0, 0x1c000
	ds_read_b128 v[148:151], v160
	ds_read_b128 v[152:155], v160 offset:1024
	ds_read_b128 v[156:159], v160 offset:2048
	ds_read_b128 v[174:177], v160 offset:3072
	v_add_u32_e32 v160, s23, v167
	ds_read_b128 v[178:181], v160
	ds_read_b128 v[182:185], v160 offset:1024
	ds_read_b128 v[186:189], v160 offset:2048
	ds_read_b128 v[190:193], v160 offset:3072
	s_add_u32 s50, vcc_lo, 0x40000
	s_addc_u32 s51, vcc_hi, 0
	s_mov_b32 m0, s87
	v_lshl_add_u64 v[226:227], s[50:51], 0, v[128:129]
	ds_read_b128 v[194:197], v173 offset:32768
	ds_read_b128 v[198:201], v173 offset:33792
	ds_read_b128 v[202:205], v173 offset:34816
	ds_read_b128 v[206:209], v173 offset:35840
	ds_read_b128 v[210:213], v173 offset:36864
	ds_read_b128 v[222:225], v173 offset:37888
	ds_read_b128 v[234:237], v173 offset:38912
	ds_read_b128 v[238:241], v173 offset:39936
	global_load_lds_dwordx4 v[226:227], off
	v_lshl_add_u64 v[226:227], s[50:51], 0, v[132:133]
	s_mov_b32 m0, s88
	s_nop 0
	global_load_lds_dwordx4 v[226:227], off
	s_waitcnt vmcnt(8)
	s_waitcnt lgkmcnt(0)
	s_barrier
	s_setprio 1
	s_waitcnt lgkmcnt(0)
	v_mfma_f32_16x16x32_bf16 v[124:127], v[148:151], v[194:197], v[124:127]
	v_mfma_f32_16x16x32_bf16 v[120:123], v[156:159], v[194:197], v[120:123]
	v_mfma_f32_16x16x32_bf16 v[108:111], v[148:151], v[202:205], v[108:111]
	v_mfma_f32_16x16x32_bf16 v[104:107], v[156:159], v[202:205], v[104:107]
	v_mfma_f32_16x16x32_bf16 v[92:95], v[148:151], v[210:213], v[92:95]
	v_mfma_f32_16x16x32_bf16 v[88:91], v[156:159], v[210:213], v[88:91]
	v_mfma_f32_16x16x32_bf16 v[76:79], v[148:151], v[234:237], v[76:79]
	v_mfma_f32_16x16x32_bf16 v[72:75], v[156:159], v[234:237], v[72:75]
	v_mfma_f32_16x16x32_bf16 v[124:127], v[152:155], v[198:201], v[124:127]
	v_mfma_f32_16x16x32_bf16 v[120:123], v[174:177], v[198:201], v[120:123]
	v_mfma_f32_16x16x32_bf16 v[108:111], v[152:155], v[206:209], v[108:111]
	v_mfma_f32_16x16x32_bf16 v[104:107], v[174:177], v[206:209], v[104:107]
	v_mfma_f32_16x16x32_bf16 v[92:95], v[152:155], v[222:225], v[92:95]
	v_mfma_f32_16x16x32_bf16 v[88:91], v[174:177], v[222:225], v[88:91]
	v_mfma_f32_16x16x32_bf16 v[76:79], v[152:155], v[238:241], v[76:79]
	v_mfma_f32_16x16x32_bf16 v[72:75], v[174:177], v[238:241], v[72:75]
	v_mfma_f32_16x16x32_bf16 v[116:119], v[178:181], v[194:197], v[116:119]
	v_mfma_f32_16x16x32_bf16 v[112:115], v[186:189], v[194:197], v[112:115]
	v_mfma_f32_16x16x32_bf16 v[100:103], v[178:181], v[202:205], v[100:103]
	v_mfma_f32_16x16x32_bf16 v[96:99], v[186:189], v[202:205], v[96:99]
	v_mfma_f32_16x16x32_bf16 v[84:87], v[178:181], v[210:213], v[84:87]
	v_mfma_f32_16x16x32_bf16 v[80:83], v[186:189], v[210:213], v[80:83]
	v_mfma_f32_16x16x32_bf16 v[68:71], v[178:181], v[234:237], v[68:71]
	v_mfma_f32_16x16x32_bf16 v[64:67], v[186:189], v[234:237], v[64:67]
	v_mfma_f32_16x16x32_bf16 v[116:119], v[182:185], v[198:201], v[116:119]
	v_mfma_f32_16x16x32_bf16 v[112:115], v[190:193], v[198:201], v[112:115]
	v_mfma_f32_16x16x32_bf16 v[100:103], v[182:185], v[206:209], v[100:103]
	v_mfma_f32_16x16x32_bf16 v[96:99], v[190:193], v[206:209], v[96:99]
	v_mfma_f32_16x16x32_bf16 v[84:87], v[182:185], v[222:225], v[84:87]
	v_mfma_f32_16x16x32_bf16 v[80:83], v[190:193], v[222:225], v[80:83]
	v_mfma_f32_16x16x32_bf16 v[68:71], v[182:185], v[238:241], v[68:71]
	v_mfma_f32_16x16x32_bf16 v[64:67], v[190:193], v[238:241], v[64:67]
	s_setprio 0
	s_barrier
	s_add_i32 s22, s22, s80
	v_lshl_add_u64 v[162:163], v[162:163], 0, s[48:49]
	s_mov_b32 m0, s22
	ds_read_b128 v[194:197], v173 offset:49152
	ds_read_b128 v[198:201], v173 offset:50176
	ds_read_b128 v[202:205], v173 offset:51200
	ds_read_b128 v[206:209], v173 offset:52224
	ds_read_b128 v[210:213], v173 offset:53248
	ds_read_b128 v[222:225], v173 offset:54272
	ds_read_b128 v[234:237], v173 offset:55296
	ds_read_b128 v[238:241], v173 offset:56320
	global_load_lds_dwordx4 v[162:163], off
	s_add_i32 m0, s22, 0x2000
	s_add_u32 s50, s82, 0x40080
	v_lshl_add_u64 v[162:163], v[164:165], 0, s[48:49]
	s_addc_u32 s51, s83, 0
	s_add_i32 s22, s23, s80
	global_load_lds_dwordx4 v[162:163], off
	v_lshl_add_u64 v[162:163], s[50:51], 0, v[130:131]
	s_mov_b32 m0, s22
	s_nop 0
	global_load_lds_dwordx4 v[162:163], off
	v_lshl_add_u64 v[162:163], s[50:51], 0, v[134:135]
	s_add_i32 m0, s22, 0x2000
	s_nop 0
	global_load_lds_dwordx4 v[162:163], off
	v_lshl_add_u64 v[162:163], v[170:171], 0, s[48:49]
	s_mov_b32 m0, s90
	s_nop 0
	global_load_lds_dwordx4 v[162:163], off
	v_lshl_add_u64 v[162:163], v[214:215], 0, s[48:49]
	s_mov_b32 m0, s91
	s_nop 0
	global_load_lds_dwordx4 v[162:163], off
	s_waitcnt vmcnt(8)
	s_waitcnt lgkmcnt(0)
	s_barrier
	s_setprio 1
	s_waitcnt lgkmcnt(0)
	v_mfma_f32_16x16x32_bf16 v[60:63], v[148:151], v[194:197], v[60:63]
	v_mfma_f32_16x16x32_bf16 v[56:59], v[156:159], v[194:197], v[56:59]
	v_mfma_f32_16x16x32_bf16 v[44:47], v[148:151], v[202:205], v[44:47]
	v_mfma_f32_16x16x32_bf16 v[40:43], v[156:159], v[202:205], v[40:43]
	v_mfma_f32_16x16x32_bf16 v[28:31], v[148:151], v[210:213], v[28:31]
	v_mfma_f32_16x16x32_bf16 v[24:27], v[156:159], v[210:213], v[24:27]
	v_mfma_f32_16x16x32_bf16 v[12:15], v[148:151], v[234:237], v[12:15]
	v_mfma_f32_16x16x32_bf16 v[8:11], v[156:159], v[234:237], v[8:11]
	v_mfma_f32_16x16x32_bf16 v[60:63], v[152:155], v[198:201], v[60:63]
	v_mfma_f32_16x16x32_bf16 v[56:59], v[174:177], v[198:201], v[56:59]
	v_mfma_f32_16x16x32_bf16 v[44:47], v[152:155], v[206:209], v[44:47]
	v_mfma_f32_16x16x32_bf16 v[40:43], v[174:177], v[206:209], v[40:43]
	v_mfma_f32_16x16x32_bf16 v[28:31], v[152:155], v[222:225], v[28:31]
	v_mfma_f32_16x16x32_bf16 v[24:27], v[174:177], v[222:225], v[24:27]
	v_mfma_f32_16x16x32_bf16 v[12:15], v[152:155], v[238:241], v[12:15]
	v_mfma_f32_16x16x32_bf16 v[8:11], v[174:177], v[238:241], v[8:11]
	v_mfma_f32_16x16x32_bf16 v[52:55], v[178:181], v[194:197], v[52:55]
	v_mfma_f32_16x16x32_bf16 v[48:51], v[186:189], v[194:197], v[48:51]
	v_mfma_f32_16x16x32_bf16 v[36:39], v[178:181], v[202:205], v[36:39]
	v_mfma_f32_16x16x32_bf16 v[32:35], v[186:189], v[202:205], v[32:35]
	v_mfma_f32_16x16x32_bf16 v[20:23], v[178:181], v[210:213], v[20:23]
	v_mfma_f32_16x16x32_bf16 v[16:19], v[186:189], v[210:213], v[16:19]
	v_mfma_f32_16x16x32_bf16 v[4:7], v[178:181], v[234:237], v[4:7]
	v_mfma_f32_16x16x32_bf16 v[0:3], v[186:189], v[234:237], v[0:3]
	v_mfma_f32_16x16x32_bf16 v[52:55], v[182:185], v[198:201], v[52:55]
	v_mfma_f32_16x16x32_bf16 v[48:51], v[190:193], v[198:201], v[48:51]
	v_mfma_f32_16x16x32_bf16 v[36:39], v[182:185], v[206:209], v[36:39]
	v_mfma_f32_16x16x32_bf16 v[32:35], v[190:193], v[206:209], v[32:35]
	v_mfma_f32_16x16x32_bf16 v[20:23], v[182:185], v[222:225], v[20:23]
	v_mfma_f32_16x16x32_bf16 v[16:19], v[190:193], v[222:225], v[16:19]
	v_mfma_f32_16x16x32_bf16 v[4:7], v[182:185], v[238:241], v[4:7]
	v_mfma_f32_16x16x32_bf16 v[0:3], v[190:193], v[238:241], v[0:3]
	s_add_i32 s41, s41, 2
	s_add_u32 s42, s42, 0x100
	s_addc_u32 s43, s43, 0
	s_add_u32 s24, s24, 0x100
	s_addc_u32 s25, s25, 0
	s_cmp_gt_u32 s41, 13
	s_setprio 0
	s_barrier
.LBB0_253:
	s_add_u32 s22, s42, 0xfffc0080
	s_addc_u32 s23, s43, -1
	s_add_i32 s28, 0, 0x10000
	s_cmp_eq_u32 s41, 12
	s_cselect_b32 vcc_hi, s4, s23
	s_cselect_b32 vcc_lo, s11, s22
	v_add_u32_e32 v160, s28, v167
	s_cselect_b32 s83, s17, s25
	s_cselect_b32 s82, s19, s24
	s_add_i32 s22, 0, 0x14000
	ds_read_b128 v[148:151], v160
	ds_read_b128 v[152:155], v160 offset:1024
	ds_read_b128 v[156:159], v160 offset:2048
	ds_read_b128 v[174:177], v160 offset:3072
	v_add_u32_e32 v160, s22, v167
	ds_read_b128 v[178:181], v160
	ds_read_b128 v[182:185], v160 offset:1024
	ds_read_b128 v[186:189], v160 offset:2048
	ds_read_b128 v[190:193], v160 offset:3072
	v_lshl_add_u64 v[162:163], s[42:43], 0, v[144:145]
	s_add_i32 m0, s81, 0xc000
	ds_read_b128 v[194:197], v173
	ds_read_b128 v[198:201], v173 offset:1024
	ds_read_b128 v[202:205], v173 offset:2048
	ds_read_b128 v[206:209], v173 offset:3072
	ds_read_b128 v[210:213], v173 offset:4096
	ds_read_b128 v[222:225], v173 offset:5120
	ds_read_b128 v[234:237], v173 offset:6144
	ds_read_b128 v[238:241], v173 offset:7168
	global_load_lds_dwordx4 v[162:163], off
	v_lshl_add_u64 v[162:163], s[42:43], 0, v[146:147]
	s_add_i32 m0, s81, 0xe000
	s_nop 0
	global_load_lds_dwordx4 v[162:163], off
	s_waitcnt vmcnt(8)
	s_waitcnt lgkmcnt(0)
	s_barrier
	s_setprio 1
	s_waitcnt lgkmcnt(0)
	v_mfma_f32_16x16x32_bf16 v[124:127], v[148:151], v[194:197], v[124:127]
	v_mfma_f32_16x16x32_bf16 v[120:123], v[156:159], v[194:197], v[120:123]
	v_mfma_f32_16x16x32_bf16 v[108:111], v[148:151], v[202:205], v[108:111]
	v_mfma_f32_16x16x32_bf16 v[104:107], v[156:159], v[202:205], v[104:107]
	v_mfma_f32_16x16x32_bf16 v[92:95], v[148:151], v[210:213], v[92:95]
	v_mfma_f32_16x16x32_bf16 v[88:91], v[156:159], v[210:213], v[88:91]
	v_mfma_f32_16x16x32_bf16 v[76:79], v[148:151], v[234:237], v[76:79]
	v_mfma_f32_16x16x32_bf16 v[72:75], v[156:159], v[234:237], v[72:75]
	v_mfma_f32_16x16x32_bf16 v[124:127], v[152:155], v[198:201], v[124:127]
	v_mfma_f32_16x16x32_bf16 v[120:123], v[174:177], v[198:201], v[120:123]
	v_mfma_f32_16x16x32_bf16 v[108:111], v[152:155], v[206:209], v[108:111]
	v_mfma_f32_16x16x32_bf16 v[104:107], v[174:177], v[206:209], v[104:107]
	v_mfma_f32_16x16x32_bf16 v[92:95], v[152:155], v[222:225], v[92:95]
	v_mfma_f32_16x16x32_bf16 v[88:91], v[174:177], v[222:225], v[88:91]
	v_mfma_f32_16x16x32_bf16 v[76:79], v[152:155], v[238:241], v[76:79]
	v_mfma_f32_16x16x32_bf16 v[72:75], v[174:177], v[238:241], v[72:75]
	v_mfma_f32_16x16x32_bf16 v[116:119], v[178:181], v[194:197], v[116:119]
	v_mfma_f32_16x16x32_bf16 v[112:115], v[186:189], v[194:197], v[112:115]
	v_mfma_f32_16x16x32_bf16 v[100:103], v[178:181], v[202:205], v[100:103]
	v_mfma_f32_16x16x32_bf16 v[96:99], v[186:189], v[202:205], v[96:99]
	v_mfma_f32_16x16x32_bf16 v[84:87], v[178:181], v[210:213], v[84:87]
	v_mfma_f32_16x16x32_bf16 v[80:83], v[186:189], v[210:213], v[80:83]
	v_mfma_f32_16x16x32_bf16 v[68:71], v[178:181], v[234:237], v[68:71]
	v_mfma_f32_16x16x32_bf16 v[64:67], v[186:189], v[234:237], v[64:67]
	v_mfma_f32_16x16x32_bf16 v[116:119], v[182:185], v[198:201], v[116:119]
	v_mfma_f32_16x16x32_bf16 v[112:115], v[190:193], v[198:201], v[112:115]
	v_mfma_f32_16x16x32_bf16 v[100:103], v[182:185], v[206:209], v[100:103]
	v_mfma_f32_16x16x32_bf16 v[96:99], v[190:193], v[206:209], v[96:99]
	v_mfma_f32_16x16x32_bf16 v[84:87], v[182:185], v[222:225], v[84:87]
	v_mfma_f32_16x16x32_bf16 v[80:83], v[190:193], v[222:225], v[80:83]
	v_mfma_f32_16x16x32_bf16 v[68:71], v[182:185], v[238:241], v[68:71]
	v_mfma_f32_16x16x32_bf16 v[64:67], v[190:193], v[238:241], v[64:67]
	s_setprio 0
	s_barrier
	s_add_i32 s23, s28, s80
	v_lshl_add_u64 v[162:163], s[82:83], 0, v[130:131]
	s_mov_b32 m0, s23
	ds_read_b128 v[194:197], v173 offset:16384
	ds_read_b128 v[198:201], v173 offset:17408
	ds_read_b128 v[202:205], v173 offset:18432
	ds_read_b128 v[206:209], v173 offset:19456
	ds_read_b128 v[210:213], v173 offset:20480
	ds_read_b128 v[222:225], v173 offset:21504
	ds_read_b128 v[234:237], v173 offset:22528
	ds_read_b128 v[238:241], v173 offset:23552
	global_load_lds_dwordx4 v[162:163], off
	s_add_i32 m0, s23, 0x2000
	s_add_u32 s50, s82, 0x40000
	v_lshl_add_u64 v[164:165], s[82:83], 0, v[134:135]
	s_addc_u32 s51, s83, 0
	s_add_i32 s22, s22, s80
	global_load_lds_dwordx4 v[164:165], off
	v_lshl_add_u64 v[170:171], s[50:51], 0, v[130:131]
	s_mov_b32 m0, s22
	v_lshl_add_u64 v[214:215], vcc, 0, v[132:133]
	global_load_lds_dwordx4 v[170:171], off
	v_lshl_add_u64 v[170:171], s[50:51], 0, v[134:135]
	s_add_i32 m0, s22, 0x2000
	s_nop 0
	global_load_lds_dwordx4 v[170:171], off
	v_lshl_add_u64 v[170:171], vcc, 0, v[128:129]
	s_mov_b32 m0, s81
	s_nop 0
	global_load_lds_dwordx4 v[170:171], off
	s_mov_b32 m0, s86
	s_nop 0
	global_load_lds_dwordx4 v[214:215], off
	s_waitcnt vmcnt(8)
	s_waitcnt lgkmcnt(0)
	s_barrier
	s_setprio 1
	s_waitcnt lgkmcnt(0)
	v_mfma_f32_16x16x32_bf16 v[60:63], v[148:151], v[194:197], v[60:63]
	v_mfma_f32_16x16x32_bf16 v[56:59], v[156:159], v[194:197], v[56:59]
	v_mfma_f32_16x16x32_bf16 v[44:47], v[148:151], v[202:205], v[44:47]
	v_mfma_f32_16x16x32_bf16 v[40:43], v[156:159], v[202:205], v[40:43]
	v_mfma_f32_16x16x32_bf16 v[28:31], v[148:151], v[210:213], v[28:31]
	v_mfma_f32_16x16x32_bf16 v[24:27], v[156:159], v[210:213], v[24:27]
	v_mfma_f32_16x16x32_bf16 v[12:15], v[148:151], v[234:237], v[12:15]
	v_mfma_f32_16x16x32_bf16 v[8:11], v[156:159], v[234:237], v[8:11]
	v_mfma_f32_16x16x32_bf16 v[60:63], v[152:155], v[198:201], v[60:63]
	v_mfma_f32_16x16x32_bf16 v[56:59], v[174:177], v[198:201], v[56:59]
	v_mfma_f32_16x16x32_bf16 v[44:47], v[152:155], v[206:209], v[44:47]
	v_mfma_f32_16x16x32_bf16 v[40:43], v[174:177], v[206:209], v[40:43]
	v_mfma_f32_16x16x32_bf16 v[28:31], v[152:155], v[222:225], v[28:31]
	v_mfma_f32_16x16x32_bf16 v[24:27], v[174:177], v[222:225], v[24:27]
	v_mfma_f32_16x16x32_bf16 v[12:15], v[152:155], v[238:241], v[12:15]
	v_mfma_f32_16x16x32_bf16 v[8:11], v[174:177], v[238:241], v[8:11]
	v_mfma_f32_16x16x32_bf16 v[52:55], v[178:181], v[194:197], v[52:55]
	v_mfma_f32_16x16x32_bf16 v[48:51], v[186:189], v[194:197], v[48:51]
	v_mfma_f32_16x16x32_bf16 v[36:39], v[178:181], v[202:205], v[36:39]
	v_mfma_f32_16x16x32_bf16 v[32:35], v[186:189], v[202:205], v[32:35]
	v_mfma_f32_16x16x32_bf16 v[20:23], v[178:181], v[210:213], v[20:23]
	v_mfma_f32_16x16x32_bf16 v[16:19], v[186:189], v[210:213], v[16:19]
	v_mfma_f32_16x16x32_bf16 v[4:7], v[178:181], v[234:237], v[4:7]
	v_mfma_f32_16x16x32_bf16 v[0:3], v[186:189], v[234:237], v[0:3]
	v_mfma_f32_16x16x32_bf16 v[52:55], v[182:185], v[198:201], v[52:55]
	v_mfma_f32_16x16x32_bf16 v[48:51], v[190:193], v[198:201], v[48:51]
	v_mfma_f32_16x16x32_bf16 v[36:39], v[182:185], v[206:209], v[36:39]
	v_mfma_f32_16x16x32_bf16 v[32:35], v[190:193], v[206:209], v[32:35]
	v_mfma_f32_16x16x32_bf16 v[20:23], v[182:185], v[222:225], v[20:23]
	v_mfma_f32_16x16x32_bf16 v[16:19], v[190:193], v[222:225], v[16:19]
	v_mfma_f32_16x16x32_bf16 v[4:7], v[182:185], v[238:241], v[4:7]
	v_mfma_f32_16x16x32_bf16 v[0:3], v[190:193], v[238:241], v[0:3]
	s_setprio 0
	s_barrier
	s_add_i32 s22, 0, 0x18000
	v_add_u32_e32 v160, s22, v167
	s_add_i32 s23, 0, 0x1c000
	ds_read_b128 v[148:151], v160
	ds_read_b128 v[152:155], v160 offset:1024
	ds_read_b128 v[156:159], v160 offset:2048
	ds_read_b128 v[174:177], v160 offset:3072
	v_add_u32_e32 v160, s23, v167
	ds_read_b128 v[178:181], v160
	ds_read_b128 v[182:185], v160 offset:1024
	ds_read_b128 v[186:189], v160 offset:2048
	ds_read_b128 v[190:193], v160 offset:3072
	s_add_u32 s50, vcc_lo, 0x40000
	s_addc_u32 s51, vcc_hi, 0
	s_mov_b32 m0, s87
	v_lshl_add_u64 v[226:227], s[50:51], 0, v[128:129]
	ds_read_b128 v[194:197], v173 offset:32768
	ds_read_b128 v[198:201], v173 offset:33792
	ds_read_b128 v[202:205], v173 offset:34816
	ds_read_b128 v[206:209], v173 offset:35840
	ds_read_b128 v[210:213], v173 offset:36864
	ds_read_b128 v[222:225], v173 offset:37888
	ds_read_b128 v[234:237], v173 offset:38912
	ds_read_b128 v[238:241], v173 offset:39936
	global_load_lds_dwordx4 v[226:227], off
	v_lshl_add_u64 v[226:227], s[50:51], 0, v[132:133]
	s_mov_b32 m0, s88
	s_nop 0
	global_load_lds_dwordx4 v[226:227], off
	s_waitcnt vmcnt(8)
	s_waitcnt lgkmcnt(0)
	s_barrier
	s_setprio 1
	s_waitcnt lgkmcnt(0)
	v_mfma_f32_16x16x32_bf16 v[124:127], v[148:151], v[194:197], v[124:127]
	v_mfma_f32_16x16x32_bf16 v[120:123], v[156:159], v[194:197], v[120:123]
	v_mfma_f32_16x16x32_bf16 v[108:111], v[148:151], v[202:205], v[108:111]
	v_mfma_f32_16x16x32_bf16 v[104:107], v[156:159], v[202:205], v[104:107]
	v_mfma_f32_16x16x32_bf16 v[92:95], v[148:151], v[210:213], v[92:95]
	v_mfma_f32_16x16x32_bf16 v[88:91], v[156:159], v[210:213], v[88:91]
	v_mfma_f32_16x16x32_bf16 v[76:79], v[148:151], v[234:237], v[76:79]
	v_mfma_f32_16x16x32_bf16 v[72:75], v[156:159], v[234:237], v[72:75]
	v_mfma_f32_16x16x32_bf16 v[124:127], v[152:155], v[198:201], v[124:127]
	v_mfma_f32_16x16x32_bf16 v[120:123], v[174:177], v[198:201], v[120:123]
	v_mfma_f32_16x16x32_bf16 v[108:111], v[152:155], v[206:209], v[108:111]
	v_mfma_f32_16x16x32_bf16 v[104:107], v[174:177], v[206:209], v[104:107]
	v_mfma_f32_16x16x32_bf16 v[92:95], v[152:155], v[222:225], v[92:95]
	v_mfma_f32_16x16x32_bf16 v[88:91], v[174:177], v[222:225], v[88:91]
	v_mfma_f32_16x16x32_bf16 v[76:79], v[152:155], v[238:241], v[76:79]
	v_mfma_f32_16x16x32_bf16 v[72:75], v[174:177], v[238:241], v[72:75]
	v_mfma_f32_16x16x32_bf16 v[116:119], v[178:181], v[194:197], v[116:119]
	v_mfma_f32_16x16x32_bf16 v[112:115], v[186:189], v[194:197], v[112:115]
	v_mfma_f32_16x16x32_bf16 v[100:103], v[178:181], v[202:205], v[100:103]
	v_mfma_f32_16x16x32_bf16 v[96:99], v[186:189], v[202:205], v[96:99]
	v_mfma_f32_16x16x32_bf16 v[84:87], v[178:181], v[210:213], v[84:87]
	v_mfma_f32_16x16x32_bf16 v[80:83], v[186:189], v[210:213], v[80:83]
	v_mfma_f32_16x16x32_bf16 v[68:71], v[178:181], v[234:237], v[68:71]
	v_mfma_f32_16x16x32_bf16 v[64:67], v[186:189], v[234:237], v[64:67]
	v_mfma_f32_16x16x32_bf16 v[116:119], v[182:185], v[198:201], v[116:119]
	v_mfma_f32_16x16x32_bf16 v[112:115], v[190:193], v[198:201], v[112:115]
	v_mfma_f32_16x16x32_bf16 v[100:103], v[182:185], v[206:209], v[100:103]
	v_mfma_f32_16x16x32_bf16 v[96:99], v[190:193], v[206:209], v[96:99]
	v_mfma_f32_16x16x32_bf16 v[84:87], v[182:185], v[222:225], v[84:87]
	v_mfma_f32_16x16x32_bf16 v[80:83], v[190:193], v[222:225], v[80:83]
	v_mfma_f32_16x16x32_bf16 v[68:71], v[182:185], v[238:241], v[68:71]
	v_mfma_f32_16x16x32_bf16 v[64:67], v[190:193], v[238:241], v[64:67]
	s_setprio 0
	s_barrier
	s_add_i32 s22, s22, s80
	v_lshl_add_u64 v[162:163], v[162:163], 0, s[48:49]
	s_mov_b32 m0, s22
	ds_read_b128 v[194:197], v173 offset:49152
	ds_read_b128 v[198:201], v173 offset:50176
	ds_read_b128 v[202:205], v173 offset:51200
	ds_read_b128 v[206:209], v173 offset:52224
	ds_read_b128 v[210:213], v173 offset:53248
	ds_read_b128 v[222:225], v173 offset:54272
	ds_read_b128 v[234:237], v173 offset:55296
	ds_read_b128 v[238:241], v173 offset:56320
	global_load_lds_dwordx4 v[162:163], off
	s_add_i32 m0, s22, 0x2000
	s_add_u32 s50, s82, 0x40080
	v_lshl_add_u64 v[162:163], v[164:165], 0, s[48:49]
	s_addc_u32 s51, s83, 0
	s_add_i32 s22, s23, s80
	global_load_lds_dwordx4 v[162:163], off
	v_lshl_add_u64 v[162:163], s[50:51], 0, v[130:131]
	s_mov_b32 m0, s22
	s_nop 0
	global_load_lds_dwordx4 v[162:163], off
	v_lshl_add_u64 v[162:163], s[50:51], 0, v[134:135]
	s_add_i32 m0, s22, 0x2000
	s_nop 0
	global_load_lds_dwordx4 v[162:163], off
	v_lshl_add_u64 v[162:163], v[170:171], 0, s[48:49]
	s_mov_b32 m0, s90
	s_nop 0
	global_load_lds_dwordx4 v[162:163], off
	v_lshl_add_u64 v[162:163], v[214:215], 0, s[48:49]
	s_mov_b32 m0, s91
	s_nop 0
	global_load_lds_dwordx4 v[162:163], off
	s_waitcnt vmcnt(8)
	s_waitcnt lgkmcnt(0)
	s_barrier
	s_setprio 1
	s_waitcnt lgkmcnt(0)
	v_mfma_f32_16x16x32_bf16 v[60:63], v[148:151], v[194:197], v[60:63]
	v_mfma_f32_16x16x32_bf16 v[56:59], v[156:159], v[194:197], v[56:59]
	v_mfma_f32_16x16x32_bf16 v[44:47], v[148:151], v[202:205], v[44:47]
	v_mfma_f32_16x16x32_bf16 v[40:43], v[156:159], v[202:205], v[40:43]
	v_mfma_f32_16x16x32_bf16 v[28:31], v[148:151], v[210:213], v[28:31]
	v_mfma_f32_16x16x32_bf16 v[24:27], v[156:159], v[210:213], v[24:27]
	v_mfma_f32_16x16x32_bf16 v[12:15], v[148:151], v[234:237], v[12:15]
	v_mfma_f32_16x16x32_bf16 v[8:11], v[156:159], v[234:237], v[8:11]
	v_mfma_f32_16x16x32_bf16 v[60:63], v[152:155], v[198:201], v[60:63]
	v_mfma_f32_16x16x32_bf16 v[56:59], v[174:177], v[198:201], v[56:59]
	v_mfma_f32_16x16x32_bf16 v[44:47], v[152:155], v[206:209], v[44:47]
	v_mfma_f32_16x16x32_bf16 v[40:43], v[174:177], v[206:209], v[40:43]
	v_mfma_f32_16x16x32_bf16 v[28:31], v[152:155], v[222:225], v[28:31]
	v_mfma_f32_16x16x32_bf16 v[24:27], v[174:177], v[222:225], v[24:27]
	v_mfma_f32_16x16x32_bf16 v[12:15], v[152:155], v[238:241], v[12:15]
	v_mfma_f32_16x16x32_bf16 v[8:11], v[174:177], v[238:241], v[8:11]
	v_mfma_f32_16x16x32_bf16 v[52:55], v[178:181], v[194:197], v[52:55]
	v_mfma_f32_16x16x32_bf16 v[48:51], v[186:189], v[194:197], v[48:51]
	v_mfma_f32_16x16x32_bf16 v[36:39], v[178:181], v[202:205], v[36:39]
	v_mfma_f32_16x16x32_bf16 v[32:35], v[186:189], v[202:205], v[32:35]
	v_mfma_f32_16x16x32_bf16 v[20:23], v[178:181], v[210:213], v[20:23]
	v_mfma_f32_16x16x32_bf16 v[16:19], v[186:189], v[210:213], v[16:19]
	v_mfma_f32_16x16x32_bf16 v[4:7], v[178:181], v[234:237], v[4:7]
	v_mfma_f32_16x16x32_bf16 v[0:3], v[186:189], v[234:237], v[0:3]
	v_mfma_f32_16x16x32_bf16 v[52:55], v[182:185], v[198:201], v[52:55]
	v_mfma_f32_16x16x32_bf16 v[48:51], v[190:193], v[198:201], v[48:51]
	v_mfma_f32_16x16x32_bf16 v[36:39], v[182:185], v[206:209], v[36:39]
	v_mfma_f32_16x16x32_bf16 v[32:35], v[190:193], v[206:209], v[32:35]
	v_mfma_f32_16x16x32_bf16 v[20:23], v[182:185], v[222:225], v[20:23]
	v_mfma_f32_16x16x32_bf16 v[16:19], v[190:193], v[222:225], v[16:19]
	v_mfma_f32_16x16x32_bf16 v[4:7], v[182:185], v[238:241], v[4:7]
	v_mfma_f32_16x16x32_bf16 v[0:3], v[190:193], v[238:241], v[0:3]
	s_add_i32 s41, s41, 2
	s_add_u32 s42, s42, 0x100
	s_addc_u32 s43, s43, 0
	s_add_u32 s24, s24, 0x100
	s_addc_u32 s25, s25, 0
	s_cmp_gt_u32 s41, 13
	s_setprio 0
	s_barrier
	s_cbranch_scc0 .LBB0_253
	s_and_b64 vcc, exec, s[12:13]
	s_cbranch_vccz .LBB0_256
	s_barrier

.LBB0_377:
	s_add_u32 s40, s82, 0x80
	s_addc_u32 s41, s83, 0
	s_add_u32 s4, s84, 0x100
	s_addc_u32 s84, s85, 0
	s_mov_b32 s82, 0
	s_add_i32 s85, s82, 2
	s_add_u32 vcc_lo, s40, 0x80
	s_addc_u32 s83, s41, 0
	s_add_i32 s28, 0, 0x10000
	s_cmp_eq_u32 s95, s82
	s_cselect_b32 s83, s19, s83
	s_cselect_b32 s82, s18, vcc_lo
	s_cselect_b32 vcc_hi, s43, s84
	s_cselect_b32 vcc_lo, s42, s4
	s_add_i32 s22, 0, 0x14000
	v_add_u32_e32 v140, s28, v169
	v_add_u32_e32 v162, s22, v169
	ds_read_b128 v[128:131], v140
	ds_read_b128 v[132:135], v140 offset:1024
	ds_read_b128 v[136:139], v140 offset:2048
	ds_read_b128 v[140:143], v140 offset:3072
	ds_read_b128 v[144:147], v162
	ds_read_b128 v[148:151], v162 offset:1024
	ds_read_b128 v[152:155], v162 offset:2048
	ds_read_b128 v[180:183], v162 offset:3072
	v_lshl_add_u64 v[162:163], s[40:41], 0, v[176:177]
	s_add_i32 m0, s86, 0xc000
	ds_read_b128 v[184:187], v205
	ds_read_b128 v[188:191], v205 offset:1024
	ds_read_b128 v[192:195], v205 offset:2048
	ds_read_b128 v[196:199], v205 offset:3072
	ds_read_b128 v[206:209], v205 offset:4096
	ds_read_b128 v[210:213], v205 offset:5120
	ds_read_b128 v[222:225], v205 offset:6144
	ds_read_b128 v[234:237], v205 offset:7168
	global_load_lds_dwordx4 v[162:163], off
	v_lshl_add_u64 v[162:163], s[40:41], 0, v[178:179]
	s_add_i32 m0, s86, 0xe000
	s_nop 0
	global_load_lds_dwordx4 v[162:163], off
	s_waitcnt vmcnt(8)
	s_waitcnt lgkmcnt(0)
	s_barrier
	s_setprio 1
	s_waitcnt lgkmcnt(0)
	v_mfma_f32_16x16x32_bf16 v[124:127], v[128:131], v[184:187], 0
	v_mfma_f32_16x16x32_bf16 v[120:123], v[136:139], v[184:187], 0
	v_mfma_f32_16x16x32_bf16 v[108:111], v[128:131], v[192:195], 0
	v_mfma_f32_16x16x32_bf16 v[104:107], v[136:139], v[192:195], 0
	v_mfma_f32_16x16x32_bf16 v[92:95], v[128:131], v[206:209], 0
	v_mfma_f32_16x16x32_bf16 v[88:91], v[136:139], v[206:209], 0
	v_mfma_f32_16x16x32_bf16 v[76:79], v[128:131], v[222:225], 0
	v_mfma_f32_16x16x32_bf16 v[72:75], v[136:139], v[222:225], 0
	v_mfma_f32_16x16x32_bf16 v[124:127], v[132:135], v[188:191], v[124:127]
	v_mfma_f32_16x16x32_bf16 v[120:123], v[140:143], v[188:191], v[120:123]
	v_mfma_f32_16x16x32_bf16 v[108:111], v[132:135], v[196:199], v[108:111]
	v_mfma_f32_16x16x32_bf16 v[104:107], v[140:143], v[196:199], v[104:107]
	v_mfma_f32_16x16x32_bf16 v[92:95], v[132:135], v[210:213], v[92:95]
	v_mfma_f32_16x16x32_bf16 v[88:91], v[140:143], v[210:213], v[88:91]
	v_mfma_f32_16x16x32_bf16 v[76:79], v[132:135], v[234:237], v[76:79]
	v_mfma_f32_16x16x32_bf16 v[72:75], v[140:143], v[234:237], v[72:75]
	v_mfma_f32_16x16x32_bf16 v[116:119], v[144:147], v[184:187], 0
	v_mfma_f32_16x16x32_bf16 v[112:115], v[152:155], v[184:187], 0
	v_mfma_f32_16x16x32_bf16 v[100:103], v[144:147], v[192:195], 0
	v_mfma_f32_16x16x32_bf16 v[96:99], v[152:155], v[192:195], 0
	v_mfma_f32_16x16x32_bf16 v[84:87], v[144:147], v[206:209], 0
	v_mfma_f32_16x16x32_bf16 v[80:83], v[152:155], v[206:209], 0
	v_mfma_f32_16x16x32_bf16 v[68:71], v[144:147], v[222:225], 0
	v_mfma_f32_16x16x32_bf16 v[64:67], v[152:155], v[222:225], 0
	v_mfma_f32_16x16x32_bf16 v[116:119], v[148:151], v[188:191], v[116:119]
	v_mfma_f32_16x16x32_bf16 v[112:115], v[180:183], v[188:191], v[112:115]
	v_mfma_f32_16x16x32_bf16 v[100:103], v[148:151], v[196:199], v[100:103]
	v_mfma_f32_16x16x32_bf16 v[96:99], v[180:183], v[196:199], v[96:99]
	v_mfma_f32_16x16x32_bf16 v[84:87], v[148:151], v[210:213], v[84:87]
	v_mfma_f32_16x16x32_bf16 v[80:83], v[180:183], v[210:213], v[80:83]
	v_mfma_f32_16x16x32_bf16 v[68:71], v[148:151], v[234:237], v[68:71]
	v_mfma_f32_16x16x32_bf16 v[64:67], v[180:183], v[234:237], v[64:67]
	s_setprio 0
	s_barrier
	s_add_i32 s23, s28, s81
	v_lshl_add_u64 v[162:163], vcc, 0, v[160:161]
	s_mov_b32 m0, s23
	ds_read_b128 v[184:187], v205 offset:16384
	ds_read_b128 v[188:191], v205 offset:17408
	ds_read_b128 v[192:195], v205 offset:18432
	ds_read_b128 v[196:199], v205 offset:19456
	ds_read_b128 v[206:209], v205 offset:20480
	ds_read_b128 v[210:213], v205 offset:21504
	ds_read_b128 v[222:225], v205 offset:22528
	ds_read_b128 v[234:237], v205 offset:23552
	global_load_lds_dwordx4 v[162:163], off
	s_add_i32 m0, s23, 0x2000
	v_lshl_add_u64 v[164:165], vcc, 0, v[170:171]
	s_add_u32 vcc_lo, vcc_lo, s8
	s_addc_u32 vcc_hi, vcc_hi, 0
	s_add_i32 s22, s22, s81
	global_load_lds_dwordx4 v[164:165], off
	v_lshl_add_u64 v[200:201], vcc, 0, v[160:161]
	s_mov_b32 m0, s22
	v_lshl_add_u64 v[214:215], vcc, 0, v[170:171]
	global_load_lds_dwordx4 v[200:201], off
	s_add_i32 m0, s22, 0x2000
	v_lshl_add_u64 v[226:227], s[82:83], 0, v[156:157]
	global_load_lds_dwordx4 v[214:215], off
	s_mov_b32 m0, s86
	v_lshl_add_u64 v[238:239], s[82:83], 0, v[158:159]
	global_load_lds_dwordx4 v[226:227], off
	s_mov_b32 m0, s87
	s_nop 0
	global_load_lds_dwordx4 v[238:239], off
	s_waitcnt vmcnt(8)
	s_waitcnt lgkmcnt(0)
	s_barrier
	s_setprio 1
	s_waitcnt lgkmcnt(0)
	v_mfma_f32_16x16x32_bf16 v[60:63], v[128:131], v[184:187], 0
	v_mfma_f32_16x16x32_bf16 v[56:59], v[136:139], v[184:187], 0
	v_mfma_f32_16x16x32_bf16 v[44:47], v[128:131], v[192:195], 0
	v_mfma_f32_16x16x32_bf16 v[40:43], v[136:139], v[192:195], 0
	v_mfma_f32_16x16x32_bf16 v[28:31], v[128:131], v[206:209], 0
	v_mfma_f32_16x16x32_bf16 v[24:27], v[136:139], v[206:209], 0
	v_mfma_f32_16x16x32_bf16 v[12:15], v[128:131], v[222:225], 0
	v_mfma_f32_16x16x32_bf16 v[8:11], v[136:139], v[222:225], 0
	v_mfma_f32_16x16x32_bf16 v[60:63], v[132:135], v[188:191], v[60:63]
	v_mfma_f32_16x16x32_bf16 v[56:59], v[140:143], v[188:191], v[56:59]
	v_mfma_f32_16x16x32_bf16 v[44:47], v[132:135], v[196:199], v[44:47]
	v_mfma_f32_16x16x32_bf16 v[40:43], v[140:143], v[196:199], v[40:43]
	v_mfma_f32_16x16x32_bf16 v[28:31], v[132:135], v[210:213], v[28:31]
	v_mfma_f32_16x16x32_bf16 v[24:27], v[140:143], v[210:213], v[24:27]
	v_mfma_f32_16x16x32_bf16 v[12:15], v[132:135], v[234:237], v[12:15]
	v_mfma_f32_16x16x32_bf16 v[8:11], v[140:143], v[234:237], v[8:11]
	v_mfma_f32_16x16x32_bf16 v[52:55], v[144:147], v[184:187], 0
	v_mfma_f32_16x16x32_bf16 v[48:51], v[152:155], v[184:187], 0
	v_mfma_f32_16x16x32_bf16 v[36:39], v[144:147], v[192:195], 0
	v_mfma_f32_16x16x32_bf16 v[32:35], v[152:155], v[192:195], 0
	v_mfma_f32_16x16x32_bf16 v[20:23], v[144:147], v[206:209], 0
	v_mfma_f32_16x16x32_bf16 v[16:19], v[152:155], v[206:209], 0
	v_mfma_f32_16x16x32_bf16 v[4:7], v[144:147], v[222:225], 0
	v_mfma_f32_16x16x32_bf16 v[0:3], v[152:155], v[222:225], 0
	v_mfma_f32_16x16x32_bf16 v[52:55], v[148:151], v[188:191], v[52:55]
	v_mfma_f32_16x16x32_bf16 v[48:51], v[180:183], v[188:191], v[48:51]
	v_mfma_f32_16x16x32_bf16 v[36:39], v[148:151], v[196:199], v[36:39]
	v_mfma_f32_16x16x32_bf16 v[32:35], v[180:183], v[196:199], v[32:35]
	v_mfma_f32_16x16x32_bf16 v[20:23], v[148:151], v[210:213], v[20:23]
	v_mfma_f32_16x16x32_bf16 v[16:19], v[180:183], v[210:213], v[16:19]
	v_mfma_f32_16x16x32_bf16 v[4:7], v[148:151], v[234:237], v[4:7]
	v_mfma_f32_16x16x32_bf16 v[0:3], v[180:183], v[234:237], v[0:3]
	s_setprio 0
	s_barrier
	s_add_i32 s22, 0, 0x18000
	s_add_i32 s23, 0, 0x1c000
	v_add_u32_e32 v140, s22, v169
	v_add_u32_e32 v173, s23, v169
	ds_read_b128 v[128:131], v140
	ds_read_b128 v[132:135], v140 offset:1024
	ds_read_b128 v[136:139], v140 offset:2048
	ds_read_b128 v[140:143], v140 offset:3072
	ds_read_b128 v[144:147], v173
	ds_read_b128 v[148:151], v173 offset:1024
	ds_read_b128 v[152:155], v173 offset:2048
	ds_read_b128 v[180:183], v173 offset:3072
	s_add_u32 s82, s82, s8
	s_addc_u32 s83, s83, 0
	s_mov_b32 m0, s88
	v_lshl_add_u64 v[240:241], s[82:83], 0, v[156:157]
	ds_read_b128 v[184:187], v205 offset:32768
	ds_read_b128 v[188:191], v205 offset:33792
	ds_read_b128 v[192:195], v205 offset:34816
	ds_read_b128 v[196:199], v205 offset:35840
	ds_read_b128 v[206:209], v205 offset:36864
	ds_read_b128 v[210:213], v205 offset:37888
	ds_read_b128 v[222:225], v205 offset:38912
	ds_read_b128 v[234:237], v205 offset:39936
	global_load_lds_dwordx4 v[240:241], off
	v_lshl_add_u64 v[240:241], s[82:83], 0, v[158:159]
	s_mov_b32 m0, s89
	s_nop 0
	global_load_lds_dwordx4 v[240:241], off
	s_waitcnt vmcnt(8)
	s_waitcnt lgkmcnt(0)
	s_barrier
	s_setprio 1
	s_waitcnt lgkmcnt(0)
	v_mfma_f32_16x16x32_bf16 v[124:127], v[128:131], v[184:187], v[124:127]
	v_mfma_f32_16x16x32_bf16 v[120:123], v[136:139], v[184:187], v[120:123]
	v_mfma_f32_16x16x32_bf16 v[108:111], v[128:131], v[192:195], v[108:111]
	v_mfma_f32_16x16x32_bf16 v[104:107], v[136:139], v[192:195], v[104:107]
	v_mfma_f32_16x16x32_bf16 v[92:95], v[128:131], v[206:209], v[92:95]
	v_mfma_f32_16x16x32_bf16 v[88:91], v[136:139], v[206:209], v[88:91]
	v_mfma_f32_16x16x32_bf16 v[76:79], v[128:131], v[222:225], v[76:79]
	v_mfma_f32_16x16x32_bf16 v[72:75], v[136:139], v[222:225], v[72:75]
	v_mfma_f32_16x16x32_bf16 v[124:127], v[132:135], v[188:191], v[124:127]
	v_mfma_f32_16x16x32_bf16 v[120:123], v[140:143], v[188:191], v[120:123]
	v_mfma_f32_16x16x32_bf16 v[108:111], v[132:135], v[196:199], v[108:111]
	v_mfma_f32_16x16x32_bf16 v[104:107], v[140:143], v[196:199], v[104:107]
	v_mfma_f32_16x16x32_bf16 v[92:95], v[132:135], v[210:213], v[92:95]
	v_mfma_f32_16x16x32_bf16 v[88:91], v[140:143], v[210:213], v[88:91]
	v_mfma_f32_16x16x32_bf16 v[76:79], v[132:135], v[234:237], v[76:79]
	v_mfma_f32_16x16x32_bf16 v[72:75], v[140:143], v[234:237], v[72:75]
	v_mfma_f32_16x16x32_bf16 v[116:119], v[144:147], v[184:187], v[116:119]
	v_mfma_f32_16x16x32_bf16 v[112:115], v[152:155], v[184:187], v[112:115]
	v_mfma_f32_16x16x32_bf16 v[100:103], v[144:147], v[192:195], v[100:103]
	v_mfma_f32_16x16x32_bf16 v[96:99], v[152:155], v[192:195], v[96:99]
	v_mfma_f32_16x16x32_bf16 v[84:87], v[144:147], v[206:209], v[84:87]
	v_mfma_f32_16x16x32_bf16 v[80:83], v[152:155], v[206:209], v[80:83]
	v_mfma_f32_16x16x32_bf16 v[68:71], v[144:147], v[222:225], v[68:71]
	v_mfma_f32_16x16x32_bf16 v[64:67], v[152:155], v[222:225], v[64:67]
	v_mfma_f32_16x16x32_bf16 v[116:119], v[148:151], v[188:191], v[116:119]
	v_mfma_f32_16x16x32_bf16 v[112:115], v[180:183], v[188:191], v[112:115]
	v_mfma_f32_16x16x32_bf16 v[100:103], v[148:151], v[196:199], v[100:103]
	v_mfma_f32_16x16x32_bf16 v[96:99], v[180:183], v[196:199], v[96:99]
	v_mfma_f32_16x16x32_bf16 v[84:87], v[148:151], v[210:213], v[84:87]
	v_mfma_f32_16x16x32_bf16 v[80:83], v[180:183], v[210:213], v[80:83]
	v_mfma_f32_16x16x32_bf16 v[68:71], v[148:151], v[234:237], v[68:71]
	v_mfma_f32_16x16x32_bf16 v[64:67], v[180:183], v[234:237], v[64:67]
	s_setprio 0
	s_barrier
	s_add_i32 s22, s22, s81
	v_lshl_add_u64 v[162:163], v[162:163], 0, s[48:49]
	s_mov_b32 m0, s22
	ds_read_b128 v[184:187], v205 offset:49152
	ds_read_b128 v[188:191], v205 offset:50176
	ds_read_b128 v[192:195], v205 offset:51200
	ds_read_b128 v[196:199], v205 offset:52224
	ds_read_b128 v[206:209], v205 offset:53248
	ds_read_b128 v[210:213], v205 offset:54272
	ds_read_b128 v[222:225], v205 offset:55296
	ds_read_b128 v[234:237], v205 offset:56320
	global_load_lds_dwordx4 v[162:163], off
	v_lshl_add_u64 v[162:163], v[164:165], 0, s[48:49]
	s_add_i32 m0, s22, 0x2000
	s_add_i32 s22, s23, s81
	global_load_lds_dwordx4 v[162:163], off
	v_lshl_add_u64 v[162:163], v[200:201], 0, s[48:49]
	s_mov_b32 m0, s22
	s_nop 0
	global_load_lds_dwordx4 v[162:163], off
	v_lshl_add_u64 v[162:163], v[214:215], 0, s[48:49]
	s_add_i32 m0, s22, 0x2000
	s_nop 0
	global_load_lds_dwordx4 v[162:163], off
	v_lshl_add_u64 v[162:163], v[226:227], 0, s[48:49]
	s_mov_b32 m0, s90
	s_nop 0
	global_load_lds_dwordx4 v[162:163], off
	v_lshl_add_u64 v[162:163], v[238:239], 0, s[48:49]
	s_mov_b32 m0, s91
	s_nop 0
	global_load_lds_dwordx4 v[162:163], off
	s_waitcnt vmcnt(8)
	s_waitcnt lgkmcnt(0)
	s_barrier
	s_setprio 1
	s_waitcnt lgkmcnt(0)
	v_mfma_f32_16x16x32_bf16 v[60:63], v[128:131], v[184:187], v[60:63]
	v_mfma_f32_16x16x32_bf16 v[56:59], v[136:139], v[184:187], v[56:59]
	v_mfma_f32_16x16x32_bf16 v[44:47], v[128:131], v[192:195], v[44:47]
	v_mfma_f32_16x16x32_bf16 v[40:43], v[136:139], v[192:195], v[40:43]
	v_mfma_f32_16x16x32_bf16 v[28:31], v[128:131], v[206:209], v[28:31]
	v_mfma_f32_16x16x32_bf16 v[24:27], v[136:139], v[206:209], v[24:27]
	v_mfma_f32_16x16x32_bf16 v[12:15], v[128:131], v[222:225], v[12:15]
	v_mfma_f32_16x16x32_bf16 v[8:11], v[136:139], v[222:225], v[8:11]
	v_mfma_f32_16x16x32_bf16 v[60:63], v[132:135], v[188:191], v[60:63]
	v_mfma_f32_16x16x32_bf16 v[56:59], v[140:143], v[188:191], v[56:59]
	v_mfma_f32_16x16x32_bf16 v[44:47], v[132:135], v[196:199], v[44:47]
	v_mfma_f32_16x16x32_bf16 v[40:43], v[140:143], v[196:199], v[40:43]
	v_mfma_f32_16x16x32_bf16 v[28:31], v[132:135], v[210:213], v[28:31]
	v_mfma_f32_16x16x32_bf16 v[24:27], v[140:143], v[210:213], v[24:27]
	v_mfma_f32_16x16x32_bf16 v[12:15], v[132:135], v[234:237], v[12:15]
	v_mfma_f32_16x16x32_bf16 v[8:11], v[140:143], v[234:237], v[8:11]
	v_mfma_f32_16x16x32_bf16 v[52:55], v[144:147], v[184:187], v[52:55]
	v_mfma_f32_16x16x32_bf16 v[48:51], v[152:155], v[184:187], v[48:51]
	v_mfma_f32_16x16x32_bf16 v[36:39], v[144:147], v[192:195], v[36:39]
	v_mfma_f32_16x16x32_bf16 v[32:35], v[152:155], v[192:195], v[32:35]
	v_mfma_f32_16x16x32_bf16 v[20:23], v[144:147], v[206:209], v[20:23]
	v_mfma_f32_16x16x32_bf16 v[16:19], v[152:155], v[206:209], v[16:19]
	v_mfma_f32_16x16x32_bf16 v[4:7], v[144:147], v[222:225], v[4:7]
	v_mfma_f32_16x16x32_bf16 v[0:3], v[152:155], v[222:225], v[0:3]
	v_mfma_f32_16x16x32_bf16 v[52:55], v[148:151], v[188:191], v[52:55]
	v_mfma_f32_16x16x32_bf16 v[48:51], v[180:183], v[188:191], v[48:51]
	v_mfma_f32_16x16x32_bf16 v[36:39], v[148:151], v[196:199], v[36:39]
	v_mfma_f32_16x16x32_bf16 v[32:35], v[180:183], v[196:199], v[32:35]
	v_mfma_f32_16x16x32_bf16 v[20:23], v[148:151], v[210:213], v[20:23]
	v_mfma_f32_16x16x32_bf16 v[16:19], v[180:183], v[210:213], v[16:19]
	v_mfma_f32_16x16x32_bf16 v[4:7], v[148:151], v[234:237], v[4:7]
	v_mfma_f32_16x16x32_bf16 v[0:3], v[180:183], v[234:237], v[0:3]
	s_add_u32 s40, s40, 0x100
	s_addc_u32 s41, s41, 0
	s_add_u32 s4, s4, 0x100
	s_addc_u32 s84, s84, 0
	s_cmp_ge_u32 s85, s94
	s_mov_b32 s82, s85
	s_setprio 0
	s_barrier
.LBB0_378:
	s_add_i32 s85, s82, 2
	s_add_u32 vcc_lo, s40, 0x80
	s_addc_u32 s83, s41, 0
	s_add_i32 s28, 0, 0x10000
	s_cmp_eq_u32 s95, s82
	s_cselect_b32 s83, s19, s83
	s_cselect_b32 s82, s18, vcc_lo
	s_cselect_b32 vcc_hi, s43, s84
	s_cselect_b32 vcc_lo, s42, s4
	s_add_i32 s22, 0, 0x14000
	v_add_u32_e32 v140, s28, v169
	v_add_u32_e32 v162, s22, v169
	ds_read_b128 v[128:131], v140
	ds_read_b128 v[132:135], v140 offset:1024
	ds_read_b128 v[136:139], v140 offset:2048
	ds_read_b128 v[140:143], v140 offset:3072
	ds_read_b128 v[144:147], v162
	ds_read_b128 v[148:151], v162 offset:1024
	ds_read_b128 v[152:155], v162 offset:2048
	ds_read_b128 v[180:183], v162 offset:3072
	v_lshl_add_u64 v[162:163], s[40:41], 0, v[176:177]
	s_add_i32 m0, s86, 0xc000
	ds_read_b128 v[184:187], v205
	ds_read_b128 v[188:191], v205 offset:1024
	ds_read_b128 v[192:195], v205 offset:2048
	ds_read_b128 v[196:199], v205 offset:3072
	ds_read_b128 v[206:209], v205 offset:4096
	ds_read_b128 v[210:213], v205 offset:5120
	ds_read_b128 v[222:225], v205 offset:6144
	ds_read_b128 v[234:237], v205 offset:7168
	global_load_lds_dwordx4 v[162:163], off
	v_lshl_add_u64 v[162:163], s[40:41], 0, v[178:179]
	s_add_i32 m0, s86, 0xe000
	s_nop 0
	global_load_lds_dwordx4 v[162:163], off
	s_waitcnt vmcnt(8)
	s_waitcnt lgkmcnt(0)
	s_barrier
	s_setprio 1
	s_waitcnt lgkmcnt(0)
	v_mfma_f32_16x16x32_bf16 v[124:127], v[128:131], v[184:187], v[124:127]
	v_mfma_f32_16x16x32_bf16 v[120:123], v[136:139], v[184:187], v[120:123]
	v_mfma_f32_16x16x32_bf16 v[108:111], v[128:131], v[192:195], v[108:111]
	v_mfma_f32_16x16x32_bf16 v[104:107], v[136:139], v[192:195], v[104:107]
	v_mfma_f32_16x16x32_bf16 v[92:95], v[128:131], v[206:209], v[92:95]
	v_mfma_f32_16x16x32_bf16 v[88:91], v[136:139], v[206:209], v[88:91]
	v_mfma_f32_16x16x32_bf16 v[76:79], v[128:131], v[222:225], v[76:79]
	v_mfma_f32_16x16x32_bf16 v[72:75], v[136:139], v[222:225], v[72:75]
	v_mfma_f32_16x16x32_bf16 v[124:127], v[132:135], v[188:191], v[124:127]
	v_mfma_f32_16x16x32_bf16 v[120:123], v[140:143], v[188:191], v[120:123]
	v_mfma_f32_16x16x32_bf16 v[108:111], v[132:135], v[196:199], v[108:111]
	v_mfma_f32_16x16x32_bf16 v[104:107], v[140:143], v[196:199], v[104:107]
	v_mfma_f32_16x16x32_bf16 v[92:95], v[132:135], v[210:213], v[92:95]
	v_mfma_f32_16x16x32_bf16 v[88:91], v[140:143], v[210:213], v[88:91]
	v_mfma_f32_16x16x32_bf16 v[76:79], v[132:135], v[234:237], v[76:79]
	v_mfma_f32_16x16x32_bf16 v[72:75], v[140:143], v[234:237], v[72:75]
	v_mfma_f32_16x16x32_bf16 v[116:119], v[144:147], v[184:187], v[116:119]
	v_mfma_f32_16x16x32_bf16 v[112:115], v[152:155], v[184:187], v[112:115]
	v_mfma_f32_16x16x32_bf16 v[100:103], v[144:147], v[192:195], v[100:103]
	v_mfma_f32_16x16x32_bf16 v[96:99], v[152:155], v[192:195], v[96:99]
	v_mfma_f32_16x16x32_bf16 v[84:87], v[144:147], v[206:209], v[84:87]
	v_mfma_f32_16x16x32_bf16 v[80:83], v[152:155], v[206:209], v[80:83]
	v_mfma_f32_16x16x32_bf16 v[68:71], v[144:147], v[222:225], v[68:71]
	v_mfma_f32_16x16x32_bf16 v[64:67], v[152:155], v[222:225], v[64:67]
	v_mfma_f32_16x16x32_bf16 v[116:119], v[148:151], v[188:191], v[116:119]
	v_mfma_f32_16x16x32_bf16 v[112:115], v[180:183], v[188:191], v[112:115]
	v_mfma_f32_16x16x32_bf16 v[100:103], v[148:151], v[196:199], v[100:103]
	v_mfma_f32_16x16x32_bf16 v[96:99], v[180:183], v[196:199], v[96:99]
	v_mfma_f32_16x16x32_bf16 v[84:87], v[148:151], v[210:213], v[84:87]
	v_mfma_f32_16x16x32_bf16 v[80:83], v[180:183], v[210:213], v[80:83]
	v_mfma_f32_16x16x32_bf16 v[68:71], v[148:151], v[234:237], v[68:71]
	v_mfma_f32_16x16x32_bf16 v[64:67], v[180:183], v[234:237], v[64:67]
	s_setprio 0
	s_barrier
	s_add_i32 s23, s28, s81
	v_lshl_add_u64 v[162:163], vcc, 0, v[160:161]
	s_mov_b32 m0, s23
	ds_read_b128 v[184:187], v205 offset:16384
	ds_read_b128 v[188:191], v205 offset:17408
	ds_read_b128 v[192:195], v205 offset:18432
	ds_read_b128 v[196:199], v205 offset:19456
	ds_read_b128 v[206:209], v205 offset:20480
	ds_read_b128 v[210:213], v205 offset:21504
	ds_read_b128 v[222:225], v205 offset:22528
	ds_read_b128 v[234:237], v205 offset:23552
	global_load_lds_dwordx4 v[162:163], off
	s_add_i32 m0, s23, 0x2000
	v_lshl_add_u64 v[164:165], vcc, 0, v[170:171]
	s_add_u32 vcc_lo, vcc_lo, s8
	s_addc_u32 vcc_hi, vcc_hi, 0
	s_add_i32 s22, s22, s81
	global_load_lds_dwordx4 v[164:165], off
	v_lshl_add_u64 v[200:201], vcc, 0, v[160:161]
	s_mov_b32 m0, s22
	v_lshl_add_u64 v[214:215], vcc, 0, v[170:171]
	global_load_lds_dwordx4 v[200:201], off
	s_add_i32 m0, s22, 0x2000
	v_lshl_add_u64 v[226:227], s[82:83], 0, v[156:157]
	global_load_lds_dwordx4 v[214:215], off
	s_mov_b32 m0, s86
	v_lshl_add_u64 v[238:239], s[82:83], 0, v[158:159]
	global_load_lds_dwordx4 v[226:227], off
	s_mov_b32 m0, s87
	s_nop 0
	global_load_lds_dwordx4 v[238:239], off
	s_waitcnt vmcnt(8)
	s_waitcnt lgkmcnt(0)
	s_barrier
	s_setprio 1
	s_waitcnt lgkmcnt(0)
	v_mfma_f32_16x16x32_bf16 v[60:63], v[128:131], v[184:187], v[60:63]
	v_mfma_f32_16x16x32_bf16 v[56:59], v[136:139], v[184:187], v[56:59]
	v_mfma_f32_16x16x32_bf16 v[44:47], v[128:131], v[192:195], v[44:47]
	v_mfma_f32_16x16x32_bf16 v[40:43], v[136:139], v[192:195], v[40:43]
	v_mfma_f32_16x16x32_bf16 v[28:31], v[128:131], v[206:209], v[28:31]
	v_mfma_f32_16x16x32_bf16 v[24:27], v[136:139], v[206:209], v[24:27]
	v_mfma_f32_16x16x32_bf16 v[12:15], v[128:131], v[222:225], v[12:15]
	v_mfma_f32_16x16x32_bf16 v[8:11], v[136:139], v[222:225], v[8:11]
	v_mfma_f32_16x16x32_bf16 v[60:63], v[132:135], v[188:191], v[60:63]
	v_mfma_f32_16x16x32_bf16 v[56:59], v[140:143], v[188:191], v[56:59]
	v_mfma_f32_16x16x32_bf16 v[44:47], v[132:135], v[196:199], v[44:47]
	v_mfma_f32_16x16x32_bf16 v[40:43], v[140:143], v[196:199], v[40:43]
	v_mfma_f32_16x16x32_bf16 v[28:31], v[132:135], v[210:213], v[28:31]
	v_mfma_f32_16x16x32_bf16 v[24:27], v[140:143], v[210:213], v[24:27]
	v_mfma_f32_16x16x32_bf16 v[12:15], v[132:135], v[234:237], v[12:15]
	v_mfma_f32_16x16x32_bf16 v[8:11], v[140:143], v[234:237], v[8:11]
	v_mfma_f32_16x16x32_bf16 v[52:55], v[144:147], v[184:187], v[52:55]
	v_mfma_f32_16x16x32_bf16 v[48:51], v[152:155], v[184:187], v[48:51]
	v_mfma_f32_16x16x32_bf16 v[36:39], v[144:147], v[192:195], v[36:39]
	v_mfma_f32_16x16x32_bf16 v[32:35], v[152:155], v[192:195], v[32:35]
	v_mfma_f32_16x16x32_bf16 v[20:23], v[144:147], v[206:209], v[20:23]
	v_mfma_f32_16x16x32_bf16 v[16:19], v[152:155], v[206:209], v[16:19]
	v_mfma_f32_16x16x32_bf16 v[4:7], v[144:147], v[222:225], v[4:7]
	v_mfma_f32_16x16x32_bf16 v[0:3], v[152:155], v[222:225], v[0:3]
	v_mfma_f32_16x16x32_bf16 v[52:55], v[148:151], v[188:191], v[52:55]
	v_mfma_f32_16x16x32_bf16 v[48:51], v[180:183], v[188:191], v[48:51]
	v_mfma_f32_16x16x32_bf16 v[36:39], v[148:151], v[196:199], v[36:39]
	v_mfma_f32_16x16x32_bf16 v[32:35], v[180:183], v[196:199], v[32:35]
	v_mfma_f32_16x16x32_bf16 v[20:23], v[148:151], v[210:213], v[20:23]
	v_mfma_f32_16x16x32_bf16 v[16:19], v[180:183], v[210:213], v[16:19]
	v_mfma_f32_16x16x32_bf16 v[4:7], v[148:151], v[234:237], v[4:7]
	v_mfma_f32_16x16x32_bf16 v[0:3], v[180:183], v[234:237], v[0:3]
	s_setprio 0
	s_barrier
	s_add_i32 s22, 0, 0x18000
	s_add_i32 s23, 0, 0x1c000
	v_add_u32_e32 v140, s22, v169
	v_add_u32_e32 v173, s23, v169
	ds_read_b128 v[128:131], v140
	ds_read_b128 v[132:135], v140 offset:1024
	ds_read_b128 v[136:139], v140 offset:2048
	ds_read_b128 v[140:143], v140 offset:3072
	ds_read_b128 v[144:147], v173
	ds_read_b128 v[148:151], v173 offset:1024
	ds_read_b128 v[152:155], v173 offset:2048
	ds_read_b128 v[180:183], v173 offset:3072
	s_add_u32 s82, s82, s8
	s_addc_u32 s83, s83, 0
	s_mov_b32 m0, s88
	v_lshl_add_u64 v[240:241], s[82:83], 0, v[156:157]
	ds_read_b128 v[184:187], v205 offset:32768
	ds_read_b128 v[188:191], v205 offset:33792
	ds_read_b128 v[192:195], v205 offset:34816
	ds_read_b128 v[196:199], v205 offset:35840
	ds_read_b128 v[206:209], v205 offset:36864
	ds_read_b128 v[210:213], v205 offset:37888
	ds_read_b128 v[222:225], v205 offset:38912
	ds_read_b128 v[234:237], v205 offset:39936
	global_load_lds_dwordx4 v[240:241], off
	v_lshl_add_u64 v[240:241], s[82:83], 0, v[158:159]
	s_mov_b32 m0, s89
	s_nop 0
	global_load_lds_dwordx4 v[240:241], off
	s_waitcnt vmcnt(8)
	s_waitcnt lgkmcnt(0)
	s_barrier
	s_setprio 1
	s_waitcnt lgkmcnt(0)
	v_mfma_f32_16x16x32_bf16 v[124:127], v[128:131], v[184:187], v[124:127]
	v_mfma_f32_16x16x32_bf16 v[120:123], v[136:139], v[184:187], v[120:123]
	v_mfma_f32_16x16x32_bf16 v[108:111], v[128:131], v[192:195], v[108:111]
	v_mfma_f32_16x16x32_bf16 v[104:107], v[136:139], v[192:195], v[104:107]
	v_mfma_f32_16x16x32_bf16 v[92:95], v[128:131], v[206:209], v[92:95]
	v_mfma_f32_16x16x32_bf16 v[88:91], v[136:139], v[206:209], v[88:91]
	v_mfma_f32_16x16x32_bf16 v[76:79], v[128:131], v[222:225], v[76:79]
	v_mfma_f32_16x16x32_bf16 v[72:75], v[136:139], v[222:225], v[72:75]
	v_mfma_f32_16x16x32_bf16 v[124:127], v[132:135], v[188:191], v[124:127]
	v_mfma_f32_16x16x32_bf16 v[120:123], v[140:143], v[188:191], v[120:123]
	v_mfma_f32_16x16x32_bf16 v[108:111], v[132:135], v[196:199], v[108:111]
	v_mfma_f32_16x16x32_bf16 v[104:107], v[140:143], v[196:199], v[104:107]
	v_mfma_f32_16x16x32_bf16 v[92:95], v[132:135], v[210:213], v[92:95]
	v_mfma_f32_16x16x32_bf16 v[88:91], v[140:143], v[210:213], v[88:91]
	v_mfma_f32_16x16x32_bf16 v[76:79], v[132:135], v[234:237], v[76:79]
	v_mfma_f32_16x16x32_bf16 v[72:75], v[140:143], v[234:237], v[72:75]
	v_mfma_f32_16x16x32_bf16 v[116:119], v[144:147], v[184:187], v[116:119]
	v_mfma_f32_16x16x32_bf16 v[112:115], v[152:155], v[184:187], v[112:115]
	v_mfma_f32_16x16x32_bf16 v[100:103], v[144:147], v[192:195], v[100:103]
	v_mfma_f32_16x16x32_bf16 v[96:99], v[152:155], v[192:195], v[96:99]
	v_mfma_f32_16x16x32_bf16 v[84:87], v[144:147], v[206:209], v[84:87]
	v_mfma_f32_16x16x32_bf16 v[80:83], v[152:155], v[206:209], v[80:83]
	v_mfma_f32_16x16x32_bf16 v[68:71], v[144:147], v[222:225], v[68:71]
	v_mfma_f32_16x16x32_bf16 v[64:67], v[152:155], v[222:225], v[64:67]
	v_mfma_f32_16x16x32_bf16 v[116:119], v[148:151], v[188:191], v[116:119]
	v_mfma_f32_16x16x32_bf16 v[112:115], v[180:183], v[188:191], v[112:115]
	v_mfma_f32_16x16x32_bf16 v[100:103], v[148:151], v[196:199], v[100:103]
	v_mfma_f32_16x16x32_bf16 v[96:99], v[180:183], v[196:199], v[96:99]
	v_mfma_f32_16x16x32_bf16 v[84:87], v[148:151], v[210:213], v[84:87]
	v_mfma_f32_16x16x32_bf16 v[80:83], v[180:183], v[210:213], v[80:83]
	v_mfma_f32_16x16x32_bf16 v[68:71], v[148:151], v[234:237], v[68:71]
	v_mfma_f32_16x16x32_bf16 v[64:67], v[180:183], v[234:237], v[64:67]
	s_setprio 0
	s_barrier
	s_add_i32 s22, s22, s81
	v_lshl_add_u64 v[162:163], v[162:163], 0, s[48:49]
	s_mov_b32 m0, s22
	ds_read_b128 v[184:187], v205 offset:49152
	ds_read_b128 v[188:191], v205 offset:50176
	ds_read_b128 v[192:195], v205 offset:51200
	ds_read_b128 v[196:199], v205 offset:52224
	ds_read_b128 v[206:209], v205 offset:53248
	ds_read_b128 v[210:213], v205 offset:54272
	ds_read_b128 v[222:225], v205 offset:55296
	ds_read_b128 v[234:237], v205 offset:56320
	global_load_lds_dwordx4 v[162:163], off
	v_lshl_add_u64 v[162:163], v[164:165], 0, s[48:49]
	s_add_i32 m0, s22, 0x2000
	s_add_i32 s22, s23, s81
	global_load_lds_dwordx4 v[162:163], off
	v_lshl_add_u64 v[162:163], v[200:201], 0, s[48:49]
	s_mov_b32 m0, s22
	s_nop 0
	global_load_lds_dwordx4 v[162:163], off
	v_lshl_add_u64 v[162:163], v[214:215], 0, s[48:49]
	s_add_i32 m0, s22, 0x2000
	s_nop 0
	global_load_lds_dwordx4 v[162:163], off
	v_lshl_add_u64 v[162:163], v[226:227], 0, s[48:49]
	s_mov_b32 m0, s90
	s_nop 0
	global_load_lds_dwordx4 v[162:163], off
	v_lshl_add_u64 v[162:163], v[238:239], 0, s[48:49]
	s_mov_b32 m0, s91
	s_nop 0
	global_load_lds_dwordx4 v[162:163], off
	s_waitcnt vmcnt(8)
	s_waitcnt lgkmcnt(0)
	s_barrier
	s_setprio 1
	s_waitcnt lgkmcnt(0)
	v_mfma_f32_16x16x32_bf16 v[60:63], v[128:131], v[184:187], v[60:63]
	v_mfma_f32_16x16x32_bf16 v[56:59], v[136:139], v[184:187], v[56:59]
	v_mfma_f32_16x16x32_bf16 v[44:47], v[128:131], v[192:195], v[44:47]
	v_mfma_f32_16x16x32_bf16 v[40:43], v[136:139], v[192:195], v[40:43]
	v_mfma_f32_16x16x32_bf16 v[28:31], v[128:131], v[206:209], v[28:31]
	v_mfma_f32_16x16x32_bf16 v[24:27], v[136:139], v[206:209], v[24:27]
	v_mfma_f32_16x16x32_bf16 v[12:15], v[128:131], v[222:225], v[12:15]
	v_mfma_f32_16x16x32_bf16 v[8:11], v[136:139], v[222:225], v[8:11]
	v_mfma_f32_16x16x32_bf16 v[60:63], v[132:135], v[188:191], v[60:63]
	v_mfma_f32_16x16x32_bf16 v[56:59], v[140:143], v[188:191], v[56:59]
	v_mfma_f32_16x16x32_bf16 v[44:47], v[132:135], v[196:199], v[44:47]
	v_mfma_f32_16x16x32_bf16 v[40:43], v[140:143], v[196:199], v[40:43]
	v_mfma_f32_16x16x32_bf16 v[28:31], v[132:135], v[210:213], v[28:31]
	v_mfma_f32_16x16x32_bf16 v[24:27], v[140:143], v[210:213], v[24:27]
	v_mfma_f32_16x16x32_bf16 v[12:15], v[132:135], v[234:237], v[12:15]
	v_mfma_f32_16x16x32_bf16 v[8:11], v[140:143], v[234:237], v[8:11]
	v_mfma_f32_16x16x32_bf16 v[52:55], v[144:147], v[184:187], v[52:55]
	v_mfma_f32_16x16x32_bf16 v[48:51], v[152:155], v[184:187], v[48:51]
	v_mfma_f32_16x16x32_bf16 v[36:39], v[144:147], v[192:195], v[36:39]
	v_mfma_f32_16x16x32_bf16 v[32:35], v[152:155], v[192:195], v[32:35]
	v_mfma_f32_16x16x32_bf16 v[20:23], v[144:147], v[206:209], v[20:23]
	v_mfma_f32_16x16x32_bf16 v[16:19], v[152:155], v[206:209], v[16:19]
	v_mfma_f32_16x16x32_bf16 v[4:7], v[144:147], v[222:225], v[4:7]
	v_mfma_f32_16x16x32_bf16 v[0:3], v[152:155], v[222:225], v[0:3]
	v_mfma_f32_16x16x32_bf16 v[52:55], v[148:151], v[188:191], v[52:55]
	v_mfma_f32_16x16x32_bf16 v[48:51], v[180:183], v[188:191], v[48:51]
	v_mfma_f32_16x16x32_bf16 v[36:39], v[148:151], v[196:199], v[36:39]
	v_mfma_f32_16x16x32_bf16 v[32:35], v[180:183], v[196:199], v[32:35]
	v_mfma_f32_16x16x32_bf16 v[20:23], v[148:151], v[210:213], v[20:23]
	v_mfma_f32_16x16x32_bf16 v[16:19], v[180:183], v[210:213], v[16:19]
	v_mfma_f32_16x16x32_bf16 v[4:7], v[148:151], v[234:237], v[4:7]
	v_mfma_f32_16x16x32_bf16 v[0:3], v[180:183], v[234:237], v[0:3]
	s_add_u32 s40, s40, 0x100
	s_addc_u32 s41, s41, 0
	s_add_u32 s4, s4, 0x100
	s_addc_u32 s84, s84, 0
	s_cmp_ge_u32 s85, s94
	s_mov_b32 s82, s85
	s_setprio 0
	s_barrier
	s_cbranch_scc0 .LBB0_378
	s_and_b64 vcc, exec, s[14:15]
	s_cbranch_vccz .LBB0_381
	s_barrier

.LBB0_477:
	s_ashr_i32 s17, s16, 31
	s_lshl_b64 s[18:19], s[16:17], 19
	s_add_u32 s18, s0, s18
	s_addc_u32 s19, s1, s19
	s_and_b64 s[24:25], s[38:39], exec
	s_cselect_b32 s4, s19, s41
	s_cselect_b32 s9, s18, s40
	s_ashr_i32 s85, s84, 31
	s_lshl_b64 s[24:25], s[84:85], 19
	s_add_u32 s82, s80, s24
	s_addc_u32 s83, s81, s25
	s_and_b64 s[24:25], s[38:39], exec
	s_cselect_b32 s17, s83, s13
	s_cselect_b32 s24, s82, s12
	s_add_u32 s40, s40, 0x40080
	s_addc_u32 s41, s41, 0
	s_add_u32 s25, s12, 0x100
	s_addc_u32 s50, s13, 0
	s_mov_b32 s51, -2
	s_add_u32 s12, s40, 0xfffc0080
	s_addc_u32 s13, s41, -1
	s_add_i32 s85, 0, 0x10000
	s_cmp_eq_u32 s51, 12
	s_cselect_b32 s43, s4, s13
	s_cselect_b32 s42, s9, s12
	v_add_u32_e32 v158, s85, v196
	s_cselect_b32 s13, s17, s50
	s_cselect_b32 s12, s24, s25
	s_add_i32 s27, 0, 0x14000
	ds_read_b128 v[150:153], v158
	ds_read_b128 v[154:157], v158 offset:1024
	ds_read_b128 v[170:173], v158 offset:2048
	ds_read_b128 v[174:177], v158 offset:3072
	v_add_u32_e32 v158, s27, v196
	ds_read_b128 v[178:181], v158
	ds_read_b128 v[182:185], v158 offset:1024
	ds_read_b128 v[186:189], v158 offset:2048
	ds_read_b128 v[200:203], v158 offset:3072
	s_add_i32 m0, s15, 0xc000
	ds_read_b128 v[204:207], v199
	ds_read_b128 v[208:211], v199 offset:1024
	ds_read_b128 v[212:215], v199 offset:2048
	ds_read_b128 v[234:237], v199 offset:3072
	ds_read_b128 v[238:241], v199 offset:4096
	ds_read_b128 v[242:245], v199 offset:5120
	ds_read_b128 v[246:249], v199 offset:6144
	ds_read_b128 v[222:225], v199 offset:7168
	global_load_lds_dwordx4 v146, s[40:41]
	s_add_i32 m0, s15, 0xe000
	s_nop 0
	global_load_lds_dwordx4 v148, s[40:41]
	s_waitcnt vmcnt(8)
	s_waitcnt lgkmcnt(0)
	s_barrier
	s_setprio 1
	s_waitcnt lgkmcnt(0)
	v_mfma_f32_16x16x32_bf16 v[124:127], v[150:153], v[204:207], 0
	v_mfma_f32_16x16x32_bf16 v[120:123], v[170:173], v[204:207], 0
	v_mfma_f32_16x16x32_bf16 v[108:111], v[150:153], v[212:215], 0
	v_mfma_f32_16x16x32_bf16 v[104:107], v[170:173], v[212:215], 0
	v_mfma_f32_16x16x32_bf16 v[92:95], v[150:153], v[238:241], 0
	v_mfma_f32_16x16x32_bf16 v[88:91], v[170:173], v[238:241], 0
	v_mfma_f32_16x16x32_bf16 v[76:79], v[150:153], v[246:249], 0
	v_mfma_f32_16x16x32_bf16 v[72:75], v[170:173], v[246:249], 0
	v_mfma_f32_16x16x32_bf16 v[124:127], v[154:157], v[208:211], v[124:127]
	v_mfma_f32_16x16x32_bf16 v[120:123], v[174:177], v[208:211], v[120:123]
	v_mfma_f32_16x16x32_bf16 v[108:111], v[154:157], v[234:237], v[108:111]
	v_mfma_f32_16x16x32_bf16 v[104:107], v[174:177], v[234:237], v[104:107]
	v_mfma_f32_16x16x32_bf16 v[92:95], v[154:157], v[242:245], v[92:95]
	v_mfma_f32_16x16x32_bf16 v[88:91], v[174:177], v[242:245], v[88:91]
	v_mfma_f32_16x16x32_bf16 v[76:79], v[154:157], v[222:225], v[76:79]
	v_mfma_f32_16x16x32_bf16 v[72:75], v[174:177], v[222:225], v[72:75]
	v_mfma_f32_16x16x32_bf16 v[116:119], v[178:181], v[204:207], 0
	v_mfma_f32_16x16x32_bf16 v[112:115], v[186:189], v[204:207], 0
	v_mfma_f32_16x16x32_bf16 v[100:103], v[178:181], v[212:215], 0
	v_mfma_f32_16x16x32_bf16 v[96:99], v[186:189], v[212:215], 0
	v_mfma_f32_16x16x32_bf16 v[84:87], v[178:181], v[238:241], 0
	v_mfma_f32_16x16x32_bf16 v[80:83], v[186:189], v[238:241], 0
	v_mfma_f32_16x16x32_bf16 v[68:71], v[178:181], v[246:249], 0
	v_mfma_f32_16x16x32_bf16 v[64:67], v[186:189], v[246:249], 0
	v_mfma_f32_16x16x32_bf16 v[116:119], v[182:185], v[208:211], v[116:119]
	v_mfma_f32_16x16x32_bf16 v[112:115], v[200:203], v[208:211], v[112:115]
	v_mfma_f32_16x16x32_bf16 v[100:103], v[182:185], v[234:237], v[100:103]
	v_mfma_f32_16x16x32_bf16 v[96:99], v[200:203], v[234:237], v[96:99]
	v_mfma_f32_16x16x32_bf16 v[84:87], v[182:185], v[242:245], v[84:87]
	v_mfma_f32_16x16x32_bf16 v[80:83], v[200:203], v[242:245], v[80:83]
	v_mfma_f32_16x16x32_bf16 v[68:71], v[182:185], v[222:225], v[68:71]
	v_mfma_f32_16x16x32_bf16 v[64:67], v[200:203], v[222:225], v[64:67]
	s_setprio 0
	s_barrier
	s_add_i32 s85, s85, s86
	s_mov_b32 m0, s85
	ds_read_b128 v[204:207], v199 offset:16384
	ds_read_b128 v[208:211], v199 offset:17408
	ds_read_b128 v[212:215], v199 offset:18432
	ds_read_b128 v[222:225], v199 offset:19456
	ds_read_b128 v[234:237], v199 offset:20480
	ds_read_b128 v[238:241], v199 offset:21504
	ds_read_b128 v[242:245], v199 offset:22528
	ds_read_b128 v[246:249], v199 offset:23552
	global_load_lds_dwordx4 v130, s[12:13]
	s_add_i32 m0, s85, 0x2000
	s_add_u32 s98, s12, 0x40000
	s_addc_u32 s99, s13, 0
	s_add_i32 s27, s27, s86
	global_load_lds_dwordx4 v134, s[12:13]
	s_mov_b32 m0, s27
	s_nop 0
	global_load_lds_dwordx4 v130, s[98:99]
	s_add_i32 m0, s27, 0x2000
	s_nop 0
	global_load_lds_dwordx4 v134, s[98:99]
	s_mov_b32 m0, s15
	s_nop 0
	global_load_lds_dwordx4 v128, s[42:43]
	s_mov_b32 m0, s87
	s_nop 0
	global_load_lds_dwordx4 v132, s[42:43]
	s_waitcnt vmcnt(8)
	s_waitcnt lgkmcnt(0)
	s_barrier
	s_setprio 1
	s_waitcnt lgkmcnt(0)
	v_mfma_f32_16x16x32_bf16 v[60:63], v[150:153], v[204:207], 0
	v_mfma_f32_16x16x32_bf16 v[56:59], v[170:173], v[204:207], 0
	v_mfma_f32_16x16x32_bf16 v[44:47], v[150:153], v[212:215], 0
	v_mfma_f32_16x16x32_bf16 v[40:43], v[170:173], v[212:215], 0
	v_mfma_f32_16x16x32_bf16 v[28:31], v[150:153], v[234:237], 0
	v_mfma_f32_16x16x32_bf16 v[24:27], v[170:173], v[234:237], 0
	v_mfma_f32_16x16x32_bf16 v[12:15], v[150:153], v[242:245], 0
	v_mfma_f32_16x16x32_bf16 v[8:11], v[170:173], v[242:245], 0
	v_mfma_f32_16x16x32_bf16 v[60:63], v[154:157], v[208:211], v[60:63]
	v_mfma_f32_16x16x32_bf16 v[56:59], v[174:177], v[208:211], v[56:59]
	v_mfma_f32_16x16x32_bf16 v[44:47], v[154:157], v[222:225], v[44:47]
	v_mfma_f32_16x16x32_bf16 v[40:43], v[174:177], v[222:225], v[40:43]
	v_mfma_f32_16x16x32_bf16 v[28:31], v[154:157], v[238:241], v[28:31]
	v_mfma_f32_16x16x32_bf16 v[24:27], v[174:177], v[238:241], v[24:27]
	v_mfma_f32_16x16x32_bf16 v[12:15], v[154:157], v[246:249], v[12:15]
	v_mfma_f32_16x16x32_bf16 v[8:11], v[174:177], v[246:249], v[8:11]
	v_mfma_f32_16x16x32_bf16 v[52:55], v[178:181], v[204:207], 0
	v_mfma_f32_16x16x32_bf16 v[48:51], v[186:189], v[204:207], 0
	v_mfma_f32_16x16x32_bf16 v[36:39], v[178:181], v[212:215], 0
	v_mfma_f32_16x16x32_bf16 v[32:35], v[186:189], v[212:215], 0
	v_mfma_f32_16x16x32_bf16 v[20:23], v[178:181], v[234:237], 0
	v_mfma_f32_16x16x32_bf16 v[16:19], v[186:189], v[234:237], 0
	v_mfma_f32_16x16x32_bf16 v[4:7], v[178:181], v[242:245], 0
	v_mfma_f32_16x16x32_bf16 v[0:3], v[186:189], v[242:245], 0
	v_mfma_f32_16x16x32_bf16 v[52:55], v[182:185], v[208:211], v[52:55]
	v_mfma_f32_16x16x32_bf16 v[48:51], v[200:203], v[208:211], v[48:51]
	v_mfma_f32_16x16x32_bf16 v[36:39], v[182:185], v[222:225], v[36:39]
	v_mfma_f32_16x16x32_bf16 v[32:35], v[200:203], v[222:225], v[32:35]
	v_mfma_f32_16x16x32_bf16 v[20:23], v[182:185], v[238:241], v[20:23]
	v_mfma_f32_16x16x32_bf16 v[16:19], v[200:203], v[238:241], v[16:19]
	v_mfma_f32_16x16x32_bf16 v[4:7], v[182:185], v[246:249], v[4:7]
	v_mfma_f32_16x16x32_bf16 v[0:3], v[200:203], v[246:249], v[0:3]
	s_setprio 0
	s_barrier
	s_add_i32 s27, 0, 0x18000
	v_add_u32_e32 v160, s27, v196
	s_add_i32 s85, 0, 0x1c000
	ds_read_b128 v[150:153], v160
	ds_read_b128 v[154:157], v160 offset:1024
	ds_read_b128 v[170:173], v160 offset:2048
	ds_read_b128 v[174:177], v160 offset:3072
	v_add_u32_e32 v160, s85, v196
	ds_read_b128 v[178:181], v160
	ds_read_b128 v[182:185], v160 offset:1024
	ds_read_b128 v[186:189], v160 offset:2048
	ds_read_b128 v[200:203], v160 offset:3072
	s_add_u32 s42, s42, 0x40000
	s_addc_u32 s43, s43, 0
	s_mov_b32 m0, s88
	ds_read_b128 v[204:207], v199 offset:32768
	ds_read_b128 v[208:211], v199 offset:33792
	ds_read_b128 v[212:215], v199 offset:34816
	ds_read_b128 v[222:225], v199 offset:35840
	ds_read_b128 v[234:237], v199 offset:36864
	ds_read_b128 v[238:241], v199 offset:37888
	ds_read_b128 v[242:245], v199 offset:38912
	ds_read_b128 v[246:249], v199 offset:39936
	global_load_lds_dwordx4 v128, s[42:43]
	s_mov_b32 m0, s89
	s_nop 0
	global_load_lds_dwordx4 v132, s[42:43]
	s_waitcnt vmcnt(8)
	s_waitcnt lgkmcnt(0)
	s_barrier
	s_setprio 1
	s_waitcnt lgkmcnt(0)
	v_mfma_f32_16x16x32_bf16 v[124:127], v[150:153], v[204:207], v[124:127]
	v_mfma_f32_16x16x32_bf16 v[120:123], v[170:173], v[204:207], v[120:123]
	v_mfma_f32_16x16x32_bf16 v[108:111], v[150:153], v[212:215], v[108:111]
	v_mfma_f32_16x16x32_bf16 v[104:107], v[170:173], v[212:215], v[104:107]
	v_mfma_f32_16x16x32_bf16 v[92:95], v[150:153], v[234:237], v[92:95]
	v_mfma_f32_16x16x32_bf16 v[88:91], v[170:173], v[234:237], v[88:91]
	v_mfma_f32_16x16x32_bf16 v[76:79], v[150:153], v[242:245], v[76:79]
	v_mfma_f32_16x16x32_bf16 v[72:75], v[170:173], v[242:245], v[72:75]
	v_mfma_f32_16x16x32_bf16 v[124:127], v[154:157], v[208:211], v[124:127]
	v_mfma_f32_16x16x32_bf16 v[120:123], v[174:177], v[208:211], v[120:123]
	v_mfma_f32_16x16x32_bf16 v[108:111], v[154:157], v[222:225], v[108:111]
	v_mfma_f32_16x16x32_bf16 v[104:107], v[174:177], v[222:225], v[104:107]
	v_mfma_f32_16x16x32_bf16 v[92:95], v[154:157], v[238:241], v[92:95]
	v_mfma_f32_16x16x32_bf16 v[88:91], v[174:177], v[238:241], v[88:91]
	v_mfma_f32_16x16x32_bf16 v[76:79], v[154:157], v[246:249], v[76:79]
	v_mfma_f32_16x16x32_bf16 v[72:75], v[174:177], v[246:249], v[72:75]
	v_mfma_f32_16x16x32_bf16 v[116:119], v[178:181], v[204:207], v[116:119]
	v_mfma_f32_16x16x32_bf16 v[112:115], v[186:189], v[204:207], v[112:115]
	v_mfma_f32_16x16x32_bf16 v[100:103], v[178:181], v[212:215], v[100:103]
	v_mfma_f32_16x16x32_bf16 v[96:99], v[186:189], v[212:215], v[96:99]
	v_mfma_f32_16x16x32_bf16 v[84:87], v[178:181], v[234:237], v[84:87]
	v_mfma_f32_16x16x32_bf16 v[80:83], v[186:189], v[234:237], v[80:83]
	v_mfma_f32_16x16x32_bf16 v[68:71], v[178:181], v[242:245], v[68:71]
	v_mfma_f32_16x16x32_bf16 v[64:67], v[186:189], v[242:245], v[64:67]
	v_mfma_f32_16x16x32_bf16 v[116:119], v[182:185], v[208:211], v[116:119]
	v_mfma_f32_16x16x32_bf16 v[112:115], v[200:203], v[208:211], v[112:115]
	v_mfma_f32_16x16x32_bf16 v[100:103], v[182:185], v[222:225], v[100:103]
	v_mfma_f32_16x16x32_bf16 v[96:99], v[200:203], v[222:225], v[96:99]
	v_mfma_f32_16x16x32_bf16 v[84:87], v[182:185], v[238:241], v[84:87]
	v_mfma_f32_16x16x32_bf16 v[80:83], v[200:203], v[238:241], v[80:83]
	v_mfma_f32_16x16x32_bf16 v[68:71], v[182:185], v[246:249], v[68:71]
	v_mfma_f32_16x16x32_bf16 v[64:67], v[200:203], v[246:249], v[64:67]
	s_setprio 0
	s_barrier
	s_add_i32 s27, s27, s86
	s_add_u32 s100, s12, 0x80
	s_addc_u32 s101, s13, 0
	s_mov_b32 m0, s27
	ds_read_b128 v[204:207], v199 offset:49152
	ds_read_b128 v[208:211], v199 offset:50176
	ds_read_b128 v[212:215], v199 offset:51200
	ds_read_b128 v[222:225], v199 offset:52224
	ds_read_b128 v[234:237], v199 offset:53248
	ds_read_b128 v[238:241], v199 offset:54272
	ds_read_b128 v[242:245], v199 offset:55296
	ds_read_b128 v[246:249], v199 offset:56320
	global_load_lds_dwordx4 v130, s[100:101]
	s_add_i32 m0, s27, 0x2000
	s_add_u32 s12, s12, 0x40080
	s_addc_u32 s13, s13, 0
	s_add_i32 s27, s85, s86
	global_load_lds_dwordx4 v134, s[100:101]
	s_mov_b32 m0, s27
	s_nop 0
	global_load_lds_dwordx4 v130, s[12:13]
	s_add_i32 m0, s27, 0x2000
	s_nop 0
	global_load_lds_dwordx4 v134, s[12:13]
	s_add_u32 s98, s42, 0xfffc0080
	s_addc_u32 s99, s43, -1
	s_mov_b32 m0, s92
	s_nop 0
	global_load_lds_dwordx4 v128, s[98:99]
	s_mov_b32 m0, s93
	s_nop 0
	global_load_lds_dwordx4 v132, s[98:99]
	s_waitcnt vmcnt(8)
	s_waitcnt lgkmcnt(0)
	s_barrier
	s_setprio 1
	s_waitcnt lgkmcnt(0)
	v_mfma_f32_16x16x32_bf16 v[60:63], v[150:153], v[204:207], v[60:63]
	v_mfma_f32_16x16x32_bf16 v[56:59], v[170:173], v[204:207], v[56:59]
	v_mfma_f32_16x16x32_bf16 v[44:47], v[150:153], v[212:215], v[44:47]
	v_mfma_f32_16x16x32_bf16 v[40:43], v[170:173], v[212:215], v[40:43]
	v_mfma_f32_16x16x32_bf16 v[28:31], v[150:153], v[234:237], v[28:31]
	v_mfma_f32_16x16x32_bf16 v[24:27], v[170:173], v[234:237], v[24:27]
	v_mfma_f32_16x16x32_bf16 v[12:15], v[150:153], v[242:245], v[12:15]
	v_mfma_f32_16x16x32_bf16 v[8:11], v[170:173], v[242:245], v[8:11]
	v_mfma_f32_16x16x32_bf16 v[60:63], v[154:157], v[208:211], v[60:63]
	v_mfma_f32_16x16x32_bf16 v[56:59], v[174:177], v[208:211], v[56:59]
	v_mfma_f32_16x16x32_bf16 v[44:47], v[154:157], v[222:225], v[44:47]
	v_mfma_f32_16x16x32_bf16 v[40:43], v[174:177], v[222:225], v[40:43]
	v_mfma_f32_16x16x32_bf16 v[28:31], v[154:157], v[238:241], v[28:31]
	v_mfma_f32_16x16x32_bf16 v[24:27], v[174:177], v[238:241], v[24:27]
	v_mfma_f32_16x16x32_bf16 v[12:15], v[154:157], v[246:249], v[12:15]
	v_mfma_f32_16x16x32_bf16 v[8:11], v[174:177], v[246:249], v[8:11]
	v_mfma_f32_16x16x32_bf16 v[52:55], v[178:181], v[204:207], v[52:55]
	v_mfma_f32_16x16x32_bf16 v[48:51], v[186:189], v[204:207], v[48:51]
	v_mfma_f32_16x16x32_bf16 v[36:39], v[178:181], v[212:215], v[36:39]
	v_mfma_f32_16x16x32_bf16 v[32:35], v[186:189], v[212:215], v[32:35]
	v_mfma_f32_16x16x32_bf16 v[20:23], v[178:181], v[234:237], v[20:23]
	v_mfma_f32_16x16x32_bf16 v[16:19], v[186:189], v[234:237], v[16:19]
	v_mfma_f32_16x16x32_bf16 v[4:7], v[178:181], v[242:245], v[4:7]
	v_mfma_f32_16x16x32_bf16 v[0:3], v[186:189], v[242:245], v[0:3]
	v_mfma_f32_16x16x32_bf16 v[52:55], v[182:185], v[208:211], v[52:55]
	v_mfma_f32_16x16x32_bf16 v[48:51], v[200:203], v[208:211], v[48:51]
	v_mfma_f32_16x16x32_bf16 v[36:39], v[182:185], v[222:225], v[36:39]
	v_mfma_f32_16x16x32_bf16 v[32:35], v[200:203], v[222:225], v[32:35]
	v_mfma_f32_16x16x32_bf16 v[20:23], v[182:185], v[238:241], v[20:23]
	v_mfma_f32_16x16x32_bf16 v[16:19], v[200:203], v[238:241], v[16:19]
	v_mfma_f32_16x16x32_bf16 v[4:7], v[182:185], v[246:249], v[4:7]
	v_mfma_f32_16x16x32_bf16 v[0:3], v[200:203], v[246:249], v[0:3]
	s_add_i32 s51, s51, 2
	s_add_u32 s40, s40, 0x100
	s_addc_u32 s41, s41, 0
	s_add_u32 s25, s25, 0x100
	s_addc_u32 s50, s50, 0
	s_cmp_gt_u32 s51, 13
	s_setprio 0
	s_barrier
.LBB0_478:
	s_add_u32 s12, s40, 0xfffc0080
	s_addc_u32 s13, s41, -1
	s_add_i32 s85, 0, 0x10000
	s_cmp_eq_u32 s51, 12
	s_cselect_b32 s43, s4, s13
	s_cselect_b32 s42, s9, s12
	v_add_u32_e32 v158, s85, v196
	s_cselect_b32 s13, s17, s50
	s_cselect_b32 s12, s24, s25
	s_add_i32 s27, 0, 0x14000
	ds_read_b128 v[150:153], v158
	ds_read_b128 v[154:157], v158 offset:1024
	ds_read_b128 v[170:173], v158 offset:2048
	ds_read_b128 v[174:177], v158 offset:3072
	v_add_u32_e32 v158, s27, v196
	ds_read_b128 v[178:181], v158
	ds_read_b128 v[182:185], v158 offset:1024
	ds_read_b128 v[186:189], v158 offset:2048
	ds_read_b128 v[200:203], v158 offset:3072
	s_add_i32 m0, s15, 0xc000
	ds_read_b128 v[204:207], v199
	ds_read_b128 v[208:211], v199 offset:1024
	ds_read_b128 v[212:215], v199 offset:2048
	ds_read_b128 v[234:237], v199 offset:3072
	ds_read_b128 v[238:241], v199 offset:4096
	ds_read_b128 v[242:245], v199 offset:5120
	ds_read_b128 v[246:249], v199 offset:6144
	ds_read_b128 v[222:225], v199 offset:7168
	global_load_lds_dwordx4 v146, s[40:41]
	s_add_i32 m0, s15, 0xe000
	s_nop 0
	global_load_lds_dwordx4 v148, s[40:41]
	s_waitcnt vmcnt(8)
	s_waitcnt lgkmcnt(0)
	s_barrier
	s_setprio 1
	s_waitcnt lgkmcnt(0)
	v_mfma_f32_16x16x32_bf16 v[124:127], v[150:153], v[204:207], v[124:127]
	v_mfma_f32_16x16x32_bf16 v[120:123], v[170:173], v[204:207], v[120:123]
	v_mfma_f32_16x16x32_bf16 v[108:111], v[150:153], v[212:215], v[108:111]
	v_mfma_f32_16x16x32_bf16 v[104:107], v[170:173], v[212:215], v[104:107]
	v_mfma_f32_16x16x32_bf16 v[92:95], v[150:153], v[238:241], v[92:95]
	v_mfma_f32_16x16x32_bf16 v[88:91], v[170:173], v[238:241], v[88:91]
	v_mfma_f32_16x16x32_bf16 v[76:79], v[150:153], v[246:249], v[76:79]
	v_mfma_f32_16x16x32_bf16 v[72:75], v[170:173], v[246:249], v[72:75]
	v_mfma_f32_16x16x32_bf16 v[124:127], v[154:157], v[208:211], v[124:127]
	v_mfma_f32_16x16x32_bf16 v[120:123], v[174:177], v[208:211], v[120:123]
	v_mfma_f32_16x16x32_bf16 v[108:111], v[154:157], v[234:237], v[108:111]
	v_mfma_f32_16x16x32_bf16 v[104:107], v[174:177], v[234:237], v[104:107]
	v_mfma_f32_16x16x32_bf16 v[92:95], v[154:157], v[242:245], v[92:95]
	v_mfma_f32_16x16x32_bf16 v[88:91], v[174:177], v[242:245], v[88:91]
	v_mfma_f32_16x16x32_bf16 v[76:79], v[154:157], v[222:225], v[76:79]
	v_mfma_f32_16x16x32_bf16 v[72:75], v[174:177], v[222:225], v[72:75]
	v_mfma_f32_16x16x32_bf16 v[116:119], v[178:181], v[204:207], v[116:119]
	v_mfma_f32_16x16x32_bf16 v[112:115], v[186:189], v[204:207], v[112:115]
	v_mfma_f32_16x16x32_bf16 v[100:103], v[178:181], v[212:215], v[100:103]
	v_mfma_f32_16x16x32_bf16 v[96:99], v[186:189], v[212:215], v[96:99]
	v_mfma_f32_16x16x32_bf16 v[84:87], v[178:181], v[238:241], v[84:87]
	v_mfma_f32_16x16x32_bf16 v[80:83], v[186:189], v[238:241], v[80:83]
	v_mfma_f32_16x16x32_bf16 v[68:71], v[178:181], v[246:249], v[68:71]
	v_mfma_f32_16x16x32_bf16 v[64:67], v[186:189], v[246:249], v[64:67]
	v_mfma_f32_16x16x32_bf16 v[116:119], v[182:185], v[208:211], v[116:119]
	v_mfma_f32_16x16x32_bf16 v[112:115], v[200:203], v[208:211], v[112:115]
	v_mfma_f32_16x16x32_bf16 v[100:103], v[182:185], v[234:237], v[100:103]
	v_mfma_f32_16x16x32_bf16 v[96:99], v[200:203], v[234:237], v[96:99]
	v_mfma_f32_16x16x32_bf16 v[84:87], v[182:185], v[242:245], v[84:87]
	v_mfma_f32_16x16x32_bf16 v[80:83], v[200:203], v[242:245], v[80:83]
	v_mfma_f32_16x16x32_bf16 v[68:71], v[182:185], v[222:225], v[68:71]
	v_mfma_f32_16x16x32_bf16 v[64:67], v[200:203], v[222:225], v[64:67]
	s_setprio 0
	s_barrier
	s_add_i32 s85, s85, s86
	s_mov_b32 m0, s85
	ds_read_b128 v[204:207], v199 offset:16384
	ds_read_b128 v[208:211], v199 offset:17408
	ds_read_b128 v[212:215], v199 offset:18432
	ds_read_b128 v[222:225], v199 offset:19456
	ds_read_b128 v[234:237], v199 offset:20480
	ds_read_b128 v[238:241], v199 offset:21504
	ds_read_b128 v[242:245], v199 offset:22528
	ds_read_b128 v[246:249], v199 offset:23552
	global_load_lds_dwordx4 v130, s[12:13]
	s_add_i32 m0, s85, 0x2000
	s_add_u32 s98, s12, 0x40000
	s_addc_u32 s99, s13, 0
	s_add_i32 s27, s27, s86
	global_load_lds_dwordx4 v134, s[12:13]
	s_mov_b32 m0, s27
	s_nop 0
	global_load_lds_dwordx4 v130, s[98:99]
	s_add_i32 m0, s27, 0x2000
	s_nop 0
	global_load_lds_dwordx4 v134, s[98:99]
	s_mov_b32 m0, s15
	s_nop 0
	global_load_lds_dwordx4 v128, s[42:43]
	s_mov_b32 m0, s87
	s_nop 0
	global_load_lds_dwordx4 v132, s[42:43]
	s_waitcnt vmcnt(8)
	s_waitcnt lgkmcnt(0)
	s_barrier
	s_setprio 1
	s_waitcnt lgkmcnt(0)
	v_mfma_f32_16x16x32_bf16 v[60:63], v[150:153], v[204:207], v[60:63]
	v_mfma_f32_16x16x32_bf16 v[56:59], v[170:173], v[204:207], v[56:59]
	v_mfma_f32_16x16x32_bf16 v[44:47], v[150:153], v[212:215], v[44:47]
	v_mfma_f32_16x16x32_bf16 v[40:43], v[170:173], v[212:215], v[40:43]
	v_mfma_f32_16x16x32_bf16 v[28:31], v[150:153], v[234:237], v[28:31]
	v_mfma_f32_16x16x32_bf16 v[24:27], v[170:173], v[234:237], v[24:27]
	v_mfma_f32_16x16x32_bf16 v[12:15], v[150:153], v[242:245], v[12:15]
	v_mfma_f32_16x16x32_bf16 v[8:11], v[170:173], v[242:245], v[8:11]
	v_mfma_f32_16x16x32_bf16 v[60:63], v[154:157], v[208:211], v[60:63]
	v_mfma_f32_16x16x32_bf16 v[56:59], v[174:177], v[208:211], v[56:59]
	v_mfma_f32_16x16x32_bf16 v[44:47], v[154:157], v[222:225], v[44:47]
	v_mfma_f32_16x16x32_bf16 v[40:43], v[174:177], v[222:225], v[40:43]
	v_mfma_f32_16x16x32_bf16 v[28:31], v[154:157], v[238:241], v[28:31]
	v_mfma_f32_16x16x32_bf16 v[24:27], v[174:177], v[238:241], v[24:27]
	v_mfma_f32_16x16x32_bf16 v[12:15], v[154:157], v[246:249], v[12:15]
	v_mfma_f32_16x16x32_bf16 v[8:11], v[174:177], v[246:249], v[8:11]
	v_mfma_f32_16x16x32_bf16 v[52:55], v[178:181], v[204:207], v[52:55]
	v_mfma_f32_16x16x32_bf16 v[48:51], v[186:189], v[204:207], v[48:51]
	v_mfma_f32_16x16x32_bf16 v[36:39], v[178:181], v[212:215], v[36:39]
	v_mfma_f32_16x16x32_bf16 v[32:35], v[186:189], v[212:215], v[32:35]
	v_mfma_f32_16x16x32_bf16 v[20:23], v[178:181], v[234:237], v[20:23]
	v_mfma_f32_16x16x32_bf16 v[16:19], v[186:189], v[234:237], v[16:19]
	v_mfma_f32_16x16x32_bf16 v[4:7], v[178:181], v[242:245], v[4:7]
	v_mfma_f32_16x16x32_bf16 v[0:3], v[186:189], v[242:245], v[0:3]
	v_mfma_f32_16x16x32_bf16 v[52:55], v[182:185], v[208:211], v[52:55]
	v_mfma_f32_16x16x32_bf16 v[48:51], v[200:203], v[208:211], v[48:51]
	v_mfma_f32_16x16x32_bf16 v[36:39], v[182:185], v[222:225], v[36:39]
	v_mfma_f32_16x16x32_bf16 v[32:35], v[200:203], v[222:225], v[32:35]
	v_mfma_f32_16x16x32_bf16 v[20:23], v[182:185], v[238:241], v[20:23]
	v_mfma_f32_16x16x32_bf16 v[16:19], v[200:203], v[238:241], v[16:19]
	v_mfma_f32_16x16x32_bf16 v[4:7], v[182:185], v[246:249], v[4:7]
	v_mfma_f32_16x16x32_bf16 v[0:3], v[200:203], v[246:249], v[0:3]
	s_setprio 0
	s_barrier
	s_add_i32 s27, 0, 0x18000
	v_add_u32_e32 v160, s27, v196
	s_add_i32 s85, 0, 0x1c000
	ds_read_b128 v[150:153], v160
	ds_read_b128 v[154:157], v160 offset:1024
	ds_read_b128 v[170:173], v160 offset:2048
	ds_read_b128 v[174:177], v160 offset:3072
	v_add_u32_e32 v160, s85, v196
	ds_read_b128 v[178:181], v160
	ds_read_b128 v[182:185], v160 offset:1024
	ds_read_b128 v[186:189], v160 offset:2048
	ds_read_b128 v[200:203], v160 offset:3072
	s_add_u32 s42, s42, 0x40000
	s_addc_u32 s43, s43, 0
	s_mov_b32 m0, s88
	ds_read_b128 v[204:207], v199 offset:32768
	ds_read_b128 v[208:211], v199 offset:33792
	ds_read_b128 v[212:215], v199 offset:34816
	ds_read_b128 v[222:225], v199 offset:35840
	ds_read_b128 v[234:237], v199 offset:36864
	ds_read_b128 v[238:241], v199 offset:37888
	ds_read_b128 v[242:245], v199 offset:38912
	ds_read_b128 v[246:249], v199 offset:39936
	global_load_lds_dwordx4 v128, s[42:43]
	s_mov_b32 m0, s89
	s_nop 0
	global_load_lds_dwordx4 v132, s[42:43]
	s_waitcnt vmcnt(8)
	s_waitcnt lgkmcnt(0)
	s_barrier
	s_setprio 1
	s_waitcnt lgkmcnt(0)
	v_mfma_f32_16x16x32_bf16 v[124:127], v[150:153], v[204:207], v[124:127]
	v_mfma_f32_16x16x32_bf16 v[120:123], v[170:173], v[204:207], v[120:123]
	v_mfma_f32_16x16x32_bf16 v[108:111], v[150:153], v[212:215], v[108:111]
	v_mfma_f32_16x16x32_bf16 v[104:107], v[170:173], v[212:215], v[104:107]
	v_mfma_f32_16x16x32_bf16 v[92:95], v[150:153], v[234:237], v[92:95]
	v_mfma_f32_16x16x32_bf16 v[88:91], v[170:173], v[234:237], v[88:91]
	v_mfma_f32_16x16x32_bf16 v[76:79], v[150:153], v[242:245], v[76:79]
	v_mfma_f32_16x16x32_bf16 v[72:75], v[170:173], v[242:245], v[72:75]
	v_mfma_f32_16x16x32_bf16 v[124:127], v[154:157], v[208:211], v[124:127]
	v_mfma_f32_16x16x32_bf16 v[120:123], v[174:177], v[208:211], v[120:123]
	v_mfma_f32_16x16x32_bf16 v[108:111], v[154:157], v[222:225], v[108:111]
	v_mfma_f32_16x16x32_bf16 v[104:107], v[174:177], v[222:225], v[104:107]
	v_mfma_f32_16x16x32_bf16 v[92:95], v[154:157], v[238:241], v[92:95]
	v_mfma_f32_16x16x32_bf16 v[88:91], v[174:177], v[238:241], v[88:91]
	v_mfma_f32_16x16x32_bf16 v[76:79], v[154:157], v[246:249], v[76:79]
	v_mfma_f32_16x16x32_bf16 v[72:75], v[174:177], v[246:249], v[72:75]
	v_mfma_f32_16x16x32_bf16 v[116:119], v[178:181], v[204:207], v[116:119]
	v_mfma_f32_16x16x32_bf16 v[112:115], v[186:189], v[204:207], v[112:115]
	v_mfma_f32_16x16x32_bf16 v[100:103], v[178:181], v[212:215], v[100:103]
	v_mfma_f32_16x16x32_bf16 v[96:99], v[186:189], v[212:215], v[96:99]
	v_mfma_f32_16x16x32_bf16 v[84:87], v[178:181], v[234:237], v[84:87]
	v_mfma_f32_16x16x32_bf16 v[80:83], v[186:189], v[234:237], v[80:83]
	v_mfma_f32_16x16x32_bf16 v[68:71], v[178:181], v[242:245], v[68:71]
	v_mfma_f32_16x16x32_bf16 v[64:67], v[186:189], v[242:245], v[64:67]
	v_mfma_f32_16x16x32_bf16 v[116:119], v[182:185], v[208:211], v[116:119]
	v_mfma_f32_16x16x32_bf16 v[112:115], v[200:203], v[208:211], v[112:115]
	v_mfma_f32_16x16x32_bf16 v[100:103], v[182:185], v[222:225], v[100:103]
	v_mfma_f32_16x16x32_bf16 v[96:99], v[200:203], v[222:225], v[96:99]
	v_mfma_f32_16x16x32_bf16 v[84:87], v[182:185], v[238:241], v[84:87]
	v_mfma_f32_16x16x32_bf16 v[80:83], v[200:203], v[238:241], v[80:83]
	v_mfma_f32_16x16x32_bf16 v[68:71], v[182:185], v[246:249], v[68:71]
	v_mfma_f32_16x16x32_bf16 v[64:67], v[200:203], v[246:249], v[64:67]
	s_setprio 0
	s_barrier
	s_add_i32 s27, s27, s86
	s_add_u32 s100, s12, 0x80
	s_addc_u32 s101, s13, 0
	s_mov_b32 m0, s27
	ds_read_b128 v[204:207], v199 offset:49152
	ds_read_b128 v[208:211], v199 offset:50176
	ds_read_b128 v[212:215], v199 offset:51200
	ds_read_b128 v[222:225], v199 offset:52224
	ds_read_b128 v[234:237], v199 offset:53248
	ds_read_b128 v[238:241], v199 offset:54272
	ds_read_b128 v[242:245], v199 offset:55296
	ds_read_b128 v[246:249], v199 offset:56320
	global_load_lds_dwordx4 v130, s[100:101]
	s_add_i32 m0, s27, 0x2000
	s_add_u32 s12, s12, 0x40080
	s_addc_u32 s13, s13, 0
	s_add_i32 s27, s85, s86
	global_load_lds_dwordx4 v134, s[100:101]
	s_mov_b32 m0, s27
	s_nop 0
	global_load_lds_dwordx4 v130, s[12:13]
	s_add_i32 m0, s27, 0x2000
	s_nop 0
	global_load_lds_dwordx4 v134, s[12:13]
	s_add_u32 s98, s42, 0xfffc0080
	s_addc_u32 s99, s43, -1
	s_mov_b32 m0, s92
	s_nop 0
	global_load_lds_dwordx4 v128, s[98:99]
	s_mov_b32 m0, s93
	s_nop 0
	global_load_lds_dwordx4 v132, s[98:99]
	s_waitcnt vmcnt(8)
	s_waitcnt lgkmcnt(0)
	s_barrier
	s_setprio 1
	s_waitcnt lgkmcnt(0)
	v_mfma_f32_16x16x32_bf16 v[60:63], v[150:153], v[204:207], v[60:63]
	v_mfma_f32_16x16x32_bf16 v[56:59], v[170:173], v[204:207], v[56:59]
	v_mfma_f32_16x16x32_bf16 v[44:47], v[150:153], v[212:215], v[44:47]
	v_mfma_f32_16x16x32_bf16 v[40:43], v[170:173], v[212:215], v[40:43]
	v_mfma_f32_16x16x32_bf16 v[28:31], v[150:153], v[234:237], v[28:31]
	v_mfma_f32_16x16x32_bf16 v[24:27], v[170:173], v[234:237], v[24:27]
	v_mfma_f32_16x16x32_bf16 v[12:15], v[150:153], v[242:245], v[12:15]
	v_mfma_f32_16x16x32_bf16 v[8:11], v[170:173], v[242:245], v[8:11]
	v_mfma_f32_16x16x32_bf16 v[60:63], v[154:157], v[208:211], v[60:63]
	v_mfma_f32_16x16x32_bf16 v[56:59], v[174:177], v[208:211], v[56:59]
	v_mfma_f32_16x16x32_bf16 v[44:47], v[154:157], v[222:225], v[44:47]
	v_mfma_f32_16x16x32_bf16 v[40:43], v[174:177], v[222:225], v[40:43]
	v_mfma_f32_16x16x32_bf16 v[28:31], v[154:157], v[238:241], v[28:31]
	v_mfma_f32_16x16x32_bf16 v[24:27], v[174:177], v[238:241], v[24:27]
	v_mfma_f32_16x16x32_bf16 v[12:15], v[154:157], v[246:249], v[12:15]
	v_mfma_f32_16x16x32_bf16 v[8:11], v[174:177], v[246:249], v[8:11]
	v_mfma_f32_16x16x32_bf16 v[52:55], v[178:181], v[204:207], v[52:55]
	v_mfma_f32_16x16x32_bf16 v[48:51], v[186:189], v[204:207], v[48:51]
	v_mfma_f32_16x16x32_bf16 v[36:39], v[178:181], v[212:215], v[36:39]
	v_mfma_f32_16x16x32_bf16 v[32:35], v[186:189], v[212:215], v[32:35]
	v_mfma_f32_16x16x32_bf16 v[20:23], v[178:181], v[234:237], v[20:23]
	v_mfma_f32_16x16x32_bf16 v[16:19], v[186:189], v[234:237], v[16:19]
	v_mfma_f32_16x16x32_bf16 v[4:7], v[178:181], v[242:245], v[4:7]
	v_mfma_f32_16x16x32_bf16 v[0:3], v[186:189], v[242:245], v[0:3]
	v_mfma_f32_16x16x32_bf16 v[52:55], v[182:185], v[208:211], v[52:55]
	v_mfma_f32_16x16x32_bf16 v[48:51], v[200:203], v[208:211], v[48:51]
	v_mfma_f32_16x16x32_bf16 v[36:39], v[182:185], v[222:225], v[36:39]
	v_mfma_f32_16x16x32_bf16 v[32:35], v[200:203], v[222:225], v[32:35]
	v_mfma_f32_16x16x32_bf16 v[20:23], v[182:185], v[238:241], v[20:23]
	v_mfma_f32_16x16x32_bf16 v[16:19], v[200:203], v[238:241], v[16:19]
	v_mfma_f32_16x16x32_bf16 v[4:7], v[182:185], v[246:249], v[4:7]
	v_mfma_f32_16x16x32_bf16 v[0:3], v[200:203], v[246:249], v[0:3]
	s_add_i32 s51, s51, 2
	s_add_u32 s40, s40, 0x100
	s_addc_u32 s41, s41, 0
	s_add_u32 s25, s25, 0x100
	s_addc_u32 s50, s50, 0
	s_cmp_gt_u32 s51, 13
	s_setprio 0
	s_barrier
	s_cbranch_scc0 .LBB0_478
	s_and_b64 vcc, exec, s[10:11]
	s_cbranch_vccz .LBB0_481
	s_barrier

.LBB0_654:
	s_ashr_i32 s17, s16, 31
	s_lshl_b64 s[18:19], s[16:17], 19
	s_add_u32 s18, s68, s18
	s_addc_u32 s19, s69, s19
	s_and_b64 s[36:37], s[12:13], exec
	s_cselect_b32 s17, s19, s39
	s_cselect_b32 s84, s18, s38
	s_ashr_i32 s15, s14, 31
	s_lshl_b64 s[36:37], s[14:15], 19
	s_add_u32 s36, s28, s36
	s_addc_u32 s37, s66, s37
	s_and_b64 s[42:43], s[12:13], exec
	s_cselect_b32 s15, s37, s41
	s_cselect_b32 s85, s36, s40
	s_add_u32 s38, s38, 0x40080
	s_addc_u32 s39, s39, 0
	s_add_u32 s86, s40, 0x100
	s_addc_u32 s87, s41, 0
	s_mov_b32 s88, -2
	s_add_u32 s40, s38, 0xfffc0080
	s_addc_u32 s41, s39, -1
	s_add_i32 s89, 0, 0x10000
	s_cmp_eq_u32 s88, 12
	s_cselect_b32 s43, s17, s41
	s_cselect_b32 s42, s84, s40
	v_add_u32_e32 v143, s89, v141
	s_cselect_b32 s41, s15, s87
	s_cselect_b32 s40, s85, s86
	s_add_i32 s92, 0, 0x14000
	ds_read_b128 v[144:147], v143
	ds_read_b128 v[148:151], v143 offset:1024
	ds_read_b128 v[152:155], v143 offset:2048
	ds_read_b128 v[156:159], v143 offset:3072
	v_add_u32_e32 v143, s92, v141
	ds_read_b128 v[170:173], v143
	ds_read_b128 v[174:177], v143 offset:1024
	ds_read_b128 v[178:181], v143 offset:2048
	ds_read_b128 v[182:185], v143 offset:3072
	v_lshl_add_u64 v[162:163], s[38:39], 0, v[136:137]
	s_add_i32 m0, s27, 0xc000
	ds_read_b128 v[186:189], v142
	ds_read_b128 v[190:193], v142 offset:1024
	ds_read_b128 v[194:197], v142 offset:2048
	ds_read_b128 v[198:201], v142 offset:3072
	ds_read_b128 v[202:205], v142 offset:4096
	ds_read_b128 v[206:209], v142 offset:5120
	ds_read_b128 v[210:213], v142 offset:6144
	ds_read_b128 v[222:225], v142 offset:7168
	global_load_lds_dwordx4 v[162:163], off
	v_lshl_add_u64 v[162:163], s[38:39], 0, v[138:139]
	s_add_i32 m0, s27, 0xe000
	s_nop 0
	global_load_lds_dwordx4 v[162:163], off
	s_waitcnt vmcnt(8)
	s_waitcnt lgkmcnt(0)
	s_barrier
	s_setprio 1
	s_waitcnt lgkmcnt(0)
	v_mfma_f32_16x16x32_bf16 v[124:127], v[144:147], v[186:189], 0
	v_mfma_f32_16x16x32_bf16 v[120:123], v[152:155], v[186:189], 0
	v_mfma_f32_16x16x32_bf16 v[116:119], v[144:147], v[194:197], 0
	v_mfma_f32_16x16x32_bf16 v[112:115], v[152:155], v[194:197], 0
	v_mfma_f32_16x16x32_bf16 v[100:103], v[144:147], v[202:205], 0
	v_mfma_f32_16x16x32_bf16 v[96:99], v[152:155], v[202:205], 0
	v_mfma_f32_16x16x32_bf16 v[84:87], v[144:147], v[210:213], 0
	v_mfma_f32_16x16x32_bf16 v[80:83], v[152:155], v[210:213], 0
	v_mfma_f32_16x16x32_bf16 v[124:127], v[148:151], v[190:193], v[124:127]
	v_mfma_f32_16x16x32_bf16 v[120:123], v[156:159], v[190:193], v[120:123]
	v_mfma_f32_16x16x32_bf16 v[116:119], v[148:151], v[198:201], v[116:119]
	v_mfma_f32_16x16x32_bf16 v[112:115], v[156:159], v[198:201], v[112:115]
	v_mfma_f32_16x16x32_bf16 v[100:103], v[148:151], v[206:209], v[100:103]
	v_mfma_f32_16x16x32_bf16 v[96:99], v[156:159], v[206:209], v[96:99]
	v_mfma_f32_16x16x32_bf16 v[84:87], v[148:151], v[222:225], v[84:87]
	v_mfma_f32_16x16x32_bf16 v[80:83], v[156:159], v[222:225], v[80:83]
	v_mfma_f32_16x16x32_bf16 v[108:111], v[170:173], v[186:189], 0
	v_mfma_f32_16x16x32_bf16 v[104:107], v[178:181], v[186:189], 0
	v_mfma_f32_16x16x32_bf16 v[92:95], v[170:173], v[194:197], 0
	v_mfma_f32_16x16x32_bf16 v[88:91], v[178:181], v[194:197], 0
	v_mfma_f32_16x16x32_bf16 v[76:79], v[170:173], v[202:205], 0
	v_mfma_f32_16x16x32_bf16 v[72:75], v[178:181], v[202:205], 0
	v_mfma_f32_16x16x32_bf16 v[68:71], v[170:173], v[210:213], 0
	v_mfma_f32_16x16x32_bf16 v[64:67], v[178:181], v[210:213], 0
	v_mfma_f32_16x16x32_bf16 v[108:111], v[174:177], v[190:193], v[108:111]
	v_mfma_f32_16x16x32_bf16 v[104:107], v[182:185], v[190:193], v[104:107]
	v_mfma_f32_16x16x32_bf16 v[92:95], v[174:177], v[198:201], v[92:95]
	v_mfma_f32_16x16x32_bf16 v[88:91], v[182:185], v[198:201], v[88:91]
	v_mfma_f32_16x16x32_bf16 v[76:79], v[174:177], v[206:209], v[76:79]
	v_mfma_f32_16x16x32_bf16 v[72:75], v[182:185], v[206:209], v[72:75]
	v_mfma_f32_16x16x32_bf16 v[68:71], v[174:177], v[222:225], v[68:71]
	v_mfma_f32_16x16x32_bf16 v[64:67], v[182:185], v[222:225], v[64:67]
	s_setprio 0
	s_barrier
	s_add_i32 s89, s89, s26
	v_lshl_add_u64 v[162:163], s[40:41], 0, v[130:131]
	s_mov_b32 m0, s89
	ds_read_b128 v[186:189], v142 offset:16384
	ds_read_b128 v[190:193], v142 offset:17408
	ds_read_b128 v[194:197], v142 offset:18432
	ds_read_b128 v[198:201], v142 offset:19456
	ds_read_b128 v[202:205], v142 offset:20480
	ds_read_b128 v[206:209], v142 offset:21504
	ds_read_b128 v[210:213], v142 offset:22528
	ds_read_b128 v[222:225], v142 offset:23552
	global_load_lds_dwordx4 v[162:163], off
	s_add_i32 m0, s89, 0x2000
	s_add_u32 s90, s40, 0x40000
	v_lshl_add_u64 v[164:165], s[40:41], 0, v[134:135]
	s_addc_u32 s91, s41, 0
	s_add_i32 s89, s92, s26
	global_load_lds_dwordx4 v[164:165], off
	v_lshl_add_u64 v[214:215], s[90:91], 0, v[130:131]
	s_mov_b32 m0, s89
	v_lshl_add_u64 v[226:227], s[42:43], 0, v[132:133]
	global_load_lds_dwordx4 v[214:215], off
	v_lshl_add_u64 v[214:215], s[90:91], 0, v[134:135]
	s_add_i32 m0, s89, 0x2000
	s_nop 0
	global_load_lds_dwordx4 v[214:215], off
	v_lshl_add_u64 v[214:215], s[42:43], 0, v[128:129]
	s_mov_b32 m0, s27
	s_nop 0
	global_load_lds_dwordx4 v[214:215], off
	s_mov_b32 m0, s50
	s_nop 0
	global_load_lds_dwordx4 v[226:227], off
	s_waitcnt vmcnt(8)
	s_waitcnt lgkmcnt(0)
	s_barrier
	s_setprio 1
	s_waitcnt lgkmcnt(0)
	v_mfma_f32_16x16x32_bf16 v[60:63], v[144:147], v[186:189], 0
	v_mfma_f32_16x16x32_bf16 v[56:59], v[152:155], v[186:189], 0
	v_mfma_f32_16x16x32_bf16 v[52:55], v[144:147], v[194:197], 0
	v_mfma_f32_16x16x32_bf16 v[48:51], v[152:155], v[194:197], 0
	v_mfma_f32_16x16x32_bf16 v[36:39], v[144:147], v[202:205], 0
	v_mfma_f32_16x16x32_bf16 v[32:35], v[152:155], v[202:205], 0
	v_mfma_f32_16x16x32_bf16 v[20:23], v[144:147], v[210:213], 0
	v_mfma_f32_16x16x32_bf16 v[16:19], v[152:155], v[210:213], 0
	v_mfma_f32_16x16x32_bf16 v[60:63], v[148:151], v[190:193], v[60:63]
	v_mfma_f32_16x16x32_bf16 v[56:59], v[156:159], v[190:193], v[56:59]
	v_mfma_f32_16x16x32_bf16 v[52:55], v[148:151], v[198:201], v[52:55]
	v_mfma_f32_16x16x32_bf16 v[48:51], v[156:159], v[198:201], v[48:51]
	v_mfma_f32_16x16x32_bf16 v[36:39], v[148:151], v[206:209], v[36:39]
	v_mfma_f32_16x16x32_bf16 v[32:35], v[156:159], v[206:209], v[32:35]
	v_mfma_f32_16x16x32_bf16 v[20:23], v[148:151], v[222:225], v[20:23]
	v_mfma_f32_16x16x32_bf16 v[16:19], v[156:159], v[222:225], v[16:19]
	v_mfma_f32_16x16x32_bf16 v[44:47], v[170:173], v[186:189], 0
	v_mfma_f32_16x16x32_bf16 v[40:43], v[178:181], v[186:189], 0
	v_mfma_f32_16x16x32_bf16 v[28:31], v[170:173], v[194:197], 0
	v_mfma_f32_16x16x32_bf16 v[24:27], v[178:181], v[194:197], 0
	v_mfma_f32_16x16x32_bf16 v[12:15], v[170:173], v[202:205], 0
	v_mfma_f32_16x16x32_bf16 v[8:11], v[178:181], v[202:205], 0
	v_mfma_f32_16x16x32_bf16 v[4:7], v[170:173], v[210:213], 0
	v_mfma_f32_16x16x32_bf16 v[0:3], v[178:181], v[210:213], 0
	v_mfma_f32_16x16x32_bf16 v[44:47], v[174:177], v[190:193], v[44:47]
	v_mfma_f32_16x16x32_bf16 v[40:43], v[182:185], v[190:193], v[40:43]
	v_mfma_f32_16x16x32_bf16 v[28:31], v[174:177], v[198:201], v[28:31]
	v_mfma_f32_16x16x32_bf16 v[24:27], v[182:185], v[198:201], v[24:27]
	v_mfma_f32_16x16x32_bf16 v[12:15], v[174:177], v[206:209], v[12:15]
	v_mfma_f32_16x16x32_bf16 v[8:11], v[182:185], v[206:209], v[8:11]
	v_mfma_f32_16x16x32_bf16 v[4:7], v[174:177], v[222:225], v[4:7]
	v_mfma_f32_16x16x32_bf16 v[0:3], v[182:185], v[222:225], v[0:3]
	s_setprio 0
	s_barrier
	s_add_i32 s89, 0, 0x18000
	v_add_u32_e32 v143, s89, v141
	s_add_i32 s90, 0, 0x1c000
	ds_read_b128 v[144:147], v143
	ds_read_b128 v[148:151], v143 offset:1024
	ds_read_b128 v[152:155], v143 offset:2048
	ds_read_b128 v[156:159], v143 offset:3072
	v_add_u32_e32 v143, s90, v141
	ds_read_b128 v[170:173], v143
	ds_read_b128 v[174:177], v143 offset:1024
	ds_read_b128 v[178:181], v143 offset:2048
	ds_read_b128 v[182:185], v143 offset:3072
	s_add_u32 s42, s42, 0x40000
	s_addc_u32 s43, s43, 0
	s_mov_b32 m0, s51
	v_lshl_add_u64 v[234:235], s[42:43], 0, v[128:129]
	ds_read_b128 v[186:189], v142 offset:32768
	ds_read_b128 v[190:193], v142 offset:33792
	ds_read_b128 v[194:197], v142 offset:34816
	ds_read_b128 v[198:201], v142 offset:35840
	ds_read_b128 v[202:205], v142 offset:36864
	ds_read_b128 v[206:209], v142 offset:37888
	ds_read_b128 v[210:213], v142 offset:38912
	ds_read_b128 v[222:225], v142 offset:39936
	global_load_lds_dwordx4 v[234:235], off
	v_lshl_add_u64 v[234:235], s[42:43], 0, v[132:133]
	s_mov_b32 m0, s80
	s_nop 0
	global_load_lds_dwordx4 v[234:235], off
	s_waitcnt vmcnt(8)
	s_waitcnt lgkmcnt(0)
	s_barrier
	s_setprio 1
	s_waitcnt lgkmcnt(0)
	v_mfma_f32_16x16x32_bf16 v[124:127], v[144:147], v[186:189], v[124:127]
	v_mfma_f32_16x16x32_bf16 v[120:123], v[152:155], v[186:189], v[120:123]
	v_mfma_f32_16x16x32_bf16 v[116:119], v[144:147], v[194:197], v[116:119]
	v_mfma_f32_16x16x32_bf16 v[112:115], v[152:155], v[194:197], v[112:115]
	v_mfma_f32_16x16x32_bf16 v[100:103], v[144:147], v[202:205], v[100:103]
	v_mfma_f32_16x16x32_bf16 v[96:99], v[152:155], v[202:205], v[96:99]
	v_mfma_f32_16x16x32_bf16 v[84:87], v[144:147], v[210:213], v[84:87]
	v_mfma_f32_16x16x32_bf16 v[80:83], v[152:155], v[210:213], v[80:83]
	v_mfma_f32_16x16x32_bf16 v[124:127], v[148:151], v[190:193], v[124:127]
	v_mfma_f32_16x16x32_bf16 v[120:123], v[156:159], v[190:193], v[120:123]
	v_mfma_f32_16x16x32_bf16 v[116:119], v[148:151], v[198:201], v[116:119]
	v_mfma_f32_16x16x32_bf16 v[112:115], v[156:159], v[198:201], v[112:115]
	v_mfma_f32_16x16x32_bf16 v[100:103], v[148:151], v[206:209], v[100:103]
	v_mfma_f32_16x16x32_bf16 v[96:99], v[156:159], v[206:209], v[96:99]
	v_mfma_f32_16x16x32_bf16 v[84:87], v[148:151], v[222:225], v[84:87]
	v_mfma_f32_16x16x32_bf16 v[80:83], v[156:159], v[222:225], v[80:83]
	v_mfma_f32_16x16x32_bf16 v[108:111], v[170:173], v[186:189], v[108:111]
	v_mfma_f32_16x16x32_bf16 v[104:107], v[178:181], v[186:189], v[104:107]
	v_mfma_f32_16x16x32_bf16 v[92:95], v[170:173], v[194:197], v[92:95]
	v_mfma_f32_16x16x32_bf16 v[88:91], v[178:181], v[194:197], v[88:91]
	v_mfma_f32_16x16x32_bf16 v[76:79], v[170:173], v[202:205], v[76:79]
	v_mfma_f32_16x16x32_bf16 v[72:75], v[178:181], v[202:205], v[72:75]
	v_mfma_f32_16x16x32_bf16 v[68:71], v[170:173], v[210:213], v[68:71]
	v_mfma_f32_16x16x32_bf16 v[64:67], v[178:181], v[210:213], v[64:67]
	v_mfma_f32_16x16x32_bf16 v[108:111], v[174:177], v[190:193], v[108:111]
	v_mfma_f32_16x16x32_bf16 v[104:107], v[182:185], v[190:193], v[104:107]
	v_mfma_f32_16x16x32_bf16 v[92:95], v[174:177], v[198:201], v[92:95]
	v_mfma_f32_16x16x32_bf16 v[88:91], v[182:185], v[198:201], v[88:91]
	v_mfma_f32_16x16x32_bf16 v[76:79], v[174:177], v[206:209], v[76:79]
	v_mfma_f32_16x16x32_bf16 v[72:75], v[182:185], v[206:209], v[72:75]
	v_mfma_f32_16x16x32_bf16 v[68:71], v[174:177], v[222:225], v[68:71]
	v_mfma_f32_16x16x32_bf16 v[64:67], v[182:185], v[222:225], v[64:67]
	s_setprio 0
	s_barrier
	s_add_i32 s42, s89, s26
	v_lshl_add_u64 v[162:163], v[162:163], 0, s[48:49]
	s_mov_b32 m0, s42
	ds_read_b128 v[186:189], v142 offset:49152
	ds_read_b128 v[190:193], v142 offset:50176
	ds_read_b128 v[194:197], v142 offset:51200
	ds_read_b128 v[198:201], v142 offset:52224
	ds_read_b128 v[202:205], v142 offset:53248
	ds_read_b128 v[206:209], v142 offset:54272
	ds_read_b128 v[210:213], v142 offset:55296
	ds_read_b128 v[222:225], v142 offset:56320
	global_load_lds_dwordx4 v[162:163], off
	s_add_i32 m0, s42, 0x2000
	s_add_u32 s40, s40, 0x40080
	v_lshl_add_u64 v[162:163], v[164:165], 0, s[48:49]
	s_addc_u32 s41, s41, 0
	s_add_i32 s42, s90, s26
	global_load_lds_dwordx4 v[162:163], off
	v_lshl_add_u64 v[162:163], s[40:41], 0, v[130:131]
	s_mov_b32 m0, s42
	s_nop 0
	global_load_lds_dwordx4 v[162:163], off
	v_lshl_add_u64 v[162:163], s[40:41], 0, v[134:135]
	s_add_i32 m0, s42, 0x2000
	s_nop 0
	global_load_lds_dwordx4 v[162:163], off
	v_lshl_add_u64 v[162:163], v[214:215], 0, s[48:49]
	s_mov_b32 m0, s81
	s_nop 0
	global_load_lds_dwordx4 v[162:163], off
	v_lshl_add_u64 v[162:163], v[226:227], 0, s[48:49]
	s_mov_b32 m0, s82
	s_nop 0
	global_load_lds_dwordx4 v[162:163], off
	s_waitcnt vmcnt(8)
	s_waitcnt lgkmcnt(0)
	s_barrier
	s_setprio 1
	s_waitcnt lgkmcnt(0)
	v_mfma_f32_16x16x32_bf16 v[60:63], v[144:147], v[186:189], v[60:63]
	v_mfma_f32_16x16x32_bf16 v[56:59], v[152:155], v[186:189], v[56:59]
	v_mfma_f32_16x16x32_bf16 v[52:55], v[144:147], v[194:197], v[52:55]
	v_mfma_f32_16x16x32_bf16 v[48:51], v[152:155], v[194:197], v[48:51]
	v_mfma_f32_16x16x32_bf16 v[36:39], v[144:147], v[202:205], v[36:39]
	v_mfma_f32_16x16x32_bf16 v[32:35], v[152:155], v[202:205], v[32:35]
	v_mfma_f32_16x16x32_bf16 v[20:23], v[144:147], v[210:213], v[20:23]
	v_mfma_f32_16x16x32_bf16 v[16:19], v[152:155], v[210:213], v[16:19]
	v_mfma_f32_16x16x32_bf16 v[60:63], v[148:151], v[190:193], v[60:63]
	v_mfma_f32_16x16x32_bf16 v[56:59], v[156:159], v[190:193], v[56:59]
	v_mfma_f32_16x16x32_bf16 v[52:55], v[148:151], v[198:201], v[52:55]
	v_mfma_f32_16x16x32_bf16 v[48:51], v[156:159], v[198:201], v[48:51]
	v_mfma_f32_16x16x32_bf16 v[36:39], v[148:151], v[206:209], v[36:39]
	v_mfma_f32_16x16x32_bf16 v[32:35], v[156:159], v[206:209], v[32:35]
	v_mfma_f32_16x16x32_bf16 v[20:23], v[148:151], v[222:225], v[20:23]
	v_mfma_f32_16x16x32_bf16 v[16:19], v[156:159], v[222:225], v[16:19]
	v_mfma_f32_16x16x32_bf16 v[44:47], v[170:173], v[186:189], v[44:47]
	v_mfma_f32_16x16x32_bf16 v[40:43], v[178:181], v[186:189], v[40:43]
	v_mfma_f32_16x16x32_bf16 v[28:31], v[170:173], v[194:197], v[28:31]
	v_mfma_f32_16x16x32_bf16 v[24:27], v[178:181], v[194:197], v[24:27]
	v_mfma_f32_16x16x32_bf16 v[12:15], v[170:173], v[202:205], v[12:15]
	v_mfma_f32_16x16x32_bf16 v[8:11], v[178:181], v[202:205], v[8:11]
	v_mfma_f32_16x16x32_bf16 v[4:7], v[170:173], v[210:213], v[4:7]
	v_mfma_f32_16x16x32_bf16 v[0:3], v[178:181], v[210:213], v[0:3]
	v_mfma_f32_16x16x32_bf16 v[44:47], v[174:177], v[190:193], v[44:47]
	v_mfma_f32_16x16x32_bf16 v[40:43], v[182:185], v[190:193], v[40:43]
	v_mfma_f32_16x16x32_bf16 v[28:31], v[174:177], v[198:201], v[28:31]
	v_mfma_f32_16x16x32_bf16 v[24:27], v[182:185], v[198:201], v[24:27]
	v_mfma_f32_16x16x32_bf16 v[12:15], v[174:177], v[206:209], v[12:15]
	v_mfma_f32_16x16x32_bf16 v[8:11], v[182:185], v[206:209], v[8:11]
	v_mfma_f32_16x16x32_bf16 v[4:7], v[174:177], v[222:225], v[4:7]
	v_mfma_f32_16x16x32_bf16 v[0:3], v[182:185], v[222:225], v[0:3]
	s_add_i32 s88, s88, 2
	s_add_u32 s38, s38, 0x100
	s_addc_u32 s39, s39, 0
	s_add_u32 s86, s86, 0x100
	s_addc_u32 s87, s87, 0
	s_cmp_gt_u32 s88, 13
	s_setprio 0
	s_barrier
.LBB0_655:
	s_add_u32 s40, s38, 0xfffc0080
	s_addc_u32 s41, s39, -1
	s_add_i32 s89, 0, 0x10000
	s_cmp_eq_u32 s88, 12
	s_cselect_b32 s43, s17, s41
	s_cselect_b32 s42, s84, s40
	v_add_u32_e32 v143, s89, v141
	s_cselect_b32 s41, s15, s87
	s_cselect_b32 s40, s85, s86
	s_add_i32 s92, 0, 0x14000
	ds_read_b128 v[144:147], v143
	ds_read_b128 v[148:151], v143 offset:1024
	ds_read_b128 v[152:155], v143 offset:2048
	ds_read_b128 v[156:159], v143 offset:3072
	v_add_u32_e32 v143, s92, v141
	ds_read_b128 v[170:173], v143
	ds_read_b128 v[174:177], v143 offset:1024
	ds_read_b128 v[178:181], v143 offset:2048
	ds_read_b128 v[182:185], v143 offset:3072
	v_lshl_add_u64 v[162:163], s[38:39], 0, v[136:137]
	s_add_i32 m0, s27, 0xc000
	ds_read_b128 v[186:189], v142
	ds_read_b128 v[190:193], v142 offset:1024
	ds_read_b128 v[194:197], v142 offset:2048
	ds_read_b128 v[198:201], v142 offset:3072
	ds_read_b128 v[202:205], v142 offset:4096
	ds_read_b128 v[206:209], v142 offset:5120
	ds_read_b128 v[210:213], v142 offset:6144
	ds_read_b128 v[222:225], v142 offset:7168
	global_load_lds_dwordx4 v[162:163], off
	v_lshl_add_u64 v[162:163], s[38:39], 0, v[138:139]
	s_add_i32 m0, s27, 0xe000
	s_nop 0
	global_load_lds_dwordx4 v[162:163], off
	s_waitcnt vmcnt(8)
	s_waitcnt lgkmcnt(0)
	s_barrier
	s_setprio 1
	s_waitcnt lgkmcnt(0)
	v_mfma_f32_16x16x32_bf16 v[124:127], v[144:147], v[186:189], v[124:127]
	v_mfma_f32_16x16x32_bf16 v[120:123], v[152:155], v[186:189], v[120:123]
	v_mfma_f32_16x16x32_bf16 v[116:119], v[144:147], v[194:197], v[116:119]
	v_mfma_f32_16x16x32_bf16 v[112:115], v[152:155], v[194:197], v[112:115]
	v_mfma_f32_16x16x32_bf16 v[100:103], v[144:147], v[202:205], v[100:103]
	v_mfma_f32_16x16x32_bf16 v[96:99], v[152:155], v[202:205], v[96:99]
	v_mfma_f32_16x16x32_bf16 v[84:87], v[144:147], v[210:213], v[84:87]
	v_mfma_f32_16x16x32_bf16 v[80:83], v[152:155], v[210:213], v[80:83]
	v_mfma_f32_16x16x32_bf16 v[124:127], v[148:151], v[190:193], v[124:127]
	v_mfma_f32_16x16x32_bf16 v[120:123], v[156:159], v[190:193], v[120:123]
	v_mfma_f32_16x16x32_bf16 v[116:119], v[148:151], v[198:201], v[116:119]
	v_mfma_f32_16x16x32_bf16 v[112:115], v[156:159], v[198:201], v[112:115]
	v_mfma_f32_16x16x32_bf16 v[100:103], v[148:151], v[206:209], v[100:103]
	v_mfma_f32_16x16x32_bf16 v[96:99], v[156:159], v[206:209], v[96:99]
	v_mfma_f32_16x16x32_bf16 v[84:87], v[148:151], v[222:225], v[84:87]
	v_mfma_f32_16x16x32_bf16 v[80:83], v[156:159], v[222:225], v[80:83]
	v_mfma_f32_16x16x32_bf16 v[108:111], v[170:173], v[186:189], v[108:111]
	v_mfma_f32_16x16x32_bf16 v[104:107], v[178:181], v[186:189], v[104:107]
	v_mfma_f32_16x16x32_bf16 v[92:95], v[170:173], v[194:197], v[92:95]
	v_mfma_f32_16x16x32_bf16 v[88:91], v[178:181], v[194:197], v[88:91]
	v_mfma_f32_16x16x32_bf16 v[76:79], v[170:173], v[202:205], v[76:79]
	v_mfma_f32_16x16x32_bf16 v[72:75], v[178:181], v[202:205], v[72:75]
	v_mfma_f32_16x16x32_bf16 v[68:71], v[170:173], v[210:213], v[68:71]
	v_mfma_f32_16x16x32_bf16 v[64:67], v[178:181], v[210:213], v[64:67]
	v_mfma_f32_16x16x32_bf16 v[108:111], v[174:177], v[190:193], v[108:111]
	v_mfma_f32_16x16x32_bf16 v[104:107], v[182:185], v[190:193], v[104:107]
	v_mfma_f32_16x16x32_bf16 v[92:95], v[174:177], v[198:201], v[92:95]
	v_mfma_f32_16x16x32_bf16 v[88:91], v[182:185], v[198:201], v[88:91]
	v_mfma_f32_16x16x32_bf16 v[76:79], v[174:177], v[206:209], v[76:79]
	v_mfma_f32_16x16x32_bf16 v[72:75], v[182:185], v[206:209], v[72:75]
	v_mfma_f32_16x16x32_bf16 v[68:71], v[174:177], v[222:225], v[68:71]
	v_mfma_f32_16x16x32_bf16 v[64:67], v[182:185], v[222:225], v[64:67]
	s_setprio 0
	s_barrier
	s_add_i32 s89, s89, s26
	v_lshl_add_u64 v[162:163], s[40:41], 0, v[130:131]
	s_mov_b32 m0, s89
	ds_read_b128 v[186:189], v142 offset:16384
	ds_read_b128 v[190:193], v142 offset:17408
	ds_read_b128 v[194:197], v142 offset:18432
	ds_read_b128 v[198:201], v142 offset:19456
	ds_read_b128 v[202:205], v142 offset:20480
	ds_read_b128 v[206:209], v142 offset:21504
	ds_read_b128 v[210:213], v142 offset:22528
	ds_read_b128 v[222:225], v142 offset:23552
	global_load_lds_dwordx4 v[162:163], off
	s_add_i32 m0, s89, 0x2000
	s_add_u32 s90, s40, 0x40000
	v_lshl_add_u64 v[164:165], s[40:41], 0, v[134:135]
	s_addc_u32 s91, s41, 0
	s_add_i32 s89, s92, s26
	global_load_lds_dwordx4 v[164:165], off
	v_lshl_add_u64 v[214:215], s[90:91], 0, v[130:131]
	s_mov_b32 m0, s89
	v_lshl_add_u64 v[226:227], s[42:43], 0, v[132:133]
	global_load_lds_dwordx4 v[214:215], off
	v_lshl_add_u64 v[214:215], s[90:91], 0, v[134:135]
	s_add_i32 m0, s89, 0x2000
	s_nop 0
	global_load_lds_dwordx4 v[214:215], off
	v_lshl_add_u64 v[214:215], s[42:43], 0, v[128:129]
	s_mov_b32 m0, s27
	s_nop 0
	global_load_lds_dwordx4 v[214:215], off
	s_mov_b32 m0, s50
	s_nop 0
	global_load_lds_dwordx4 v[226:227], off
	s_waitcnt vmcnt(8)
	s_waitcnt lgkmcnt(0)
	s_barrier
	s_setprio 1
	s_waitcnt lgkmcnt(0)
	v_mfma_f32_16x16x32_bf16 v[60:63], v[144:147], v[186:189], v[60:63]
	v_mfma_f32_16x16x32_bf16 v[56:59], v[152:155], v[186:189], v[56:59]
	v_mfma_f32_16x16x32_bf16 v[52:55], v[144:147], v[194:197], v[52:55]
	v_mfma_f32_16x16x32_bf16 v[48:51], v[152:155], v[194:197], v[48:51]
	v_mfma_f32_16x16x32_bf16 v[36:39], v[144:147], v[202:205], v[36:39]
	v_mfma_f32_16x16x32_bf16 v[32:35], v[152:155], v[202:205], v[32:35]
	v_mfma_f32_16x16x32_bf16 v[20:23], v[144:147], v[210:213], v[20:23]
	v_mfma_f32_16x16x32_bf16 v[16:19], v[152:155], v[210:213], v[16:19]
	v_mfma_f32_16x16x32_bf16 v[60:63], v[148:151], v[190:193], v[60:63]
	v_mfma_f32_16x16x32_bf16 v[56:59], v[156:159], v[190:193], v[56:59]
	v_mfma_f32_16x16x32_bf16 v[52:55], v[148:151], v[198:201], v[52:55]
	v_mfma_f32_16x16x32_bf16 v[48:51], v[156:159], v[198:201], v[48:51]
	v_mfma_f32_16x16x32_bf16 v[36:39], v[148:151], v[206:209], v[36:39]
	v_mfma_f32_16x16x32_bf16 v[32:35], v[156:159], v[206:209], v[32:35]
	v_mfma_f32_16x16x32_bf16 v[20:23], v[148:151], v[222:225], v[20:23]
	v_mfma_f32_16x16x32_bf16 v[16:19], v[156:159], v[222:225], v[16:19]
	v_mfma_f32_16x16x32_bf16 v[44:47], v[170:173], v[186:189], v[44:47]
	v_mfma_f32_16x16x32_bf16 v[40:43], v[178:181], v[186:189], v[40:43]
	v_mfma_f32_16x16x32_bf16 v[28:31], v[170:173], v[194:197], v[28:31]
	v_mfma_f32_16x16x32_bf16 v[24:27], v[178:181], v[194:197], v[24:27]
	v_mfma_f32_16x16x32_bf16 v[12:15], v[170:173], v[202:205], v[12:15]
	v_mfma_f32_16x16x32_bf16 v[8:11], v[178:181], v[202:205], v[8:11]
	v_mfma_f32_16x16x32_bf16 v[4:7], v[170:173], v[210:213], v[4:7]
	v_mfma_f32_16x16x32_bf16 v[0:3], v[178:181], v[210:213], v[0:3]
	v_mfma_f32_16x16x32_bf16 v[44:47], v[174:177], v[190:193], v[44:47]
	v_mfma_f32_16x16x32_bf16 v[40:43], v[182:185], v[190:193], v[40:43]
	v_mfma_f32_16x16x32_bf16 v[28:31], v[174:177], v[198:201], v[28:31]
	v_mfma_f32_16x16x32_bf16 v[24:27], v[182:185], v[198:201], v[24:27]
	v_mfma_f32_16x16x32_bf16 v[12:15], v[174:177], v[206:209], v[12:15]
	v_mfma_f32_16x16x32_bf16 v[8:11], v[182:185], v[206:209], v[8:11]
	v_mfma_f32_16x16x32_bf16 v[4:7], v[174:177], v[222:225], v[4:7]
	v_mfma_f32_16x16x32_bf16 v[0:3], v[182:185], v[222:225], v[0:3]
	s_setprio 0
	s_barrier
	s_add_i32 s89, 0, 0x18000
	v_add_u32_e32 v143, s89, v141
	s_add_i32 s90, 0, 0x1c000
	ds_read_b128 v[144:147], v143
	ds_read_b128 v[148:151], v143 offset:1024
	ds_read_b128 v[152:155], v143 offset:2048
	ds_read_b128 v[156:159], v143 offset:3072
	v_add_u32_e32 v143, s90, v141
	ds_read_b128 v[170:173], v143
	ds_read_b128 v[174:177], v143 offset:1024
	ds_read_b128 v[178:181], v143 offset:2048
	ds_read_b128 v[182:185], v143 offset:3072
	s_add_u32 s42, s42, 0x40000
	s_addc_u32 s43, s43, 0
	s_mov_b32 m0, s51
	v_lshl_add_u64 v[234:235], s[42:43], 0, v[128:129]
	ds_read_b128 v[186:189], v142 offset:32768
	ds_read_b128 v[190:193], v142 offset:33792
	ds_read_b128 v[194:197], v142 offset:34816
	ds_read_b128 v[198:201], v142 offset:35840
	ds_read_b128 v[202:205], v142 offset:36864
	ds_read_b128 v[206:209], v142 offset:37888
	ds_read_b128 v[210:213], v142 offset:38912
	ds_read_b128 v[222:225], v142 offset:39936
	global_load_lds_dwordx4 v[234:235], off
	v_lshl_add_u64 v[234:235], s[42:43], 0, v[132:133]
	s_mov_b32 m0, s80
	s_nop 0
	global_load_lds_dwordx4 v[234:235], off
	s_waitcnt vmcnt(8)
	s_waitcnt lgkmcnt(0)
	s_barrier
	s_setprio 1
	s_waitcnt lgkmcnt(0)
	v_mfma_f32_16x16x32_bf16 v[124:127], v[144:147], v[186:189], v[124:127]
	v_mfma_f32_16x16x32_bf16 v[120:123], v[152:155], v[186:189], v[120:123]
	v_mfma_f32_16x16x32_bf16 v[116:119], v[144:147], v[194:197], v[116:119]
	v_mfma_f32_16x16x32_bf16 v[112:115], v[152:155], v[194:197], v[112:115]
	v_mfma_f32_16x16x32_bf16 v[100:103], v[144:147], v[202:205], v[100:103]
	v_mfma_f32_16x16x32_bf16 v[96:99], v[152:155], v[202:205], v[96:99]
	v_mfma_f32_16x16x32_bf16 v[84:87], v[144:147], v[210:213], v[84:87]
	v_mfma_f32_16x16x32_bf16 v[80:83], v[152:155], v[210:213], v[80:83]
	v_mfma_f32_16x16x32_bf16 v[124:127], v[148:151], v[190:193], v[124:127]
	v_mfma_f32_16x16x32_bf16 v[120:123], v[156:159], v[190:193], v[120:123]
	v_mfma_f32_16x16x32_bf16 v[116:119], v[148:151], v[198:201], v[116:119]
	v_mfma_f32_16x16x32_bf16 v[112:115], v[156:159], v[198:201], v[112:115]
	v_mfma_f32_16x16x32_bf16 v[100:103], v[148:151], v[206:209], v[100:103]
	v_mfma_f32_16x16x32_bf16 v[96:99], v[156:159], v[206:209], v[96:99]
	v_mfma_f32_16x16x32_bf16 v[84:87], v[148:151], v[222:225], v[84:87]
	v_mfma_f32_16x16x32_bf16 v[80:83], v[156:159], v[222:225], v[80:83]
	v_mfma_f32_16x16x32_bf16 v[108:111], v[170:173], v[186:189], v[108:111]
	v_mfma_f32_16x16x32_bf16 v[104:107], v[178:181], v[186:189], v[104:107]
	v_mfma_f32_16x16x32_bf16 v[92:95], v[170:173], v[194:197], v[92:95]
	v_mfma_f32_16x16x32_bf16 v[88:91], v[178:181], v[194:197], v[88:91]
	v_mfma_f32_16x16x32_bf16 v[76:79], v[170:173], v[202:205], v[76:79]
	v_mfma_f32_16x16x32_bf16 v[72:75], v[178:181], v[202:205], v[72:75]
	v_mfma_f32_16x16x32_bf16 v[68:71], v[170:173], v[210:213], v[68:71]
	v_mfma_f32_16x16x32_bf16 v[64:67], v[178:181], v[210:213], v[64:67]
	v_mfma_f32_16x16x32_bf16 v[108:111], v[174:177], v[190:193], v[108:111]
	v_mfma_f32_16x16x32_bf16 v[104:107], v[182:185], v[190:193], v[104:107]
	v_mfma_f32_16x16x32_bf16 v[92:95], v[174:177], v[198:201], v[92:95]
	v_mfma_f32_16x16x32_bf16 v[88:91], v[182:185], v[198:201], v[88:91]
	v_mfma_f32_16x16x32_bf16 v[76:79], v[174:177], v[206:209], v[76:79]
	v_mfma_f32_16x16x32_bf16 v[72:75], v[182:185], v[206:209], v[72:75]
	v_mfma_f32_16x16x32_bf16 v[68:71], v[174:177], v[222:225], v[68:71]
	v_mfma_f32_16x16x32_bf16 v[64:67], v[182:185], v[222:225], v[64:67]
	s_setprio 0
	s_barrier
	s_add_i32 s42, s89, s26
	v_lshl_add_u64 v[162:163], v[162:163], 0, s[48:49]
	s_mov_b32 m0, s42
	ds_read_b128 v[186:189], v142 offset:49152
	ds_read_b128 v[190:193], v142 offset:50176
	ds_read_b128 v[194:197], v142 offset:51200
	ds_read_b128 v[198:201], v142 offset:52224
	ds_read_b128 v[202:205], v142 offset:53248
	ds_read_b128 v[206:209], v142 offset:54272
	ds_read_b128 v[210:213], v142 offset:55296
	ds_read_b128 v[222:225], v142 offset:56320
	global_load_lds_dwordx4 v[162:163], off
	s_add_i32 m0, s42, 0x2000
	s_add_u32 s40, s40, 0x40080
	v_lshl_add_u64 v[162:163], v[164:165], 0, s[48:49]
	s_addc_u32 s41, s41, 0
	s_add_i32 s42, s90, s26
	global_load_lds_dwordx4 v[162:163], off
	v_lshl_add_u64 v[162:163], s[40:41], 0, v[130:131]
	s_mov_b32 m0, s42
	s_nop 0
	global_load_lds_dwordx4 v[162:163], off
	v_lshl_add_u64 v[162:163], s[40:41], 0, v[134:135]
	s_add_i32 m0, s42, 0x2000
	s_nop 0
	global_load_lds_dwordx4 v[162:163], off
	v_lshl_add_u64 v[162:163], v[214:215], 0, s[48:49]
	s_mov_b32 m0, s81
	s_nop 0
	global_load_lds_dwordx4 v[162:163], off
	v_lshl_add_u64 v[162:163], v[226:227], 0, s[48:49]
	s_mov_b32 m0, s82
	s_nop 0
	global_load_lds_dwordx4 v[162:163], off
	s_waitcnt vmcnt(8)
	s_waitcnt lgkmcnt(0)
	s_barrier
	s_setprio 1
	s_waitcnt lgkmcnt(0)
	v_mfma_f32_16x16x32_bf16 v[60:63], v[144:147], v[186:189], v[60:63]
	v_mfma_f32_16x16x32_bf16 v[56:59], v[152:155], v[186:189], v[56:59]
	v_mfma_f32_16x16x32_bf16 v[52:55], v[144:147], v[194:197], v[52:55]
	v_mfma_f32_16x16x32_bf16 v[48:51], v[152:155], v[194:197], v[48:51]
	v_mfma_f32_16x16x32_bf16 v[36:39], v[144:147], v[202:205], v[36:39]
	v_mfma_f32_16x16x32_bf16 v[32:35], v[152:155], v[202:205], v[32:35]
	v_mfma_f32_16x16x32_bf16 v[20:23], v[144:147], v[210:213], v[20:23]
	v_mfma_f32_16x16x32_bf16 v[16:19], v[152:155], v[210:213], v[16:19]
	v_mfma_f32_16x16x32_bf16 v[60:63], v[148:151], v[190:193], v[60:63]
	v_mfma_f32_16x16x32_bf16 v[56:59], v[156:159], v[190:193], v[56:59]
	v_mfma_f32_16x16x32_bf16 v[52:55], v[148:151], v[198:201], v[52:55]
	v_mfma_f32_16x16x32_bf16 v[48:51], v[156:159], v[198:201], v[48:51]
	v_mfma_f32_16x16x32_bf16 v[36:39], v[148:151], v[206:209], v[36:39]
	v_mfma_f32_16x16x32_bf16 v[32:35], v[156:159], v[206:209], v[32:35]
	v_mfma_f32_16x16x32_bf16 v[20:23], v[148:151], v[222:225], v[20:23]
	v_mfma_f32_16x16x32_bf16 v[16:19], v[156:159], v[222:225], v[16:19]
	v_mfma_f32_16x16x32_bf16 v[44:47], v[170:173], v[186:189], v[44:47]
	v_mfma_f32_16x16x32_bf16 v[40:43], v[178:181], v[186:189], v[40:43]
	v_mfma_f32_16x16x32_bf16 v[28:31], v[170:173], v[194:197], v[28:31]
	v_mfma_f32_16x16x32_bf16 v[24:27], v[178:181], v[194:197], v[24:27]
	v_mfma_f32_16x16x32_bf16 v[12:15], v[170:173], v[202:205], v[12:15]
	v_mfma_f32_16x16x32_bf16 v[8:11], v[178:181], v[202:205], v[8:11]
	v_mfma_f32_16x16x32_bf16 v[4:7], v[170:173], v[210:213], v[4:7]
	v_mfma_f32_16x16x32_bf16 v[0:3], v[178:181], v[210:213], v[0:3]
	v_mfma_f32_16x16x32_bf16 v[44:47], v[174:177], v[190:193], v[44:47]
	v_mfma_f32_16x16x32_bf16 v[40:43], v[182:185], v[190:193], v[40:43]
	v_mfma_f32_16x16x32_bf16 v[28:31], v[174:177], v[198:201], v[28:31]
	v_mfma_f32_16x16x32_bf16 v[24:27], v[182:185], v[198:201], v[24:27]
	v_mfma_f32_16x16x32_bf16 v[12:15], v[174:177], v[206:209], v[12:15]
	v_mfma_f32_16x16x32_bf16 v[8:11], v[182:185], v[206:209], v[8:11]
	v_mfma_f32_16x16x32_bf16 v[4:7], v[174:177], v[222:225], v[4:7]
	v_mfma_f32_16x16x32_bf16 v[0:3], v[182:185], v[222:225], v[0:3]
	s_add_i32 s88, s88, 2
	s_add_u32 s38, s38, 0x100
	s_addc_u32 s39, s39, 0
	s_add_u32 s86, s86, 0x100
	s_addc_u32 s87, s87, 0
	s_cmp_gt_u32 s88, 13
	s_setprio 0
	s_barrier
	s_cbranch_scc0 .LBB0_655
	v_readlane_b32 s88, v254, 60
	v_readlane_b32 s86, v255, 21
	v_readlane_b32 s84, v255, 23
	s_and_b64 vcc, exec, s[8:9]
	v_readlane_b32 s89, v254, 61
	v_readlane_b32 s87, v255, 22
	v_readlane_b32 s85, v255, 24
	s_cbranch_vccz .LBB0_658
	s_barrier
